# K-loop heads aligned to 64 B (v4 + alignment)
# speedup vs baseline: 1.0036x; 1.0036x over previous
.LBB0_353:
	s_lshl_b64 s[2:3], s[14:15], 1
	v_readlane_b32 s20, v253, 52
	v_readlane_b32 s21, v253, 53
	s_add_u32 s20, s20, s2
	s_addc_u32 s21, s21, s3
	s_and_b64 s[2:3], s[18:19], exec
	s_cselect_b32 s11, s21, s27
	s_cselect_b32 s13, s20, s26
	s_lshl_b64 s[2:3], s[16:17], 1
	s_add_u32 s22, s48, s2
	s_addc_u32 s23, s49, s3
	s_and_b64 s[2:3], s[18:19], exec
	s_cselect_b32 s44, s23, s29
	s_cselect_b32 s45, s22, s28
	s_add_u32 s26, s26, 0x40080
	s_addc_u32 s27, s27, 0
	s_add_u32 s46, s28, 0x100
	s_addc_u32 s47, s29, 0
	s_mov_b32 s52, -2
	s_branch .Lpk354_peel
	.p2align 6
.Lpk354_peel:
	ds_read_b128 v[166:169], v139
	ds_read_b128 v[170:173], v139 offset:1024
	ds_read_b128 v[178:181], v139 offset:2048
	ds_read_b128 v[182:185], v139 offset:3072
	ds_read_b128 v[186:189], v164
	ds_read_b128 v[190:193], v164 offset:1024
	ds_read_b128 v[194:197], v164 offset:2048
	ds_read_b128 v[198:201], v164 offset:3072
	s_add_u32 s2, s26, 0xfffc0080
	s_addc_u32 s3, s27, -1
	s_cmp_eq_u32 s52, 12
	s_cselect_b32 s3, s11, s3
	s_cselect_b32 s2, s13, s2
	s_cselect_b32 s29, s44, s47
	s_cselect_b32 s28, s45, s46
	v_lshl_add_u64 v[148:149], s[26:27], 0, v[142:143]
	s_add_i32 m0, s34, 0xc000
	ds_read_b128 v[202:205], v165
	ds_read_b128 v[206:209], v165 offset:1024
	ds_read_b128 v[210:213], v165 offset:2048
	ds_read_b128 v[214:217], v165 offset:3072
	ds_read_b128 v[218:221], v165 offset:4096
	ds_read_b128 v[222:225], v165 offset:5120
	ds_read_b128 v[226:229], v165 offset:6144
	ds_read_b128 v[230:233], v165 offset:7168
	global_load_lds_dwordx4 v[148:149], off
	v_lshl_add_u64 v[148:149], s[26:27], 0, v[144:145]
	s_add_i32 m0, s34, 0xe000
	s_nop 0
	global_load_lds_dwordx4 v[148:149], off
	s_waitcnt vmcnt(8)
	s_waitcnt lgkmcnt(0)
	s_barrier
	s_setprio 1
	s_waitcnt lgkmcnt(0)
	v_mfma_f32_16x16x32_bf16 v[126:129], v[166:169], v[202:205], 0
	v_mfma_f32_16x16x32_bf16 v[122:125], v[178:181], v[202:205], 0
	v_mfma_f32_16x16x32_bf16 v[110:113], v[166:169], v[210:213], 0
	v_mfma_f32_16x16x32_bf16 v[106:109], v[178:181], v[210:213], 0
	v_mfma_f32_16x16x32_bf16 v[94:97], v[166:169], v[218:221], 0
	v_mfma_f32_16x16x32_bf16 v[90:93], v[178:181], v[218:221], 0
	v_mfma_f32_16x16x32_bf16 v[78:81], v[166:169], v[226:229], 0
	v_mfma_f32_16x16x32_bf16 v[74:77], v[178:181], v[226:229], 0
	v_mfma_f32_16x16x32_bf16 v[126:129], v[170:173], v[206:209], v[126:129]
	v_mfma_f32_16x16x32_bf16 v[122:125], v[182:185], v[206:209], v[122:125]
	v_mfma_f32_16x16x32_bf16 v[110:113], v[170:173], v[214:217], v[110:113]
	v_mfma_f32_16x16x32_bf16 v[106:109], v[182:185], v[214:217], v[106:109]
	v_mfma_f32_16x16x32_bf16 v[94:97], v[170:173], v[222:225], v[94:97]
	v_mfma_f32_16x16x32_bf16 v[90:93], v[182:185], v[222:225], v[90:93]
	v_mfma_f32_16x16x32_bf16 v[78:81], v[170:173], v[230:233], v[78:81]
	v_mfma_f32_16x16x32_bf16 v[74:77], v[182:185], v[230:233], v[74:77]
	s_setprio 0
	s_setprio 1
	v_mfma_f32_16x16x32_bf16 v[118:121], v[186:189], v[202:205], 0
	v_mfma_f32_16x16x32_bf16 v[114:117], v[194:197], v[202:205], 0
	v_mfma_f32_16x16x32_bf16 v[102:105], v[186:189], v[210:213], 0
	v_mfma_f32_16x16x32_bf16 v[98:101], v[194:197], v[210:213], 0
	v_mfma_f32_16x16x32_bf16 v[86:89], v[186:189], v[218:221], 0
	v_mfma_f32_16x16x32_bf16 v[82:85], v[194:197], v[218:221], 0
	v_mfma_f32_16x16x32_bf16 v[70:73], v[186:189], v[226:229], 0
	v_mfma_f32_16x16x32_bf16 v[66:69], v[194:197], v[226:229], 0
	v_mfma_f32_16x16x32_bf16 v[118:121], v[190:193], v[206:209], v[118:121]
	v_mfma_f32_16x16x32_bf16 v[114:117], v[198:201], v[206:209], v[114:117]
	v_mfma_f32_16x16x32_bf16 v[102:105], v[190:193], v[214:217], v[102:105]
	v_mfma_f32_16x16x32_bf16 v[98:101], v[198:201], v[214:217], v[98:101]
	v_mfma_f32_16x16x32_bf16 v[86:89], v[190:193], v[222:225], v[86:89]
	v_mfma_f32_16x16x32_bf16 v[82:85], v[198:201], v[222:225], v[82:85]
	v_mfma_f32_16x16x32_bf16 v[70:73], v[190:193], v[230:233], v[70:73]
	v_mfma_f32_16x16x32_bf16 v[66:69], v[198:201], v[230:233], v[66:69]
	s_setprio 0
	s_barrier
	s_add_i32 s53, s41, s30
	v_lshl_add_u64 v[148:149], s[28:29], 0, v[132:133]
	s_mov_b32 m0, s53
	ds_read_b128 v[202:205], v165 offset:16384
	ds_read_b128 v[206:209], v165 offset:17408
	ds_read_b128 v[210:213], v165 offset:18432
	ds_read_b128 v[214:217], v165 offset:19456
	ds_read_b128 v[218:221], v165 offset:20480
	ds_read_b128 v[222:225], v165 offset:21504
	ds_read_b128 v[226:229], v165 offset:22528
	ds_read_b128 v[230:233], v165 offset:23552
	global_load_lds_dwordx4 v[148:149], off
	s_add_i32 m0, s53, 0x2000
	s_add_u32 s54, s28, 0x40000
	v_lshl_add_u64 v[174:175], s[28:29], 0, v[136:137]
	s_addc_u32 s55, s29, 0
	s_add_i32 s53, s42, s30
	global_load_lds_dwordx4 v[174:175], off
	v_lshl_add_u64 v[234:235], s[54:55], 0, v[132:133]
	s_mov_b32 m0, s53
	v_lshl_add_u64 v[236:237], s[2:3], 0, v[134:135]
	global_load_lds_dwordx4 v[234:235], off
	v_lshl_add_u64 v[234:235], s[54:55], 0, v[136:137]
	s_add_i32 m0, s53, 0x2000
	s_nop 0
	global_load_lds_dwordx4 v[234:235], off
	v_lshl_add_u64 v[234:235], s[2:3], 0, v[130:131]
	s_mov_b32 m0, s34
	s_nop 0
	global_load_lds_dwordx4 v[234:235], off
	s_mov_b32 m0, s25
	s_nop 0
	global_load_lds_dwordx4 v[236:237], off
	s_waitcnt vmcnt(8)
	s_waitcnt lgkmcnt(0)
	s_barrier
	s_setprio 1
	s_waitcnt lgkmcnt(0)
	v_mfma_f32_16x16x32_bf16 v[62:65], v[166:169], v[202:205], 0
	v_mfma_f32_16x16x32_bf16 v[58:61], v[178:181], v[202:205], 0
	v_mfma_f32_16x16x32_bf16 v[46:49], v[166:169], v[210:213], 0
	v_mfma_f32_16x16x32_bf16 v[42:45], v[178:181], v[210:213], 0
	v_mfma_f32_16x16x32_bf16 v[30:33], v[166:169], v[218:221], 0
	v_mfma_f32_16x16x32_bf16 v[26:29], v[178:181], v[218:221], 0
	v_mfma_f32_16x16x32_bf16 v[14:17], v[166:169], v[226:229], 0
	v_mfma_f32_16x16x32_bf16 v[10:13], v[178:181], v[226:229], 0
	v_mfma_f32_16x16x32_bf16 v[62:65], v[170:173], v[206:209], v[62:65]
	v_mfma_f32_16x16x32_bf16 v[58:61], v[182:185], v[206:209], v[58:61]
	v_mfma_f32_16x16x32_bf16 v[46:49], v[170:173], v[214:217], v[46:49]
	v_mfma_f32_16x16x32_bf16 v[42:45], v[182:185], v[214:217], v[42:45]
	v_mfma_f32_16x16x32_bf16 v[30:33], v[170:173], v[222:225], v[30:33]
	v_mfma_f32_16x16x32_bf16 v[26:29], v[182:185], v[222:225], v[26:29]
	v_mfma_f32_16x16x32_bf16 v[14:17], v[170:173], v[230:233], v[14:17]
	v_mfma_f32_16x16x32_bf16 v[10:13], v[182:185], v[230:233], v[10:13]
	s_setprio 0
	s_setprio 1
	v_mfma_f32_16x16x32_bf16 v[54:57], v[186:189], v[202:205], 0
	v_mfma_f32_16x16x32_bf16 v[50:53], v[194:197], v[202:205], 0
	v_mfma_f32_16x16x32_bf16 v[38:41], v[186:189], v[210:213], 0
	v_mfma_f32_16x16x32_bf16 v[34:37], v[194:197], v[210:213], 0
	v_mfma_f32_16x16x32_bf16 v[22:25], v[186:189], v[218:221], 0
	v_mfma_f32_16x16x32_bf16 v[18:21], v[194:197], v[218:221], 0
	v_mfma_f32_16x16x32_bf16 v[6:9], v[186:189], v[226:229], 0
	v_mfma_f32_16x16x32_bf16 v[2:5], v[194:197], v[226:229], 0
	v_mfma_f32_16x16x32_bf16 v[54:57], v[190:193], v[206:209], v[54:57]
	v_mfma_f32_16x16x32_bf16 v[50:53], v[198:201], v[206:209], v[50:53]
	v_mfma_f32_16x16x32_bf16 v[38:41], v[190:193], v[214:217], v[38:41]
	v_mfma_f32_16x16x32_bf16 v[34:37], v[198:201], v[214:217], v[34:37]
	v_mfma_f32_16x16x32_bf16 v[22:25], v[190:193], v[222:225], v[22:25]
	v_mfma_f32_16x16x32_bf16 v[18:21], v[198:201], v[222:225], v[18:21]
	v_mfma_f32_16x16x32_bf16 v[6:9], v[190:193], v[230:233], v[6:9]
	v_mfma_f32_16x16x32_bf16 v[2:5], v[198:201], v[230:233], v[2:5]
	s_setprio 0
	s_barrier
	s_add_i32 s53, 0, 0x18000
	v_add_u32_e32 v176, s53, v163
	s_add_i32 s54, 0, 0x1c000
	ds_read_b128 v[166:169], v176
	ds_read_b128 v[170:173], v176 offset:1024
	ds_read_b128 v[178:181], v176 offset:2048
	ds_read_b128 v[182:185], v176 offset:3072
	v_add_u32_e32 v176, s54, v163
	ds_read_b128 v[186:189], v176
	ds_read_b128 v[190:193], v176 offset:1024
	ds_read_b128 v[194:197], v176 offset:2048
	ds_read_b128 v[198:201], v176 offset:3072
	s_add_u32 s2, s2, 0x40000
	s_addc_u32 s3, s3, 0
	s_mov_b32 m0, s35
	v_lshl_add_u64 v[238:239], s[2:3], 0, v[130:131]
	ds_read_b128 v[202:205], v165 offset:32768
	ds_read_b128 v[206:209], v165 offset:33792
	ds_read_b128 v[210:213], v165 offset:34816
	ds_read_b128 v[214:217], v165 offset:35840
	ds_read_b128 v[218:221], v165 offset:36864
	ds_read_b128 v[222:225], v165 offset:37888
	ds_read_b128 v[226:229], v165 offset:38912
	ds_read_b128 v[230:233], v165 offset:39936
	global_load_lds_dwordx4 v[238:239], off
	v_lshl_add_u64 v[238:239], s[2:3], 0, v[134:135]
	s_mov_b32 m0, s36
	s_nop 0
	global_load_lds_dwordx4 v[238:239], off
	s_waitcnt vmcnt(8)
	s_waitcnt lgkmcnt(0)
	s_barrier
	s_setprio 1
	s_waitcnt lgkmcnt(0)
	v_mfma_f32_16x16x32_bf16 v[126:129], v[166:169], v[202:205], v[126:129]
	v_mfma_f32_16x16x32_bf16 v[122:125], v[178:181], v[202:205], v[122:125]
	v_mfma_f32_16x16x32_bf16 v[110:113], v[166:169], v[210:213], v[110:113]
	v_mfma_f32_16x16x32_bf16 v[106:109], v[178:181], v[210:213], v[106:109]
	v_mfma_f32_16x16x32_bf16 v[94:97], v[166:169], v[218:221], v[94:97]
	v_mfma_f32_16x16x32_bf16 v[90:93], v[178:181], v[218:221], v[90:93]
	v_mfma_f32_16x16x32_bf16 v[78:81], v[166:169], v[226:229], v[78:81]
	v_mfma_f32_16x16x32_bf16 v[74:77], v[178:181], v[226:229], v[74:77]
	v_mfma_f32_16x16x32_bf16 v[126:129], v[170:173], v[206:209], v[126:129]
	v_mfma_f32_16x16x32_bf16 v[122:125], v[182:185], v[206:209], v[122:125]
	v_mfma_f32_16x16x32_bf16 v[110:113], v[170:173], v[214:217], v[110:113]
	v_mfma_f32_16x16x32_bf16 v[106:109], v[182:185], v[214:217], v[106:109]
	v_mfma_f32_16x16x32_bf16 v[94:97], v[170:173], v[222:225], v[94:97]
	v_mfma_f32_16x16x32_bf16 v[90:93], v[182:185], v[222:225], v[90:93]
	v_mfma_f32_16x16x32_bf16 v[78:81], v[170:173], v[230:233], v[78:81]
	v_mfma_f32_16x16x32_bf16 v[74:77], v[182:185], v[230:233], v[74:77]
	s_setprio 0
	s_setprio 1
	v_mfma_f32_16x16x32_bf16 v[118:121], v[186:189], v[202:205], v[118:121]
	v_mfma_f32_16x16x32_bf16 v[114:117], v[194:197], v[202:205], v[114:117]
	v_mfma_f32_16x16x32_bf16 v[102:105], v[186:189], v[210:213], v[102:105]
	v_mfma_f32_16x16x32_bf16 v[98:101], v[194:197], v[210:213], v[98:101]
	v_mfma_f32_16x16x32_bf16 v[86:89], v[186:189], v[218:221], v[86:89]
	v_mfma_f32_16x16x32_bf16 v[82:85], v[194:197], v[218:221], v[82:85]
	v_mfma_f32_16x16x32_bf16 v[70:73], v[186:189], v[226:229], v[70:73]
	v_mfma_f32_16x16x32_bf16 v[66:69], v[194:197], v[226:229], v[66:69]
	v_mfma_f32_16x16x32_bf16 v[118:121], v[190:193], v[206:209], v[118:121]
	v_mfma_f32_16x16x32_bf16 v[114:117], v[198:201], v[206:209], v[114:117]
	v_mfma_f32_16x16x32_bf16 v[102:105], v[190:193], v[214:217], v[102:105]
	v_mfma_f32_16x16x32_bf16 v[98:101], v[198:201], v[214:217], v[98:101]
	v_mfma_f32_16x16x32_bf16 v[86:89], v[190:193], v[222:225], v[86:89]
	v_mfma_f32_16x16x32_bf16 v[82:85], v[198:201], v[222:225], v[82:85]
	v_mfma_f32_16x16x32_bf16 v[70:73], v[190:193], v[230:233], v[70:73]
	v_mfma_f32_16x16x32_bf16 v[66:69], v[198:201], v[230:233], v[66:69]
	s_setprio 0
	s_barrier
	s_add_i32 s2, s53, s30
	v_lshl_add_u64 v[148:149], v[148:149], 0, s[6:7]
	s_mov_b32 m0, s2
	ds_read_b128 v[202:205], v165 offset:49152
	ds_read_b128 v[206:209], v165 offset:50176
	ds_read_b128 v[210:213], v165 offset:51200
	ds_read_b128 v[214:217], v165 offset:52224
	ds_read_b128 v[218:221], v165 offset:53248
	ds_read_b128 v[222:225], v165 offset:54272
	ds_read_b128 v[226:229], v165 offset:55296
	ds_read_b128 v[230:233], v165 offset:56320
	global_load_lds_dwordx4 v[148:149], off
	s_add_i32 m0, s2, 0x2000
	s_add_u32 s2, s28, 0x40080
	v_lshl_add_u64 v[148:149], v[174:175], 0, s[6:7]
	s_addc_u32 s3, s29, 0
	s_add_i32 s28, s54, s30
	global_load_lds_dwordx4 v[148:149], off
	v_lshl_add_u64 v[148:149], s[2:3], 0, v[132:133]
	s_mov_b32 m0, s28
	s_nop 0
	global_load_lds_dwordx4 v[148:149], off
	v_lshl_add_u64 v[148:149], s[2:3], 0, v[136:137]
	s_add_i32 m0, s28, 0x2000
	s_nop 0
	global_load_lds_dwordx4 v[148:149], off
	v_lshl_add_u64 v[148:149], v[234:235], 0, s[6:7]
	s_mov_b32 m0, s38
	s_nop 0
	global_load_lds_dwordx4 v[148:149], off
	v_lshl_add_u64 v[148:149], v[236:237], 0, s[6:7]
	s_mov_b32 m0, s39
	s_nop 0
	global_load_lds_dwordx4 v[148:149], off
	s_waitcnt vmcnt(8)
	s_waitcnt lgkmcnt(0)
	s_barrier
	s_setprio 1
	s_waitcnt lgkmcnt(0)
	v_mfma_f32_16x16x32_bf16 v[62:65], v[166:169], v[202:205], v[62:65]
	v_mfma_f32_16x16x32_bf16 v[58:61], v[178:181], v[202:205], v[58:61]
	v_mfma_f32_16x16x32_bf16 v[46:49], v[166:169], v[210:213], v[46:49]
	v_mfma_f32_16x16x32_bf16 v[42:45], v[178:181], v[210:213], v[42:45]
	v_mfma_f32_16x16x32_bf16 v[30:33], v[166:169], v[218:221], v[30:33]
	v_mfma_f32_16x16x32_bf16 v[26:29], v[178:181], v[218:221], v[26:29]
	v_mfma_f32_16x16x32_bf16 v[14:17], v[166:169], v[226:229], v[14:17]
	v_mfma_f32_16x16x32_bf16 v[10:13], v[178:181], v[226:229], v[10:13]
	v_mfma_f32_16x16x32_bf16 v[62:65], v[170:173], v[206:209], v[62:65]
	v_mfma_f32_16x16x32_bf16 v[58:61], v[182:185], v[206:209], v[58:61]
	v_mfma_f32_16x16x32_bf16 v[46:49], v[170:173], v[214:217], v[46:49]
	v_mfma_f32_16x16x32_bf16 v[42:45], v[182:185], v[214:217], v[42:45]
	v_mfma_f32_16x16x32_bf16 v[30:33], v[170:173], v[222:225], v[30:33]
	v_mfma_f32_16x16x32_bf16 v[26:29], v[182:185], v[222:225], v[26:29]
	v_mfma_f32_16x16x32_bf16 v[14:17], v[170:173], v[230:233], v[14:17]
	v_mfma_f32_16x16x32_bf16 v[10:13], v[182:185], v[230:233], v[10:13]
	s_setprio 0
	s_setprio 1
	v_mfma_f32_16x16x32_bf16 v[54:57], v[186:189], v[202:205], v[54:57]
	v_mfma_f32_16x16x32_bf16 v[50:53], v[194:197], v[202:205], v[50:53]
	v_mfma_f32_16x16x32_bf16 v[38:41], v[186:189], v[210:213], v[38:41]
	v_mfma_f32_16x16x32_bf16 v[34:37], v[194:197], v[210:213], v[34:37]
	v_mfma_f32_16x16x32_bf16 v[22:25], v[186:189], v[218:221], v[22:25]
	v_mfma_f32_16x16x32_bf16 v[18:21], v[194:197], v[218:221], v[18:21]
	v_mfma_f32_16x16x32_bf16 v[6:9], v[186:189], v[226:229], v[6:9]
	v_mfma_f32_16x16x32_bf16 v[2:5], v[194:197], v[226:229], v[2:5]
	v_mfma_f32_16x16x32_bf16 v[54:57], v[190:193], v[206:209], v[54:57]
	v_mfma_f32_16x16x32_bf16 v[50:53], v[198:201], v[206:209], v[50:53]
	v_mfma_f32_16x16x32_bf16 v[38:41], v[190:193], v[214:217], v[38:41]
	v_mfma_f32_16x16x32_bf16 v[34:37], v[198:201], v[214:217], v[34:37]
	v_mfma_f32_16x16x32_bf16 v[22:25], v[190:193], v[222:225], v[22:25]
	v_mfma_f32_16x16x32_bf16 v[18:21], v[198:201], v[222:225], v[18:21]
	v_mfma_f32_16x16x32_bf16 v[6:9], v[190:193], v[230:233], v[6:9]
	v_mfma_f32_16x16x32_bf16 v[2:5], v[198:201], v[230:233], v[2:5]
	s_setprio 0
	s_barrier
	s_add_i32 s52, s52, 2
	s_add_u32 s26, s26, 0x100
	s_addc_u32 s27, s27, 0
	s_add_u32 s46, s46, 0x100
	s_addc_u32 s47, s47, 0
	s_cmp_gt_u32 s52, 13
	s_cbranch_scc0 .LBB0_354
	s_branch .Lpk354_exit
	s_branch .LBB0_354
	.p2align 6

.LBB0_436:
	s_lshl_b32 s3, s3, 5
	v_lshl_or_b32 v131, s8, 6, v156
	s_lshl_b32 s8, s8, 13
	s_and_b32 s23, s3, 0x60
	v_lshlrev_b32_e32 v3, 2, v156
	s_add_u32 s12, s0, 0x8000
	v_lshl_or_b32 v2, v156, 6, v138
	v_and_b32_e32 v3, 32, v3
	s_addc_u32 s13, s1, 0
	v_bitop3_b32 v4, v2, s8, v3 bitop3:0xde
	s_add_i32 m0, s19, 0x18000
	v_lshl_add_u64 v[2:3], s[12:13], 0, v[142:143]
	s_waitcnt vmcnt(2)
	s_barrier
	global_load_lds_dwordx4 v[2:3], off
	s_add_i32 m0, s19, 0x1a000
	v_lshl_add_u64 v[2:3], s[12:13], 0, v[146:147]
	s_add_u32 s12, s6, 0x8000
	s_addc_u32 s13, s7, 0
	s_add_i32 s24, s19, 0x8000
	global_load_lds_dwordx4 v[2:3], off
	v_lshl_add_u64 v[2:3], s[12:13], 0, v[140:141]
	s_mov_b32 m0, s24
	s_add_i32 s25, s19, 0xa000
	global_load_lds_dwordx4 v[2:3], off
	v_lshl_add_u64 v[2:3], s[12:13], 0, v[144:145]
	s_add_u32 s12, s0, 0xc000
	s_mov_b32 m0, s25
	s_addc_u32 s13, s1, 0
	global_load_lds_dwordx4 v[2:3], off
	s_add_i32 m0, s19, 0x1c000
	v_lshl_add_u64 v[2:3], s[12:13], 0, v[142:143]
	global_load_lds_dwordx4 v[2:3], off
	v_lshl_add_u64 v[2:3], s[12:13], 0, v[146:147]
	s_add_i32 m0, s19, 0x1e000
	s_mul_i32 s3, s86, 0x1800000
	global_load_lds_dwordx4 v[2:3], off
	v_and_b32_e32 v2, 0x1800, v150
	v_lshlrev_b32_e32 v6, 7, v154
	s_add_u32 s8, s3, s10
	s_mul_hi_i32 s3, s86, 0x1800000
	v_or3_b32 v2, v152, v2, v6
	s_addc_u32 s9, s3, s9
	v_add_u32_e32 v2, v2, v153
	v_mov_b32_e32 v3, v143
	v_readlane_b32 s10, v252, 9
	v_lshl_add_u64 v[2:3], s[8:9], 0, v[2:3]
	s_mul_hi_i32 s3, s10, 0x160000
	s_mul_i32 s10, s10, 0x160000
	v_mov_b32_e32 v7, s3
	v_subrev_co_u32_e32 v2, vcc, s10, v2
	v_lshl_or_b32 v5, s23, 7, v157
	s_nop 0
	v_subb_co_u32_e32 v3, vcc, v3, v7, vcc
	v_lshl_add_u64 v[148:149], s[78:79], 0, v[2:3]
	v_and_b32_e32 v2, 0x3800, v155
	v_or3_b32 v2, v152, v2, v6
	v_add_u32_e32 v2, v2, v153
	v_mov_b32_e32 v3, v143
	v_lshl_add_u64 v[2:3], s[8:9], 0, v[2:3]
	s_waitcnt vmcnt(6)
	v_mov_b32_e32 v6, s3
	v_subrev_co_u32_e32 v2, vcc, s10, v2
	s_add_i32 s29, 0, 0x10000
	s_add_i32 s31, 0, 0x14000
	s_add_i32 s35, 0, 0x18000
	s_add_i32 s37, 0, 0x1c000
	v_subb_co_u32_e32 v3, vcc, v3, v6, vcc
	v_add_u32_e32 v133, s29, v5
	v_add_u32_e32 v135, s31, v5
	s_add_i32 s29, s29, s2
	s_add_i32 s31, s31, s2
	v_add_u32_e32 v139, s35, v5
	v_add_u32_e32 v159, s37, v5
	s_add_i32 s35, s35, s2
	s_add_i32 s37, s37, s2
	v_lshl_add_u64 v[150:151], s[78:79], 0, v[2:3]
	s_mov_b32 s26, -2
	s_mov_b64 s[8:9], 0x10000
	v_add_u32_e32 v137, 0, v4
	s_mov_b64 s[10:11], 0x87fc000
	s_add_i32 s27, s19, 0xc000
	s_add_i32 s28, s19, 0xe000
	s_add_i32 s30, s29, 0x2000
	s_add_i32 s34, s31, 0x2000
	s_add_i32 s36, s35, 0x2000
	s_add_i32 s38, s37, 0x2000
	v_mov_b32_e32 v2, v143
	v_mov_b32_e32 v3, v143
	v_mov_b32_e32 v4, v143
	v_mov_b32_e32 v5, v143
	v_mov_b32_e32 v6, v143
	v_mov_b32_e32 v7, v143
	v_mov_b32_e32 v8, v143
	v_mov_b32_e32 v9, v143
	v_mov_b32_e32 v14, v143
	v_mov_b32_e32 v15, v143
	v_mov_b32_e32 v16, v143
	v_mov_b32_e32 v17, v143
	v_mov_b32_e32 v22, v143
	v_mov_b32_e32 v23, v143
	v_mov_b32_e32 v24, v143
	v_mov_b32_e32 v25, v143
	v_mov_b32_e32 v30, v143
	v_mov_b32_e32 v31, v143
	v_mov_b32_e32 v32, v143
	v_mov_b32_e32 v33, v143
	v_mov_b32_e32 v38, v143
	v_mov_b32_e32 v39, v143
	v_mov_b32_e32 v40, v143
	v_mov_b32_e32 v41, v143
	v_mov_b32_e32 v46, v143
	v_mov_b32_e32 v47, v143
	v_mov_b32_e32 v48, v143
	v_mov_b32_e32 v49, v143
	v_mov_b32_e32 v54, v143
	v_mov_b32_e32 v55, v143
	v_mov_b32_e32 v56, v143
	v_mov_b32_e32 v57, v143
	v_mov_b32_e32 v10, v143
	v_mov_b32_e32 v11, v143
	v_mov_b32_e32 v12, v143
	v_mov_b32_e32 v13, v143
	v_mov_b32_e32 v18, v143
	v_mov_b32_e32 v19, v143
	v_mov_b32_e32 v20, v143
	v_mov_b32_e32 v21, v143
	v_mov_b32_e32 v26, v143
	v_mov_b32_e32 v27, v143
	v_mov_b32_e32 v28, v143
	v_mov_b32_e32 v29, v143
	v_mov_b32_e32 v34, v143
	v_mov_b32_e32 v35, v143
	v_mov_b32_e32 v36, v143
	v_mov_b32_e32 v37, v143
	v_mov_b32_e32 v42, v143
	v_mov_b32_e32 v43, v143
	v_mov_b32_e32 v44, v143
	v_mov_b32_e32 v45, v143
	v_mov_b32_e32 v50, v143
	v_mov_b32_e32 v51, v143
	v_mov_b32_e32 v52, v143
	v_mov_b32_e32 v53, v143
	v_mov_b32_e32 v58, v143
	v_mov_b32_e32 v59, v143
	v_mov_b32_e32 v60, v143
	v_mov_b32_e32 v61, v143
	v_mov_b32_e32 v62, v143
	s_waitcnt vmcnt(0)
	v_mov_b32_e32 v63, v143
	v_mov_b32_e32 v64, v143
	v_mov_b32_e32 v65, v143
	v_mov_b32_e32 v66, v143
	v_mov_b32_e32 v67, v143
	v_mov_b32_e32 v68, v143
	v_mov_b32_e32 v69, v143
	v_mov_b32_e32 v70, v143
	v_mov_b32_e32 v71, v143
	v_mov_b32_e32 v72, v143
	v_mov_b32_e32 v73, v143
	v_mov_b32_e32 v78, v143
	v_mov_b32_e32 v79, v143
	v_mov_b32_e32 v80, v143
	v_mov_b32_e32 v81, v143
	v_mov_b32_e32 v86, v143
	v_mov_b32_e32 v87, v143
	v_mov_b32_e32 v88, v143
	v_mov_b32_e32 v89, v143
	v_mov_b32_e32 v94, v143
	v_mov_b32_e32 v95, v143
	v_mov_b32_e32 v96, v143
	v_mov_b32_e32 v97, v143
	v_mov_b32_e32 v102, v143
	v_mov_b32_e32 v103, v143
	v_mov_b32_e32 v104, v143
	v_mov_b32_e32 v105, v143
	v_mov_b32_e32 v110, v143
	v_mov_b32_e32 v111, v143
	v_mov_b32_e32 v112, v143
	v_mov_b32_e32 v113, v143
	v_mov_b32_e32 v118, v143
	v_mov_b32_e32 v119, v143
	v_mov_b32_e32 v120, v143
	v_mov_b32_e32 v121, v143
	v_mov_b32_e32 v74, v143
	v_mov_b32_e32 v75, v143
	v_mov_b32_e32 v76, v143
	v_mov_b32_e32 v77, v143
	v_mov_b32_e32 v82, v143
	v_mov_b32_e32 v83, v143
	v_mov_b32_e32 v84, v143
	v_mov_b32_e32 v85, v143
	v_mov_b32_e32 v90, v143
	v_mov_b32_e32 v91, v143
	v_mov_b32_e32 v92, v143
	v_mov_b32_e32 v93, v143
	v_mov_b32_e32 v98, v143
	v_mov_b32_e32 v99, v143
	v_mov_b32_e32 v100, v143
	v_mov_b32_e32 v101, v143
	v_mov_b32_e32 v106, v143
	v_mov_b32_e32 v107, v143
	v_mov_b32_e32 v108, v143
	v_mov_b32_e32 v109, v143
	v_mov_b32_e32 v114, v143
	v_mov_b32_e32 v115, v143
	v_mov_b32_e32 v116, v143
	v_mov_b32_e32 v117, v143
	v_mov_b32_e32 v122, v143
	v_mov_b32_e32 v123, v143
	v_mov_b32_e32 v124, v143
	v_mov_b32_e32 v125, v143
	v_mov_b32_e32 v126, v143
	v_mov_b32_e32 v127, v143
	v_mov_b32_e32 v128, v143
	v_mov_b32_e32 v129, v143
	s_barrier
	s_branch .LBB0_437
	.p2align 6

.LBB0_450:
	s_lshl_b64 s[2:3], s[14:15], 1
	v_readlane_b32 s20, v253, 52
	v_readlane_b32 s21, v253, 53
	s_add_u32 s20, s20, s2
	s_addc_u32 s21, s21, s3
	s_and_b64 s[2:3], s[18:19], exec
	s_cselect_b32 s11, s21, s29
	s_cselect_b32 s13, s20, s28
	s_lshl_b64 s[2:3], s[16:17], 1
	s_add_u32 s22, s48, s2
	s_addc_u32 s23, s49, s3
	s_and_b64 s[2:3], s[18:19], exec
	s_cselect_b32 s44, s23, s31
	s_cselect_b32 s45, s22, s30
	s_add_u32 s28, s28, 0x40080
	s_addc_u32 s29, s29, 0
	s_add_u32 s46, s30, 0x100
	s_addc_u32 s47, s31, 0
	s_mov_b32 s52, -2
	s_branch .Lpk451_peel
	.p2align 6
.Lpk451_peel:
	ds_read_b128 v[152:155], v149
	ds_read_b128 v[156:159], v149 offset:1024
	ds_read_b128 v[160:163], v149 offset:2048
	ds_read_b128 v[164:167], v149 offset:3072
	ds_read_b128 v[168:171], v150
	ds_read_b128 v[172:175], v150 offset:1024
	ds_read_b128 v[178:181], v150 offset:2048
	ds_read_b128 v[182:185], v150 offset:3072
	s_add_u32 s2, s28, 0xfffc0080
	s_addc_u32 s3, s29, -1
	s_cmp_eq_u32 s52, 12
	s_cselect_b32 s3, s11, s3
	s_cselect_b32 s2, s13, s2
	s_cselect_b32 s31, s44, s47
	s_cselect_b32 s30, s45, s46
	v_lshl_add_u64 v[146:147], s[28:29], 0, v[140:141]
	s_add_i32 m0, s25, 0xc000
	ds_read_b128 v[186:189], v151
	ds_read_b128 v[190:193], v151 offset:1024
	ds_read_b128 v[194:197], v151 offset:2048
	ds_read_b128 v[198:201], v151 offset:3072
	ds_read_b128 v[202:205], v151 offset:4096
	ds_read_b128 v[206:209], v151 offset:5120
	ds_read_b128 v[210:213], v151 offset:6144
	ds_read_b128 v[214:217], v151 offset:7168
	global_load_lds_dwordx4 v[146:147], off
	v_lshl_add_u64 v[146:147], s[28:29], 0, v[142:143]
	s_add_i32 m0, s25, 0xe000
	s_nop 0
	global_load_lds_dwordx4 v[146:147], off
	s_waitcnt vmcnt(8)
	s_waitcnt lgkmcnt(0)
	s_barrier
	s_setprio 1
	s_waitcnt lgkmcnt(0)
	v_mfma_f32_16x16x32_bf16 v[126:129], v[152:155], v[186:189], 0
	v_mfma_f32_16x16x32_bf16 v[122:125], v[160:163], v[186:189], 0
	v_mfma_f32_16x16x32_bf16 v[110:113], v[152:155], v[194:197], 0
	v_mfma_f32_16x16x32_bf16 v[106:109], v[160:163], v[194:197], 0
	v_mfma_f32_16x16x32_bf16 v[94:97], v[152:155], v[202:205], 0
	v_mfma_f32_16x16x32_bf16 v[90:93], v[160:163], v[202:205], 0
	v_mfma_f32_16x16x32_bf16 v[78:81], v[152:155], v[210:213], 0
	v_mfma_f32_16x16x32_bf16 v[74:77], v[160:163], v[210:213], 0
	v_mfma_f32_16x16x32_bf16 v[126:129], v[156:159], v[190:193], v[126:129]
	v_mfma_f32_16x16x32_bf16 v[122:125], v[164:167], v[190:193], v[122:125]
	v_mfma_f32_16x16x32_bf16 v[110:113], v[156:159], v[198:201], v[110:113]
	v_mfma_f32_16x16x32_bf16 v[106:109], v[164:167], v[198:201], v[106:109]
	v_mfma_f32_16x16x32_bf16 v[94:97], v[156:159], v[206:209], v[94:97]
	v_mfma_f32_16x16x32_bf16 v[90:93], v[164:167], v[206:209], v[90:93]
	v_mfma_f32_16x16x32_bf16 v[78:81], v[156:159], v[214:217], v[78:81]
	v_mfma_f32_16x16x32_bf16 v[74:77], v[164:167], v[214:217], v[74:77]
	s_setprio 0
	s_setprio 1
	v_mfma_f32_16x16x32_bf16 v[118:121], v[168:171], v[186:189], 0
	v_mfma_f32_16x16x32_bf16 v[114:117], v[178:181], v[186:189], 0
	v_mfma_f32_16x16x32_bf16 v[102:105], v[168:171], v[194:197], 0
	v_mfma_f32_16x16x32_bf16 v[98:101], v[178:181], v[194:197], 0
	v_mfma_f32_16x16x32_bf16 v[86:89], v[168:171], v[202:205], 0
	v_mfma_f32_16x16x32_bf16 v[82:85], v[178:181], v[202:205], 0
	v_mfma_f32_16x16x32_bf16 v[70:73], v[168:171], v[210:213], 0
	v_mfma_f32_16x16x32_bf16 v[66:69], v[178:181], v[210:213], 0
	v_mfma_f32_16x16x32_bf16 v[118:121], v[172:175], v[190:193], v[118:121]
	v_mfma_f32_16x16x32_bf16 v[114:117], v[182:185], v[190:193], v[114:117]
	v_mfma_f32_16x16x32_bf16 v[102:105], v[172:175], v[198:201], v[102:105]
	v_mfma_f32_16x16x32_bf16 v[98:101], v[182:185], v[198:201], v[98:101]
	v_mfma_f32_16x16x32_bf16 v[86:89], v[172:175], v[206:209], v[86:89]
	v_mfma_f32_16x16x32_bf16 v[82:85], v[182:185], v[206:209], v[82:85]
	v_mfma_f32_16x16x32_bf16 v[70:73], v[172:175], v[214:217], v[70:73]
	v_mfma_f32_16x16x32_bf16 v[66:69], v[182:185], v[214:217], v[66:69]
	s_setprio 0
	s_barrier
	s_add_i32 s53, s42, s34
	v_lshl_add_u64 v[146:147], s[30:31], 0, v[132:133]
	s_mov_b32 m0, s53
	ds_read_b128 v[186:189], v151 offset:16384
	ds_read_b128 v[190:193], v151 offset:17408
	ds_read_b128 v[194:197], v151 offset:18432
	ds_read_b128 v[198:201], v151 offset:19456
	ds_read_b128 v[202:205], v151 offset:20480
	ds_read_b128 v[206:209], v151 offset:21504
	ds_read_b128 v[210:213], v151 offset:22528
	ds_read_b128 v[214:217], v151 offset:23552
	global_load_lds_dwordx4 v[146:147], off
	s_add_i32 m0, s53, 0x2000
	s_add_u32 s54, s30, 0x40000
	v_lshl_add_u64 v[218:219], s[30:31], 0, v[136:137]
	s_addc_u32 s55, s31, 0
	s_add_i32 s53, s43, s34
	global_load_lds_dwordx4 v[218:219], off
	v_lshl_add_u64 v[220:221], s[54:55], 0, v[132:133]
	s_mov_b32 m0, s53
	v_lshl_add_u64 v[222:223], s[2:3], 0, v[134:135]
	global_load_lds_dwordx4 v[220:221], off
	v_lshl_add_u64 v[220:221], s[54:55], 0, v[136:137]
	s_add_i32 m0, s53, 0x2000
	s_nop 0
	global_load_lds_dwordx4 v[220:221], off
	v_lshl_add_u64 v[220:221], s[2:3], 0, v[130:131]
	s_mov_b32 m0, s25
	s_nop 0
	global_load_lds_dwordx4 v[220:221], off
	s_mov_b32 m0, s27
	s_nop 0
	global_load_lds_dwordx4 v[222:223], off
	s_waitcnt vmcnt(8)
	s_waitcnt lgkmcnt(0)
	s_barrier
	s_setprio 1
	s_waitcnt lgkmcnt(0)
	v_mfma_f32_16x16x32_bf16 v[62:65], v[152:155], v[186:189], 0
	v_mfma_f32_16x16x32_bf16 v[58:61], v[160:163], v[186:189], 0
	v_mfma_f32_16x16x32_bf16 v[46:49], v[152:155], v[194:197], 0
	v_mfma_f32_16x16x32_bf16 v[42:45], v[160:163], v[194:197], 0
	v_mfma_f32_16x16x32_bf16 v[30:33], v[152:155], v[202:205], 0
	v_mfma_f32_16x16x32_bf16 v[26:29], v[160:163], v[202:205], 0
	v_mfma_f32_16x16x32_bf16 v[14:17], v[152:155], v[210:213], 0
	v_mfma_f32_16x16x32_bf16 v[10:13], v[160:163], v[210:213], 0
	v_mfma_f32_16x16x32_bf16 v[62:65], v[156:159], v[190:193], v[62:65]
	v_mfma_f32_16x16x32_bf16 v[58:61], v[164:167], v[190:193], v[58:61]
	v_mfma_f32_16x16x32_bf16 v[46:49], v[156:159], v[198:201], v[46:49]
	v_mfma_f32_16x16x32_bf16 v[42:45], v[164:167], v[198:201], v[42:45]
	v_mfma_f32_16x16x32_bf16 v[30:33], v[156:159], v[206:209], v[30:33]
	v_mfma_f32_16x16x32_bf16 v[26:29], v[164:167], v[206:209], v[26:29]
	v_mfma_f32_16x16x32_bf16 v[14:17], v[156:159], v[214:217], v[14:17]
	v_mfma_f32_16x16x32_bf16 v[10:13], v[164:167], v[214:217], v[10:13]
	s_setprio 0
	s_setprio 1
	v_mfma_f32_16x16x32_bf16 v[54:57], v[168:171], v[186:189], 0
	v_mfma_f32_16x16x32_bf16 v[50:53], v[178:181], v[186:189], 0
	v_mfma_f32_16x16x32_bf16 v[38:41], v[168:171], v[194:197], 0
	v_mfma_f32_16x16x32_bf16 v[34:37], v[178:181], v[194:197], 0
	v_mfma_f32_16x16x32_bf16 v[22:25], v[168:171], v[202:205], 0
	v_mfma_f32_16x16x32_bf16 v[18:21], v[178:181], v[202:205], 0
	v_mfma_f32_16x16x32_bf16 v[6:9], v[168:171], v[210:213], 0
	v_mfma_f32_16x16x32_bf16 v[2:5], v[178:181], v[210:213], 0
	v_mfma_f32_16x16x32_bf16 v[54:57], v[172:175], v[190:193], v[54:57]
	v_mfma_f32_16x16x32_bf16 v[50:53], v[182:185], v[190:193], v[50:53]
	v_mfma_f32_16x16x32_bf16 v[38:41], v[172:175], v[198:201], v[38:41]
	v_mfma_f32_16x16x32_bf16 v[34:37], v[182:185], v[198:201], v[34:37]
	v_mfma_f32_16x16x32_bf16 v[22:25], v[172:175], v[206:209], v[22:25]
	v_mfma_f32_16x16x32_bf16 v[18:21], v[182:185], v[206:209], v[18:21]
	v_mfma_f32_16x16x32_bf16 v[6:9], v[172:175], v[214:217], v[6:9]
	v_mfma_f32_16x16x32_bf16 v[2:5], v[182:185], v[214:217], v[2:5]
	s_setprio 0
	s_barrier
	s_add_i32 s53, 0, 0x18000
	s_add_i32 s54, 0, 0x1c000
	v_add_u32_e32 v164, s53, v148
	v_add_u32_e32 v176, s54, v148
	ds_read_b128 v[152:155], v164
	ds_read_b128 v[156:159], v164 offset:1024
	ds_read_b128 v[160:163], v164 offset:2048
	ds_read_b128 v[164:167], v164 offset:3072
	ds_read_b128 v[168:171], v176
	ds_read_b128 v[172:175], v176 offset:1024
	ds_read_b128 v[178:181], v176 offset:2048
	ds_read_b128 v[182:185], v176 offset:3072
	s_add_u32 s2, s2, 0x40000
	s_addc_u32 s3, s3, 0
	s_mov_b32 m0, s36
	v_lshl_add_u64 v[224:225], s[2:3], 0, v[130:131]
	ds_read_b128 v[186:189], v151 offset:32768
	ds_read_b128 v[190:193], v151 offset:33792
	ds_read_b128 v[194:197], v151 offset:34816
	ds_read_b128 v[198:201], v151 offset:35840
	ds_read_b128 v[202:205], v151 offset:36864
	ds_read_b128 v[206:209], v151 offset:37888
	ds_read_b128 v[210:213], v151 offset:38912
	ds_read_b128 v[214:217], v151 offset:39936
	global_load_lds_dwordx4 v[224:225], off
	v_lshl_add_u64 v[224:225], s[2:3], 0, v[134:135]
	s_mov_b32 m0, s37
	s_nop 0
	global_load_lds_dwordx4 v[224:225], off
	s_waitcnt vmcnt(8)
	s_waitcnt lgkmcnt(0)
	s_barrier
	s_setprio 1
	s_waitcnt lgkmcnt(0)
	v_mfma_f32_16x16x32_bf16 v[126:129], v[152:155], v[186:189], v[126:129]
	v_mfma_f32_16x16x32_bf16 v[122:125], v[160:163], v[186:189], v[122:125]
	v_mfma_f32_16x16x32_bf16 v[110:113], v[152:155], v[194:197], v[110:113]
	v_mfma_f32_16x16x32_bf16 v[106:109], v[160:163], v[194:197], v[106:109]
	v_mfma_f32_16x16x32_bf16 v[94:97], v[152:155], v[202:205], v[94:97]
	v_mfma_f32_16x16x32_bf16 v[90:93], v[160:163], v[202:205], v[90:93]
	v_mfma_f32_16x16x32_bf16 v[78:81], v[152:155], v[210:213], v[78:81]
	v_mfma_f32_16x16x32_bf16 v[74:77], v[160:163], v[210:213], v[74:77]
	v_mfma_f32_16x16x32_bf16 v[126:129], v[156:159], v[190:193], v[126:129]
	v_mfma_f32_16x16x32_bf16 v[122:125], v[164:167], v[190:193], v[122:125]
	v_mfma_f32_16x16x32_bf16 v[110:113], v[156:159], v[198:201], v[110:113]
	v_mfma_f32_16x16x32_bf16 v[106:109], v[164:167], v[198:201], v[106:109]
	v_mfma_f32_16x16x32_bf16 v[94:97], v[156:159], v[206:209], v[94:97]
	v_mfma_f32_16x16x32_bf16 v[90:93], v[164:167], v[206:209], v[90:93]
	v_mfma_f32_16x16x32_bf16 v[78:81], v[156:159], v[214:217], v[78:81]
	v_mfma_f32_16x16x32_bf16 v[74:77], v[164:167], v[214:217], v[74:77]
	s_setprio 0
	s_setprio 1
	v_mfma_f32_16x16x32_bf16 v[118:121], v[168:171], v[186:189], v[118:121]
	v_mfma_f32_16x16x32_bf16 v[114:117], v[178:181], v[186:189], v[114:117]
	v_mfma_f32_16x16x32_bf16 v[102:105], v[168:171], v[194:197], v[102:105]
	v_mfma_f32_16x16x32_bf16 v[98:101], v[178:181], v[194:197], v[98:101]
	v_mfma_f32_16x16x32_bf16 v[86:89], v[168:171], v[202:205], v[86:89]
	v_mfma_f32_16x16x32_bf16 v[82:85], v[178:181], v[202:205], v[82:85]
	v_mfma_f32_16x16x32_bf16 v[70:73], v[168:171], v[210:213], v[70:73]
	v_mfma_f32_16x16x32_bf16 v[66:69], v[178:181], v[210:213], v[66:69]
	v_mfma_f32_16x16x32_bf16 v[118:121], v[172:175], v[190:193], v[118:121]
	v_mfma_f32_16x16x32_bf16 v[114:117], v[182:185], v[190:193], v[114:117]
	v_mfma_f32_16x16x32_bf16 v[102:105], v[172:175], v[198:201], v[102:105]
	v_mfma_f32_16x16x32_bf16 v[98:101], v[182:185], v[198:201], v[98:101]
	v_mfma_f32_16x16x32_bf16 v[86:89], v[172:175], v[206:209], v[86:89]
	v_mfma_f32_16x16x32_bf16 v[82:85], v[182:185], v[206:209], v[82:85]
	v_mfma_f32_16x16x32_bf16 v[70:73], v[172:175], v[214:217], v[70:73]
	v_mfma_f32_16x16x32_bf16 v[66:69], v[182:185], v[214:217], v[66:69]
	s_setprio 0
	s_barrier
	s_add_i32 s2, s53, s34
	v_lshl_add_u64 v[146:147], v[146:147], 0, s[6:7]
	s_mov_b32 m0, s2
	ds_read_b128 v[186:189], v151 offset:49152
	ds_read_b128 v[190:193], v151 offset:50176
	ds_read_b128 v[194:197], v151 offset:51200
	ds_read_b128 v[198:201], v151 offset:52224
	ds_read_b128 v[202:205], v151 offset:53248
	ds_read_b128 v[206:209], v151 offset:54272
	ds_read_b128 v[210:213], v151 offset:55296
	ds_read_b128 v[214:217], v151 offset:56320
	global_load_lds_dwordx4 v[146:147], off
	s_add_i32 m0, s2, 0x2000
	s_add_u32 s2, s30, 0x40080
	v_lshl_add_u64 v[146:147], v[218:219], 0, s[6:7]
	s_addc_u32 s3, s31, 0
	s_add_i32 s30, s54, s34
	global_load_lds_dwordx4 v[146:147], off
	v_lshl_add_u64 v[146:147], s[2:3], 0, v[132:133]
	s_mov_b32 m0, s30
	s_nop 0
	global_load_lds_dwordx4 v[146:147], off
	v_lshl_add_u64 v[146:147], s[2:3], 0, v[136:137]
	s_add_i32 m0, s30, 0x2000
	s_nop 0
	global_load_lds_dwordx4 v[146:147], off
	v_lshl_add_u64 v[146:147], v[220:221], 0, s[6:7]
	s_mov_b32 m0, s39
	s_nop 0
	global_load_lds_dwordx4 v[146:147], off
	v_lshl_add_u64 v[146:147], v[222:223], 0, s[6:7]
	s_mov_b32 m0, s40
	s_nop 0
	global_load_lds_dwordx4 v[146:147], off
	s_waitcnt vmcnt(8)
	s_waitcnt lgkmcnt(0)
	s_barrier
	s_setprio 1
	s_waitcnt lgkmcnt(0)
	v_mfma_f32_16x16x32_bf16 v[62:65], v[152:155], v[186:189], v[62:65]
	v_mfma_f32_16x16x32_bf16 v[58:61], v[160:163], v[186:189], v[58:61]
	v_mfma_f32_16x16x32_bf16 v[46:49], v[152:155], v[194:197], v[46:49]
	v_mfma_f32_16x16x32_bf16 v[42:45], v[160:163], v[194:197], v[42:45]
	v_mfma_f32_16x16x32_bf16 v[30:33], v[152:155], v[202:205], v[30:33]
	v_mfma_f32_16x16x32_bf16 v[26:29], v[160:163], v[202:205], v[26:29]
	v_mfma_f32_16x16x32_bf16 v[14:17], v[152:155], v[210:213], v[14:17]
	v_mfma_f32_16x16x32_bf16 v[10:13], v[160:163], v[210:213], v[10:13]
	v_mfma_f32_16x16x32_bf16 v[62:65], v[156:159], v[190:193], v[62:65]
	v_mfma_f32_16x16x32_bf16 v[58:61], v[164:167], v[190:193], v[58:61]
	v_mfma_f32_16x16x32_bf16 v[46:49], v[156:159], v[198:201], v[46:49]
	v_mfma_f32_16x16x32_bf16 v[42:45], v[164:167], v[198:201], v[42:45]
	v_mfma_f32_16x16x32_bf16 v[30:33], v[156:159], v[206:209], v[30:33]
	v_mfma_f32_16x16x32_bf16 v[26:29], v[164:167], v[206:209], v[26:29]
	v_mfma_f32_16x16x32_bf16 v[14:17], v[156:159], v[214:217], v[14:17]
	v_mfma_f32_16x16x32_bf16 v[10:13], v[164:167], v[214:217], v[10:13]
	s_setprio 0
	s_setprio 1
	v_mfma_f32_16x16x32_bf16 v[54:57], v[168:171], v[186:189], v[54:57]
	v_mfma_f32_16x16x32_bf16 v[50:53], v[178:181], v[186:189], v[50:53]
	v_mfma_f32_16x16x32_bf16 v[38:41], v[168:171], v[194:197], v[38:41]
	v_mfma_f32_16x16x32_bf16 v[34:37], v[178:181], v[194:197], v[34:37]
	v_mfma_f32_16x16x32_bf16 v[22:25], v[168:171], v[202:205], v[22:25]
	v_mfma_f32_16x16x32_bf16 v[18:21], v[178:181], v[202:205], v[18:21]
	v_mfma_f32_16x16x32_bf16 v[6:9], v[168:171], v[210:213], v[6:9]
	v_mfma_f32_16x16x32_bf16 v[2:5], v[178:181], v[210:213], v[2:5]
	v_mfma_f32_16x16x32_bf16 v[54:57], v[172:175], v[190:193], v[54:57]
	v_mfma_f32_16x16x32_bf16 v[50:53], v[182:185], v[190:193], v[50:53]
	v_mfma_f32_16x16x32_bf16 v[38:41], v[172:175], v[198:201], v[38:41]
	v_mfma_f32_16x16x32_bf16 v[34:37], v[182:185], v[198:201], v[34:37]
	v_mfma_f32_16x16x32_bf16 v[22:25], v[172:175], v[206:209], v[22:25]
	v_mfma_f32_16x16x32_bf16 v[18:21], v[182:185], v[206:209], v[18:21]
	v_mfma_f32_16x16x32_bf16 v[6:9], v[172:175], v[214:217], v[6:9]
	v_mfma_f32_16x16x32_bf16 v[2:5], v[182:185], v[214:217], v[2:5]
	s_setprio 0
	s_barrier
	s_add_i32 s52, s52, 2
	s_add_u32 s28, s28, 0x100
	s_addc_u32 s29, s29, 0
	s_add_u32 s46, s46, 0x100
	s_addc_u32 s47, s47, 0
	s_cmp_gt_u32 s52, 13
	s_cbranch_scc0 .LBB0_451
	s_branch .Lpk451_exit
	s_branch .LBB0_451
	.p2align 6

.LBB0_494:
	s_lshl_b64 s[2:3], s[8:9], 1
	v_readlane_b32 s14, v253, 54
	s_add_u32 s14, s14, s2
	v_readlane_b32 s2, v253, 7
	s_addc_u32 s15, s2, s3
	s_and_b64 s[2:3], s[12:13], exec
	s_cselect_b32 s44, s15, s19
	s_cselect_b32 s45, s14, s18
	s_lshl_b64 s[2:3], s[10:11], 1
	s_add_u32 s16, s26, s2
	s_addc_u32 s17, s27, s3
	s_and_b64 s[2:3], s[12:13], exec
	s_cselect_b32 s46, s17, s21
	s_cselect_b32 s47, s16, s20
	s_add_u32 s18, s18, 0xc000
	s_addc_u32 s19, s19, 0
	s_add_u32 s48, s20, 0x10000
	s_addc_u32 s49, s21, 0
	s_mov_b32 s50, -2
	s_branch .Lpk495_peel
	.p2align 6
.Lpk495_peel:
	ds_read_b128 v[152:155], v149
	ds_read_b128 v[156:159], v149 offset:1024
	ds_read_b128 v[160:163], v149 offset:2048
	ds_read_b128 v[164:167], v149 offset:3072
	ds_read_b128 v[168:171], v150
	ds_read_b128 v[172:175], v150 offset:1024
	ds_read_b128 v[178:181], v150 offset:2048
	ds_read_b128 v[182:185], v150 offset:3072
	s_add_u32 s2, s18, 0x4000
	s_addc_u32 s3, s19, 0
	s_cmp_eq_u32 s50, 40
	s_cselect_b32 s2, s45, s2
	s_cselect_b32 s3, s44, s3
	s_cselect_b32 s23, s46, s49
	s_cselect_b32 s22, s47, s48
	s_add_u32 s20, s2, 0x8000
	s_addc_u32 s21, s3, 0
	v_lshl_add_u64 v[144:145], s[18:19], 0, v[138:139]
	s_add_i32 m0, s29, 0xc000
	ds_read_b128 v[186:189], v151
	ds_read_b128 v[190:193], v151 offset:1024
	ds_read_b128 v[194:197], v151 offset:2048
	ds_read_b128 v[198:201], v151 offset:3072
	ds_read_b128 v[202:205], v151 offset:4096
	ds_read_b128 v[206:209], v151 offset:5120
	ds_read_b128 v[210:213], v151 offset:6144
	ds_read_b128 v[214:217], v151 offset:7168
	global_load_lds_dwordx4 v[144:145], off
	v_lshl_add_u64 v[144:145], s[18:19], 0, v[140:141]
	s_add_i32 m0, s29, 0xe000
	s_nop 0
	global_load_lds_dwordx4 v[144:145], off
	s_waitcnt vmcnt(8)
	s_waitcnt lgkmcnt(0)
	s_barrier
	s_setprio 1
	s_waitcnt lgkmcnt(0)
	v_mfma_f32_16x16x32_bf16 v[126:129], v[152:155], v[186:189], 0
	v_mfma_f32_16x16x32_bf16 v[122:125], v[160:163], v[186:189], 0
	v_mfma_f32_16x16x32_bf16 v[114:117], v[152:155], v[194:197], 0
	v_mfma_f32_16x16x32_bf16 v[106:109], v[160:163], v[194:197], 0
	v_mfma_f32_16x16x32_bf16 v[98:101], v[152:155], v[202:205], 0
	v_mfma_f32_16x16x32_bf16 v[90:93], v[160:163], v[202:205], 0
	v_mfma_f32_16x16x32_bf16 v[82:85], v[152:155], v[210:213], 0
	v_mfma_f32_16x16x32_bf16 v[74:77], v[160:163], v[210:213], 0
	v_mfma_f32_16x16x32_bf16 v[126:129], v[156:159], v[190:193], v[126:129]
	v_mfma_f32_16x16x32_bf16 v[122:125], v[164:167], v[190:193], v[122:125]
	v_mfma_f32_16x16x32_bf16 v[114:117], v[156:159], v[198:201], v[114:117]
	v_mfma_f32_16x16x32_bf16 v[106:109], v[164:167], v[198:201], v[106:109]
	v_mfma_f32_16x16x32_bf16 v[98:101], v[156:159], v[206:209], v[98:101]
	v_mfma_f32_16x16x32_bf16 v[90:93], v[164:167], v[206:209], v[90:93]
	v_mfma_f32_16x16x32_bf16 v[82:85], v[156:159], v[214:217], v[82:85]
	v_mfma_f32_16x16x32_bf16 v[74:77], v[164:167], v[214:217], v[74:77]
	s_setprio 0
	s_setprio 1
	v_mfma_f32_16x16x32_bf16 v[118:121], v[168:171], v[186:189], 0
	v_mfma_f32_16x16x32_bf16 v[110:113], v[178:181], v[186:189], 0
	v_mfma_f32_16x16x32_bf16 v[102:105], v[168:171], v[194:197], 0
	v_mfma_f32_16x16x32_bf16 v[94:97], v[178:181], v[194:197], 0
	v_mfma_f32_16x16x32_bf16 v[86:89], v[168:171], v[202:205], 0
	v_mfma_f32_16x16x32_bf16 v[78:81], v[178:181], v[202:205], 0
	v_mfma_f32_16x16x32_bf16 v[70:73], v[168:171], v[210:213], 0
	v_mfma_f32_16x16x32_bf16 v[66:69], v[178:181], v[210:213], 0
	v_mfma_f32_16x16x32_bf16 v[118:121], v[172:175], v[190:193], v[118:121]
	v_mfma_f32_16x16x32_bf16 v[110:113], v[182:185], v[190:193], v[110:113]
	v_mfma_f32_16x16x32_bf16 v[102:105], v[172:175], v[198:201], v[102:105]
	v_mfma_f32_16x16x32_bf16 v[94:97], v[182:185], v[198:201], v[94:97]
	v_mfma_f32_16x16x32_bf16 v[86:89], v[172:175], v[206:209], v[86:89]
	v_mfma_f32_16x16x32_bf16 v[78:81], v[182:185], v[206:209], v[78:81]
	v_mfma_f32_16x16x32_bf16 v[70:73], v[172:175], v[214:217], v[70:73]
	v_mfma_f32_16x16x32_bf16 v[66:69], v[182:185], v[214:217], v[66:69]
	s_setprio 0
	s_barrier
	s_add_i32 s51, s38, s28
	v_lshl_add_u64 v[144:145], s[22:23], 0, v[132:133]
	s_mov_b32 m0, s51
	ds_read_b128 v[186:189], v151 offset:16384
	ds_read_b128 v[190:193], v151 offset:17408
	ds_read_b128 v[194:197], v151 offset:18432
	ds_read_b128 v[198:201], v151 offset:19456
	ds_read_b128 v[202:205], v151 offset:20480
	ds_read_b128 v[206:209], v151 offset:21504
	ds_read_b128 v[210:213], v151 offset:22528
	ds_read_b128 v[214:217], v151 offset:23552
	global_load_lds_dwordx4 v[144:145], off
	s_add_i32 m0, s51, 0x2000
	s_add_u32 s52, s22, 0x4000
	v_lshl_add_u64 v[144:145], s[22:23], 0, v[136:137]
	s_addc_u32 s53, s23, 0
	s_add_i32 s51, s39, s28
	global_load_lds_dwordx4 v[144:145], off
	v_lshl_add_u64 v[144:145], s[52:53], 0, v[132:133]
	s_mov_b32 m0, s51
	s_nop 0
	global_load_lds_dwordx4 v[144:145], off
	v_lshl_add_u64 v[144:145], s[52:53], 0, v[136:137]
	s_add_i32 m0, s51, 0x2000
	s_nop 0
	global_load_lds_dwordx4 v[144:145], off
	v_lshl_add_u64 v[144:145], s[2:3], 0, v[130:131]
	s_mov_b32 m0, s29
	s_nop 0
	global_load_lds_dwordx4 v[144:145], off
	v_lshl_add_u64 v[144:145], s[2:3], 0, v[134:135]
	s_mov_b32 m0, s30
	s_nop 0
	global_load_lds_dwordx4 v[144:145], off
	s_waitcnt vmcnt(8)
	s_waitcnt lgkmcnt(0)
	s_barrier
	s_setprio 1
	s_waitcnt lgkmcnt(0)
	v_mfma_f32_16x16x32_bf16 v[62:65], v[152:155], v[186:189], 0
	v_mfma_f32_16x16x32_bf16 v[58:61], v[160:163], v[186:189], 0
	v_mfma_f32_16x16x32_bf16 v[50:53], v[152:155], v[194:197], 0
	v_mfma_f32_16x16x32_bf16 v[42:45], v[160:163], v[194:197], 0
	v_mfma_f32_16x16x32_bf16 v[34:37], v[152:155], v[202:205], 0
	v_mfma_f32_16x16x32_bf16 v[26:29], v[160:163], v[202:205], 0
	v_mfma_f32_16x16x32_bf16 v[18:21], v[152:155], v[210:213], 0
	v_mfma_f32_16x16x32_bf16 v[10:13], v[160:163], v[210:213], 0
	v_mfma_f32_16x16x32_bf16 v[62:65], v[156:159], v[190:193], v[62:65]
	v_mfma_f32_16x16x32_bf16 v[58:61], v[164:167], v[190:193], v[58:61]
	v_mfma_f32_16x16x32_bf16 v[50:53], v[156:159], v[198:201], v[50:53]
	v_mfma_f32_16x16x32_bf16 v[42:45], v[164:167], v[198:201], v[42:45]
	v_mfma_f32_16x16x32_bf16 v[34:37], v[156:159], v[206:209], v[34:37]
	v_mfma_f32_16x16x32_bf16 v[26:29], v[164:167], v[206:209], v[26:29]
	v_mfma_f32_16x16x32_bf16 v[18:21], v[156:159], v[214:217], v[18:21]
	v_mfma_f32_16x16x32_bf16 v[10:13], v[164:167], v[214:217], v[10:13]
	s_setprio 0
	s_setprio 1
	v_mfma_f32_16x16x32_bf16 v[54:57], v[168:171], v[186:189], 0
	v_mfma_f32_16x16x32_bf16 v[46:49], v[178:181], v[186:189], 0
	v_mfma_f32_16x16x32_bf16 v[38:41], v[168:171], v[194:197], 0
	v_mfma_f32_16x16x32_bf16 v[30:33], v[178:181], v[194:197], 0
	v_mfma_f32_16x16x32_bf16 v[22:25], v[168:171], v[202:205], 0
	v_mfma_f32_16x16x32_bf16 v[14:17], v[178:181], v[202:205], 0
	v_mfma_f32_16x16x32_bf16 v[6:9], v[168:171], v[210:213], 0
	v_mfma_f32_16x16x32_bf16 v[2:5], v[178:181], v[210:213], 0
	v_mfma_f32_16x16x32_bf16 v[54:57], v[172:175], v[190:193], v[54:57]
	v_mfma_f32_16x16x32_bf16 v[46:49], v[182:185], v[190:193], v[46:49]
	v_mfma_f32_16x16x32_bf16 v[38:41], v[172:175], v[198:201], v[38:41]
	v_mfma_f32_16x16x32_bf16 v[30:33], v[182:185], v[198:201], v[30:33]
	v_mfma_f32_16x16x32_bf16 v[22:25], v[172:175], v[206:209], v[22:25]
	v_mfma_f32_16x16x32_bf16 v[14:17], v[182:185], v[206:209], v[14:17]
	v_mfma_f32_16x16x32_bf16 v[6:9], v[172:175], v[214:217], v[6:9]
	v_mfma_f32_16x16x32_bf16 v[2:5], v[182:185], v[214:217], v[2:5]
	s_setprio 0
	s_barrier
	s_add_i32 s51, 0, 0x18000
	v_add_u32_e32 v144, s51, v147
	s_add_i32 s52, 0, 0x1c000
	ds_read_b128 v[152:155], v144
	ds_read_b128 v[156:159], v144 offset:1024
	ds_read_b128 v[160:163], v144 offset:2048
	ds_read_b128 v[164:167], v144 offset:3072
	v_add_u32_e32 v144, s52, v147
	ds_read_b128 v[168:171], v144
	ds_read_b128 v[172:175], v144 offset:1024
	ds_read_b128 v[178:181], v144 offset:2048
	ds_read_b128 v[182:185], v144 offset:3072
	s_add_u32 s2, s2, 0x4000
	s_addc_u32 s3, s3, 0
	s_mov_b32 m0, s31
	v_lshl_add_u64 v[144:145], s[2:3], 0, v[130:131]
	ds_read_b128 v[186:189], v151 offset:32768
	ds_read_b128 v[190:193], v151 offset:33792
	ds_read_b128 v[194:197], v151 offset:34816
	ds_read_b128 v[198:201], v151 offset:35840
	ds_read_b128 v[202:205], v151 offset:36864
	ds_read_b128 v[206:209], v151 offset:37888
	ds_read_b128 v[210:213], v151 offset:38912
	ds_read_b128 v[214:217], v151 offset:39936
	global_load_lds_dwordx4 v[144:145], off
	v_lshl_add_u64 v[144:145], s[2:3], 0, v[134:135]
	s_mov_b32 m0, s34
	s_nop 0
	global_load_lds_dwordx4 v[144:145], off
	s_waitcnt vmcnt(8)
	s_waitcnt lgkmcnt(0)
	s_barrier
	s_setprio 1
	s_waitcnt lgkmcnt(0)
	v_mfma_f32_16x16x32_bf16 v[126:129], v[152:155], v[186:189], v[126:129]
	v_mfma_f32_16x16x32_bf16 v[122:125], v[160:163], v[186:189], v[122:125]
	v_mfma_f32_16x16x32_bf16 v[114:117], v[152:155], v[194:197], v[114:117]
	v_mfma_f32_16x16x32_bf16 v[106:109], v[160:163], v[194:197], v[106:109]
	v_mfma_f32_16x16x32_bf16 v[98:101], v[152:155], v[202:205], v[98:101]
	v_mfma_f32_16x16x32_bf16 v[90:93], v[160:163], v[202:205], v[90:93]
	v_mfma_f32_16x16x32_bf16 v[82:85], v[152:155], v[210:213], v[82:85]
	v_mfma_f32_16x16x32_bf16 v[74:77], v[160:163], v[210:213], v[74:77]
	v_mfma_f32_16x16x32_bf16 v[126:129], v[156:159], v[190:193], v[126:129]
	v_mfma_f32_16x16x32_bf16 v[122:125], v[164:167], v[190:193], v[122:125]
	v_mfma_f32_16x16x32_bf16 v[114:117], v[156:159], v[198:201], v[114:117]
	v_mfma_f32_16x16x32_bf16 v[106:109], v[164:167], v[198:201], v[106:109]
	v_mfma_f32_16x16x32_bf16 v[98:101], v[156:159], v[206:209], v[98:101]
	v_mfma_f32_16x16x32_bf16 v[90:93], v[164:167], v[206:209], v[90:93]
	v_mfma_f32_16x16x32_bf16 v[82:85], v[156:159], v[214:217], v[82:85]
	v_mfma_f32_16x16x32_bf16 v[74:77], v[164:167], v[214:217], v[74:77]
	s_setprio 0
	s_setprio 1
	v_mfma_f32_16x16x32_bf16 v[118:121], v[168:171], v[186:189], v[118:121]
	v_mfma_f32_16x16x32_bf16 v[110:113], v[178:181], v[186:189], v[110:113]
	v_mfma_f32_16x16x32_bf16 v[102:105], v[168:171], v[194:197], v[102:105]
	v_mfma_f32_16x16x32_bf16 v[94:97], v[178:181], v[194:197], v[94:97]
	v_mfma_f32_16x16x32_bf16 v[86:89], v[168:171], v[202:205], v[86:89]
	v_mfma_f32_16x16x32_bf16 v[78:81], v[178:181], v[202:205], v[78:81]
	v_mfma_f32_16x16x32_bf16 v[70:73], v[168:171], v[210:213], v[70:73]
	v_mfma_f32_16x16x32_bf16 v[66:69], v[178:181], v[210:213], v[66:69]
	v_mfma_f32_16x16x32_bf16 v[118:121], v[172:175], v[190:193], v[118:121]
	v_mfma_f32_16x16x32_bf16 v[110:113], v[182:185], v[190:193], v[110:113]
	v_mfma_f32_16x16x32_bf16 v[102:105], v[172:175], v[198:201], v[102:105]
	v_mfma_f32_16x16x32_bf16 v[94:97], v[182:185], v[198:201], v[94:97]
	v_mfma_f32_16x16x32_bf16 v[86:89], v[172:175], v[206:209], v[86:89]
	v_mfma_f32_16x16x32_bf16 v[78:81], v[182:185], v[206:209], v[78:81]
	v_mfma_f32_16x16x32_bf16 v[70:73], v[172:175], v[214:217], v[70:73]
	v_mfma_f32_16x16x32_bf16 v[66:69], v[182:185], v[214:217], v[66:69]
	s_setprio 0
	s_barrier
	s_add_u32 s2, s22, 0x8000
	s_addc_u32 s3, s23, 0
	s_add_i32 s51, s51, s28
	v_lshl_add_u64 v[144:145], s[2:3], 0, v[132:133]
	s_mov_b32 m0, s51
	ds_read_b128 v[186:189], v151 offset:49152
	ds_read_b128 v[190:193], v151 offset:50176
	ds_read_b128 v[194:197], v151 offset:51200
	ds_read_b128 v[198:201], v151 offset:52224
	ds_read_b128 v[202:205], v151 offset:53248
	ds_read_b128 v[206:209], v151 offset:54272
	ds_read_b128 v[210:213], v151 offset:55296
	ds_read_b128 v[214:217], v151 offset:56320
	global_load_lds_dwordx4 v[144:145], off
	s_add_i32 m0, s51, 0x2000
	v_lshl_add_u64 v[144:145], s[2:3], 0, v[136:137]
	s_add_u32 s2, s22, 0xc000
	s_addc_u32 s3, s23, 0
	s_add_i32 s22, s52, s28
	global_load_lds_dwordx4 v[144:145], off
	v_lshl_add_u64 v[144:145], s[2:3], 0, v[132:133]
	s_mov_b32 m0, s22
	s_nop 0
	global_load_lds_dwordx4 v[144:145], off
	v_lshl_add_u64 v[144:145], s[2:3], 0, v[136:137]
	s_add_i32 m0, s22, 0x2000
	s_nop 0
	global_load_lds_dwordx4 v[144:145], off
	v_lshl_add_u64 v[144:145], s[20:21], 0, v[130:131]
	s_mov_b32 m0, s36
	s_nop 0
	global_load_lds_dwordx4 v[144:145], off
	v_lshl_add_u64 v[144:145], s[20:21], 0, v[134:135]
	s_mov_b32 m0, s37
	s_nop 0
	global_load_lds_dwordx4 v[144:145], off
	s_waitcnt vmcnt(8)
	s_waitcnt lgkmcnt(0)
	s_barrier
	s_setprio 1
	s_waitcnt lgkmcnt(0)
	v_mfma_f32_16x16x32_bf16 v[62:65], v[152:155], v[186:189], v[62:65]
	v_mfma_f32_16x16x32_bf16 v[58:61], v[160:163], v[186:189], v[58:61]
	v_mfma_f32_16x16x32_bf16 v[50:53], v[152:155], v[194:197], v[50:53]
	v_mfma_f32_16x16x32_bf16 v[42:45], v[160:163], v[194:197], v[42:45]
	v_mfma_f32_16x16x32_bf16 v[34:37], v[152:155], v[202:205], v[34:37]
	v_mfma_f32_16x16x32_bf16 v[26:29], v[160:163], v[202:205], v[26:29]
	v_mfma_f32_16x16x32_bf16 v[18:21], v[152:155], v[210:213], v[18:21]
	v_mfma_f32_16x16x32_bf16 v[10:13], v[160:163], v[210:213], v[10:13]
	v_mfma_f32_16x16x32_bf16 v[62:65], v[156:159], v[190:193], v[62:65]
	v_mfma_f32_16x16x32_bf16 v[58:61], v[164:167], v[190:193], v[58:61]
	v_mfma_f32_16x16x32_bf16 v[50:53], v[156:159], v[198:201], v[50:53]
	v_mfma_f32_16x16x32_bf16 v[42:45], v[164:167], v[198:201], v[42:45]
	v_mfma_f32_16x16x32_bf16 v[34:37], v[156:159], v[206:209], v[34:37]
	v_mfma_f32_16x16x32_bf16 v[26:29], v[164:167], v[206:209], v[26:29]
	v_mfma_f32_16x16x32_bf16 v[18:21], v[156:159], v[214:217], v[18:21]
	v_mfma_f32_16x16x32_bf16 v[10:13], v[164:167], v[214:217], v[10:13]
	s_setprio 0
	s_setprio 1
	v_mfma_f32_16x16x32_bf16 v[54:57], v[168:171], v[186:189], v[54:57]
	v_mfma_f32_16x16x32_bf16 v[46:49], v[178:181], v[186:189], v[46:49]
	v_mfma_f32_16x16x32_bf16 v[38:41], v[168:171], v[194:197], v[38:41]
	v_mfma_f32_16x16x32_bf16 v[30:33], v[178:181], v[194:197], v[30:33]
	v_mfma_f32_16x16x32_bf16 v[22:25], v[168:171], v[202:205], v[22:25]
	v_mfma_f32_16x16x32_bf16 v[14:17], v[178:181], v[202:205], v[14:17]
	v_mfma_f32_16x16x32_bf16 v[6:9], v[168:171], v[210:213], v[6:9]
	v_mfma_f32_16x16x32_bf16 v[2:5], v[178:181], v[210:213], v[2:5]
	v_mfma_f32_16x16x32_bf16 v[54:57], v[172:175], v[190:193], v[54:57]
	v_mfma_f32_16x16x32_bf16 v[46:49], v[182:185], v[190:193], v[46:49]
	v_mfma_f32_16x16x32_bf16 v[38:41], v[172:175], v[198:201], v[38:41]
	v_mfma_f32_16x16x32_bf16 v[30:33], v[182:185], v[198:201], v[30:33]
	v_mfma_f32_16x16x32_bf16 v[22:25], v[172:175], v[206:209], v[22:25]
	v_mfma_f32_16x16x32_bf16 v[14:17], v[182:185], v[206:209], v[14:17]
	v_mfma_f32_16x16x32_bf16 v[6:9], v[172:175], v[214:217], v[6:9]
	v_mfma_f32_16x16x32_bf16 v[2:5], v[182:185], v[214:217], v[2:5]
	s_setprio 0
	s_barrier
	s_add_i32 s50, s50, 2
	s_add_u32 s18, s18, 0x10000
	s_addc_u32 s19, s19, 0
	s_add_u32 s48, s48, 0x10000
	s_addc_u32 s49, s49, 0
	s_cmp_gt_u32 s50, 41
	s_cbranch_scc0 .LBB0_495
	s_branch .Lpk495_exit
	s_branch .LBB0_495
	.p2align 6

.LBB0_554:
	s_lshl_b64 s[2:3], s[14:15], 1
	v_readlane_b32 s20, v253, 52
	v_readlane_b32 s21, v253, 53
	s_add_u32 s20, s20, s2
	s_addc_u32 s21, s21, s3
	s_and_b64 s[2:3], s[18:19], exec
	s_cselect_b32 s11, s21, s27
	s_cselect_b32 s13, s20, s26
	s_lshl_b64 s[2:3], s[16:17], 1
	s_add_u32 s22, s30, s2
	s_addc_u32 s23, s31, s3
	s_and_b64 s[2:3], s[18:19], exec
	s_cselect_b32 s48, s23, s29
	s_cselect_b32 s49, s22, s28
	s_add_u32 s26, s26, 0x40080
	s_addc_u32 s27, s27, 0
	s_add_u32 s50, s28, 0x100
	s_addc_u32 s51, s29, 0
	s_mov_b32 s52, -2
	s_branch .Lpk555_peel
	.p2align 6
.Lpk555_peel:
	ds_read_b128 v[154:157], v151
	ds_read_b128 v[158:161], v151 offset:1024
	ds_read_b128 v[162:165], v151 offset:2048
	ds_read_b128 v[166:169], v151 offset:3072
	ds_read_b128 v[170:173], v152
	ds_read_b128 v[178:181], v152 offset:1024
	ds_read_b128 v[182:185], v152 offset:2048
	ds_read_b128 v[186:189], v152 offset:3072
	s_add_u32 s2, s26, 0xfffc0080
	s_addc_u32 s3, s27, -1
	s_cmp_eq_u32 s52, 12
	s_cselect_b32 s3, s11, s3
	s_cselect_b32 s2, s13, s2
	s_cselect_b32 s29, s48, s51
	s_cselect_b32 s28, s49, s50
	v_lshl_add_u64 v[144:145], s[26:27], 0, v[138:139]
	s_add_i32 m0, s37, 0xc000
	ds_read_b128 v[190:193], v153
	ds_read_b128 v[194:197], v153 offset:1024
	ds_read_b128 v[198:201], v153 offset:2048
	ds_read_b128 v[202:205], v153 offset:3072
	ds_read_b128 v[206:209], v153 offset:4096
	ds_read_b128 v[210:213], v153 offset:5120
	ds_read_b128 v[214:217], v153 offset:6144
	ds_read_b128 v[218:221], v153 offset:7168
	global_load_lds_dwordx4 v[144:145], off
	v_lshl_add_u64 v[144:145], s[26:27], 0, v[140:141]
	s_add_i32 m0, s37, 0xe000
	s_nop 0
	global_load_lds_dwordx4 v[144:145], off
	s_waitcnt vmcnt(8)
	s_waitcnt lgkmcnt(0)
	s_barrier
	s_setprio 1
	s_waitcnt lgkmcnt(0)
	v_mfma_f32_16x16x32_bf16 v[126:129], v[154:157], v[190:193], 0
	v_mfma_f32_16x16x32_bf16 v[122:125], v[162:165], v[190:193], 0
	v_mfma_f32_16x16x32_bf16 v[114:117], v[154:157], v[198:201], 0
	v_mfma_f32_16x16x32_bf16 v[106:109], v[162:165], v[198:201], 0
	v_mfma_f32_16x16x32_bf16 v[98:101], v[154:157], v[206:209], 0
	v_mfma_f32_16x16x32_bf16 v[90:93], v[162:165], v[206:209], 0
	v_mfma_f32_16x16x32_bf16 v[82:85], v[154:157], v[214:217], 0
	v_mfma_f32_16x16x32_bf16 v[74:77], v[162:165], v[214:217], 0
	v_mfma_f32_16x16x32_bf16 v[126:129], v[158:161], v[194:197], v[126:129]
	v_mfma_f32_16x16x32_bf16 v[122:125], v[166:169], v[194:197], v[122:125]
	v_mfma_f32_16x16x32_bf16 v[114:117], v[158:161], v[202:205], v[114:117]
	v_mfma_f32_16x16x32_bf16 v[106:109], v[166:169], v[202:205], v[106:109]
	v_mfma_f32_16x16x32_bf16 v[98:101], v[158:161], v[210:213], v[98:101]
	v_mfma_f32_16x16x32_bf16 v[90:93], v[166:169], v[210:213], v[90:93]
	v_mfma_f32_16x16x32_bf16 v[82:85], v[158:161], v[218:221], v[82:85]
	v_mfma_f32_16x16x32_bf16 v[74:77], v[166:169], v[218:221], v[74:77]
	s_setprio 0
	s_setprio 1
	v_mfma_f32_16x16x32_bf16 v[118:121], v[170:173], v[190:193], 0
	v_mfma_f32_16x16x32_bf16 v[110:113], v[182:185], v[190:193], 0
	v_mfma_f32_16x16x32_bf16 v[102:105], v[170:173], v[198:201], 0
	v_mfma_f32_16x16x32_bf16 v[94:97], v[182:185], v[198:201], 0
	v_mfma_f32_16x16x32_bf16 v[86:89], v[170:173], v[206:209], 0
	v_mfma_f32_16x16x32_bf16 v[78:81], v[182:185], v[206:209], 0
	v_mfma_f32_16x16x32_bf16 v[70:73], v[170:173], v[214:217], 0
	v_mfma_f32_16x16x32_bf16 v[66:69], v[182:185], v[214:217], 0
	v_mfma_f32_16x16x32_bf16 v[118:121], v[178:181], v[194:197], v[118:121]
	v_mfma_f32_16x16x32_bf16 v[110:113], v[186:189], v[194:197], v[110:113]
	v_mfma_f32_16x16x32_bf16 v[102:105], v[178:181], v[202:205], v[102:105]
	v_mfma_f32_16x16x32_bf16 v[94:97], v[186:189], v[202:205], v[94:97]
	v_mfma_f32_16x16x32_bf16 v[86:89], v[178:181], v[210:213], v[86:89]
	v_mfma_f32_16x16x32_bf16 v[78:81], v[186:189], v[210:213], v[78:81]
	v_mfma_f32_16x16x32_bf16 v[70:73], v[178:181], v[218:221], v[70:73]
	v_mfma_f32_16x16x32_bf16 v[66:69], v[186:189], v[218:221], v[66:69]
	s_setprio 0
	s_barrier
	s_add_i32 s53, s44, s34
	v_lshl_add_u64 v[144:145], s[28:29], 0, v[134:135]
	s_mov_b32 m0, s53
	ds_read_b128 v[190:193], v153 offset:16384
	ds_read_b128 v[194:197], v153 offset:17408
	ds_read_b128 v[198:201], v153 offset:18432
	ds_read_b128 v[202:205], v153 offset:19456
	ds_read_b128 v[206:209], v153 offset:20480
	ds_read_b128 v[210:213], v153 offset:21504
	ds_read_b128 v[214:217], v153 offset:22528
	ds_read_b128 v[218:221], v153 offset:23552
	global_load_lds_dwordx4 v[144:145], off
	s_add_i32 m0, s53, 0x2000
	s_add_u32 s54, s28, 0x40000
	v_lshl_add_u64 v[174:175], s[28:29], 0, v[130:131]
	s_addc_u32 s55, s29, 0
	s_add_i32 s53, s45, s34
	global_load_lds_dwordx4 v[174:175], off
	v_lshl_add_u64 v[222:223], s[54:55], 0, v[134:135]
	s_mov_b32 m0, s53
	v_lshl_add_u64 v[224:225], s[2:3], 0, v[132:133]
	global_load_lds_dwordx4 v[222:223], off
	v_lshl_add_u64 v[222:223], s[54:55], 0, v[130:131]
	s_add_i32 m0, s53, 0x2000
	s_nop 0
	global_load_lds_dwordx4 v[222:223], off
	v_lshl_add_u64 v[222:223], s[2:3], 0, v[136:137]
	s_mov_b32 m0, s37
	s_nop 0
	global_load_lds_dwordx4 v[222:223], off
	s_mov_b32 m0, s25
	s_nop 0
	global_load_lds_dwordx4 v[224:225], off
	s_waitcnt vmcnt(8)
	s_waitcnt lgkmcnt(0)
	s_barrier
	s_setprio 1
	s_waitcnt lgkmcnt(0)
	v_mfma_f32_16x16x32_bf16 v[62:65], v[154:157], v[190:193], 0
	v_mfma_f32_16x16x32_bf16 v[58:61], v[162:165], v[190:193], 0
	v_mfma_f32_16x16x32_bf16 v[50:53], v[154:157], v[198:201], 0
	v_mfma_f32_16x16x32_bf16 v[42:45], v[162:165], v[198:201], 0
	v_mfma_f32_16x16x32_bf16 v[34:37], v[154:157], v[206:209], 0
	v_mfma_f32_16x16x32_bf16 v[26:29], v[162:165], v[206:209], 0
	v_mfma_f32_16x16x32_bf16 v[18:21], v[154:157], v[214:217], 0
	v_mfma_f32_16x16x32_bf16 v[10:13], v[162:165], v[214:217], 0
	v_mfma_f32_16x16x32_bf16 v[62:65], v[158:161], v[194:197], v[62:65]
	v_mfma_f32_16x16x32_bf16 v[58:61], v[166:169], v[194:197], v[58:61]
	v_mfma_f32_16x16x32_bf16 v[50:53], v[158:161], v[202:205], v[50:53]
	v_mfma_f32_16x16x32_bf16 v[42:45], v[166:169], v[202:205], v[42:45]
	v_mfma_f32_16x16x32_bf16 v[34:37], v[158:161], v[210:213], v[34:37]
	v_mfma_f32_16x16x32_bf16 v[26:29], v[166:169], v[210:213], v[26:29]
	v_mfma_f32_16x16x32_bf16 v[18:21], v[158:161], v[218:221], v[18:21]
	v_mfma_f32_16x16x32_bf16 v[10:13], v[166:169], v[218:221], v[10:13]
	s_setprio 0
	s_setprio 1
	v_mfma_f32_16x16x32_bf16 v[54:57], v[170:173], v[190:193], 0
	v_mfma_f32_16x16x32_bf16 v[46:49], v[182:185], v[190:193], 0
	v_mfma_f32_16x16x32_bf16 v[38:41], v[170:173], v[198:201], 0
	v_mfma_f32_16x16x32_bf16 v[30:33], v[182:185], v[198:201], 0
	v_mfma_f32_16x16x32_bf16 v[22:25], v[170:173], v[206:209], 0
	v_mfma_f32_16x16x32_bf16 v[14:17], v[182:185], v[206:209], 0
	v_mfma_f32_16x16x32_bf16 v[6:9], v[170:173], v[214:217], 0
	v_mfma_f32_16x16x32_bf16 v[2:5], v[182:185], v[214:217], 0
	v_mfma_f32_16x16x32_bf16 v[54:57], v[178:181], v[194:197], v[54:57]
	v_mfma_f32_16x16x32_bf16 v[46:49], v[186:189], v[194:197], v[46:49]
	v_mfma_f32_16x16x32_bf16 v[38:41], v[178:181], v[202:205], v[38:41]
	v_mfma_f32_16x16x32_bf16 v[30:33], v[186:189], v[202:205], v[30:33]
	v_mfma_f32_16x16x32_bf16 v[22:25], v[178:181], v[210:213], v[22:25]
	v_mfma_f32_16x16x32_bf16 v[14:17], v[186:189], v[210:213], v[14:17]
	v_mfma_f32_16x16x32_bf16 v[6:9], v[178:181], v[218:221], v[6:9]
	v_mfma_f32_16x16x32_bf16 v[2:5], v[186:189], v[218:221], v[2:5]
	s_setprio 0
	s_barrier
	s_add_i32 s53, 0, 0x18000
	s_add_i32 s54, 0, 0x1c000
	v_add_u32_e32 v166, s53, v149
	v_add_u32_e32 v176, s54, v149
	ds_read_b128 v[154:157], v166
	ds_read_b128 v[158:161], v166 offset:1024
	ds_read_b128 v[162:165], v166 offset:2048
	ds_read_b128 v[166:169], v166 offset:3072
	ds_read_b128 v[170:173], v176
	ds_read_b128 v[178:181], v176 offset:1024
	ds_read_b128 v[182:185], v176 offset:2048
	ds_read_b128 v[186:189], v176 offset:3072
	s_add_u32 s2, s2, 0x40000
	s_addc_u32 s3, s3, 0
	s_mov_b32 m0, s38
	v_lshl_add_u64 v[226:227], s[2:3], 0, v[136:137]
	ds_read_b128 v[190:193], v153 offset:32768
	ds_read_b128 v[194:197], v153 offset:33792
	ds_read_b128 v[198:201], v153 offset:34816
	ds_read_b128 v[202:205], v153 offset:35840
	ds_read_b128 v[206:209], v153 offset:36864
	ds_read_b128 v[210:213], v153 offset:37888
	ds_read_b128 v[214:217], v153 offset:38912
	ds_read_b128 v[218:221], v153 offset:39936
	global_load_lds_dwordx4 v[226:227], off
	v_lshl_add_u64 v[226:227], s[2:3], 0, v[132:133]
	s_mov_b32 m0, s39
	s_nop 0
	global_load_lds_dwordx4 v[226:227], off
	s_waitcnt vmcnt(8)
	s_waitcnt lgkmcnt(0)
	s_barrier
	s_setprio 1
	s_waitcnt lgkmcnt(0)
	v_mfma_f32_16x16x32_bf16 v[126:129], v[154:157], v[190:193], v[126:129]
	v_mfma_f32_16x16x32_bf16 v[122:125], v[162:165], v[190:193], v[122:125]
	v_mfma_f32_16x16x32_bf16 v[114:117], v[154:157], v[198:201], v[114:117]
	v_mfma_f32_16x16x32_bf16 v[106:109], v[162:165], v[198:201], v[106:109]
	v_mfma_f32_16x16x32_bf16 v[98:101], v[154:157], v[206:209], v[98:101]
	v_mfma_f32_16x16x32_bf16 v[90:93], v[162:165], v[206:209], v[90:93]
	v_mfma_f32_16x16x32_bf16 v[82:85], v[154:157], v[214:217], v[82:85]
	v_mfma_f32_16x16x32_bf16 v[74:77], v[162:165], v[214:217], v[74:77]
	v_mfma_f32_16x16x32_bf16 v[126:129], v[158:161], v[194:197], v[126:129]
	v_mfma_f32_16x16x32_bf16 v[122:125], v[166:169], v[194:197], v[122:125]
	v_mfma_f32_16x16x32_bf16 v[114:117], v[158:161], v[202:205], v[114:117]
	v_mfma_f32_16x16x32_bf16 v[106:109], v[166:169], v[202:205], v[106:109]
	v_mfma_f32_16x16x32_bf16 v[98:101], v[158:161], v[210:213], v[98:101]
	v_mfma_f32_16x16x32_bf16 v[90:93], v[166:169], v[210:213], v[90:93]
	v_mfma_f32_16x16x32_bf16 v[82:85], v[158:161], v[218:221], v[82:85]
	v_mfma_f32_16x16x32_bf16 v[74:77], v[166:169], v[218:221], v[74:77]
	s_setprio 0
	s_setprio 1
	v_mfma_f32_16x16x32_bf16 v[118:121], v[170:173], v[190:193], v[118:121]
	v_mfma_f32_16x16x32_bf16 v[110:113], v[182:185], v[190:193], v[110:113]
	v_mfma_f32_16x16x32_bf16 v[102:105], v[170:173], v[198:201], v[102:105]
	v_mfma_f32_16x16x32_bf16 v[94:97], v[182:185], v[198:201], v[94:97]
	v_mfma_f32_16x16x32_bf16 v[86:89], v[170:173], v[206:209], v[86:89]
	v_mfma_f32_16x16x32_bf16 v[78:81], v[182:185], v[206:209], v[78:81]
	v_mfma_f32_16x16x32_bf16 v[70:73], v[170:173], v[214:217], v[70:73]
	v_mfma_f32_16x16x32_bf16 v[66:69], v[182:185], v[214:217], v[66:69]
	v_mfma_f32_16x16x32_bf16 v[118:121], v[178:181], v[194:197], v[118:121]
	v_mfma_f32_16x16x32_bf16 v[110:113], v[186:189], v[194:197], v[110:113]
	v_mfma_f32_16x16x32_bf16 v[102:105], v[178:181], v[202:205], v[102:105]
	v_mfma_f32_16x16x32_bf16 v[94:97], v[186:189], v[202:205], v[94:97]
	v_mfma_f32_16x16x32_bf16 v[86:89], v[178:181], v[210:213], v[86:89]
	v_mfma_f32_16x16x32_bf16 v[78:81], v[186:189], v[210:213], v[78:81]
	v_mfma_f32_16x16x32_bf16 v[70:73], v[178:181], v[218:221], v[70:73]
	v_mfma_f32_16x16x32_bf16 v[66:69], v[186:189], v[218:221], v[66:69]
	s_setprio 0
	s_barrier
	s_add_i32 s2, s53, s34
	v_lshl_add_u64 v[144:145], v[144:145], 0, s[6:7]
	s_mov_b32 m0, s2
	ds_read_b128 v[190:193], v153 offset:49152
	ds_read_b128 v[194:197], v153 offset:50176
	ds_read_b128 v[198:201], v153 offset:51200
	ds_read_b128 v[202:205], v153 offset:52224
	ds_read_b128 v[206:209], v153 offset:53248
	ds_read_b128 v[210:213], v153 offset:54272
	ds_read_b128 v[214:217], v153 offset:55296
	ds_read_b128 v[218:221], v153 offset:56320
	global_load_lds_dwordx4 v[144:145], off
	s_add_i32 m0, s2, 0x2000
	s_add_u32 s2, s28, 0x40080
	v_lshl_add_u64 v[144:145], v[174:175], 0, s[6:7]
	s_addc_u32 s3, s29, 0
	s_add_i32 s28, s54, s34
	global_load_lds_dwordx4 v[144:145], off
	v_lshl_add_u64 v[144:145], s[2:3], 0, v[134:135]
	s_mov_b32 m0, s28
	s_nop 0
	global_load_lds_dwordx4 v[144:145], off
	v_lshl_add_u64 v[144:145], s[2:3], 0, v[130:131]
	s_add_i32 m0, s28, 0x2000
	s_nop 0
	global_load_lds_dwordx4 v[144:145], off
	v_lshl_add_u64 v[144:145], v[222:223], 0, s[6:7]
	s_mov_b32 m0, s41
	s_nop 0
	global_load_lds_dwordx4 v[144:145], off
	v_lshl_add_u64 v[144:145], v[224:225], 0, s[6:7]
	s_mov_b32 m0, s42
	s_nop 0
	global_load_lds_dwordx4 v[144:145], off
	s_waitcnt vmcnt(8)
	s_waitcnt lgkmcnt(0)
	s_barrier
	s_setprio 1
	s_waitcnt lgkmcnt(0)
	v_mfma_f32_16x16x32_bf16 v[62:65], v[154:157], v[190:193], v[62:65]
	v_mfma_f32_16x16x32_bf16 v[58:61], v[162:165], v[190:193], v[58:61]
	v_mfma_f32_16x16x32_bf16 v[50:53], v[154:157], v[198:201], v[50:53]
	v_mfma_f32_16x16x32_bf16 v[42:45], v[162:165], v[198:201], v[42:45]
	v_mfma_f32_16x16x32_bf16 v[34:37], v[154:157], v[206:209], v[34:37]
	v_mfma_f32_16x16x32_bf16 v[26:29], v[162:165], v[206:209], v[26:29]
	v_mfma_f32_16x16x32_bf16 v[18:21], v[154:157], v[214:217], v[18:21]
	v_mfma_f32_16x16x32_bf16 v[10:13], v[162:165], v[214:217], v[10:13]
	v_mfma_f32_16x16x32_bf16 v[62:65], v[158:161], v[194:197], v[62:65]
	v_mfma_f32_16x16x32_bf16 v[58:61], v[166:169], v[194:197], v[58:61]
	v_mfma_f32_16x16x32_bf16 v[50:53], v[158:161], v[202:205], v[50:53]
	v_mfma_f32_16x16x32_bf16 v[42:45], v[166:169], v[202:205], v[42:45]
	v_mfma_f32_16x16x32_bf16 v[34:37], v[158:161], v[210:213], v[34:37]
	v_mfma_f32_16x16x32_bf16 v[26:29], v[166:169], v[210:213], v[26:29]
	v_mfma_f32_16x16x32_bf16 v[18:21], v[158:161], v[218:221], v[18:21]
	v_mfma_f32_16x16x32_bf16 v[10:13], v[166:169], v[218:221], v[10:13]
	s_setprio 0
	s_setprio 1
	v_mfma_f32_16x16x32_bf16 v[54:57], v[170:173], v[190:193], v[54:57]
	v_mfma_f32_16x16x32_bf16 v[46:49], v[182:185], v[190:193], v[46:49]
	v_mfma_f32_16x16x32_bf16 v[38:41], v[170:173], v[198:201], v[38:41]
	v_mfma_f32_16x16x32_bf16 v[30:33], v[182:185], v[198:201], v[30:33]
	v_mfma_f32_16x16x32_bf16 v[22:25], v[170:173], v[206:209], v[22:25]
	v_mfma_f32_16x16x32_bf16 v[14:17], v[182:185], v[206:209], v[14:17]
	v_mfma_f32_16x16x32_bf16 v[6:9], v[170:173], v[214:217], v[6:9]
	v_mfma_f32_16x16x32_bf16 v[2:5], v[182:185], v[214:217], v[2:5]
	v_mfma_f32_16x16x32_bf16 v[54:57], v[178:181], v[194:197], v[54:57]
	v_mfma_f32_16x16x32_bf16 v[46:49], v[186:189], v[194:197], v[46:49]
	v_mfma_f32_16x16x32_bf16 v[38:41], v[178:181], v[202:205], v[38:41]
	v_mfma_f32_16x16x32_bf16 v[30:33], v[186:189], v[202:205], v[30:33]
	v_mfma_f32_16x16x32_bf16 v[22:25], v[178:181], v[210:213], v[22:25]
	v_mfma_f32_16x16x32_bf16 v[14:17], v[186:189], v[210:213], v[14:17]
	v_mfma_f32_16x16x32_bf16 v[6:9], v[178:181], v[218:221], v[6:9]
	v_mfma_f32_16x16x32_bf16 v[2:5], v[186:189], v[218:221], v[2:5]
	s_setprio 0
	s_barrier
	s_add_i32 s52, s52, 2
	s_add_u32 s26, s26, 0x100
	s_addc_u32 s27, s27, 0
	s_add_u32 s50, s50, 0x100
	s_addc_u32 s51, s51, 0
	s_cmp_gt_u32 s52, 13
	s_cbranch_scc0 .LBB0_555
	s_branch .Lpk555_exit
	s_branch .LBB0_555
	.p2align 6

.LBB0_645:
	v_and_b32_e32 v14, 15, v0
	v_lshlrev_b32_e32 v15, 1, v144
	v_lshlrev_b32_e32 v16, 2, v0
	v_lshl_or_b32 v145, s9, 6, v14
	v_lshl_or_b32 v14, v14, 6, v15
	s_lshl_b32 s9, s9, 13
	v_and_b32_e32 v16, 32, v16
	s_lshl_b32 s8, s8, 5
	v_bitop3_b32 v14, v14, s9, v16 bitop3:0xde
	s_and_b32 s21, s8, 0x60
	v_lshlrev_b32_e32 v16, 6, v0
	s_movk_i32 s8, 0x3c0
	v_and_or_b32 v15, v16, s8, v15
	s_lshl_b32 s8, s21, 7
	v_and_b32_e32 v16, 32, v73
	v_bitop3_b32 v15, s8, v15, v16 bitop3:0xf6
	s_mov_b64 s[8:9], 0x80
	s_add_i32 m0, s18, 0x18000
	v_lshl_add_u64 v[8:9], v[8:9], 0, s[8:9]
	s_waitcnt vmcnt(2)
	s_barrier
	global_load_lds_dwordx4 v[8:9], off
	v_lshl_add_u64 v[6:7], v[6:7], 0, s[8:9]
	s_add_i32 m0, s18, 0x1a000
	s_add_i32 s22, s18, 0x8000
	s_add_i32 s23, s18, 0xa000
	global_load_lds_dwordx4 v[6:7], off
	v_lshl_add_u64 v[4:5], v[4:5], 0, s[8:9]
	s_mov_b32 m0, s22
	s_add_u32 s10, s4, 0x40080
	global_load_lds_dwordx4 v[4:5], off
	v_lshl_add_u64 v[2:3], v[2:3], 0, s[8:9]
	s_mov_b32 m0, s23
	s_addc_u32 s11, s5, 0
	global_load_lds_dwordx4 v[2:3], off
	s_add_i32 m0, s18, 0x1c000
	v_lshl_add_u64 v[2:3], s[10:11], 0, v[134:135]
	global_load_lds_dwordx4 v[2:3], off
	v_lshl_add_u64 v[2:3], s[10:11], 0, v[130:131]
	s_add_i32 m0, s18, 0x1e000
	v_lshlrev_b32_e32 v4, 11, v13
	global_load_lds_dwordx4 v[2:3], off
	v_lshlrev_b32_e32 v2, 15, v143
	s_add_u32 s10, s78, s2
	v_or3_b32 v2, v11, v2, v4
	s_addc_u32 s11, s79, s3
	v_add_u32_e32 v2, v2, v12
	v_mov_b32_e32 v3, v135
	v_lshl_add_u64 v[2:3], s[10:11], 0, v[2:3]
	s_mov_b64 s[2:3], 0x3440080
	v_lshl_add_u64 v[138:139], v[2:3], 0, s[2:3]
	v_lshlrev_b32_e32 v2, 4, v10
	v_and_b32_e32 v2, 0x38000, v2
	v_or3_b32 v2, v11, v2, v4
	v_add_u32_e32 v2, v2, v12
	v_mov_b32_e32 v3, v135
	v_lshl_add_u64 v[2:3], s[10:11], 0, v[2:3]
	v_lshl_add_u64 v[140:141], v[2:3], 0, s[2:3]
	s_add_u32 s2, s78, s12
	s_addc_u32 s3, s79, 0
	s_add_u32 s24, s2, 0x2e00100
	s_waitcnt vmcnt(6)
	s_addc_u32 s25, s3, 0
	s_add_i32 s29, 0, 0x10000
	s_add_i32 s31, 0, 0x14000
	s_add_i32 s35, 0, 0x18000
	s_add_i32 s37, 0, 0x1c000
	v_add_u32_e32 v146, s29, v15
	v_add_u32_e32 v147, s31, v15
	s_add_i32 s29, s29, s14
	s_add_i32 s31, s31, s14
	v_add_u32_e32 v149, s35, v15
	v_add_u32_e32 v150, s37, v15
	s_add_i32 s35, s35, s14
	s_add_i32 s37, s37, s14
	s_mov_b32 s26, -2
	s_mov_b64 s[12:13], 0
	v_add_u32_e32 v148, 0, v14
	s_add_i32 s27, s18, 0xc000
	s_add_i32 s28, s18, 0xe000
	s_add_i32 s30, s29, 0x2000
	s_add_i32 s34, s31, 0x2000
	s_add_i32 s36, s35, 0x2000
	s_add_i32 s38, s37, 0x2000
	v_mov_b32_e32 v2, v135
	v_mov_b32_e32 v3, v135
	v_mov_b32_e32 v4, v135
	v_mov_b32_e32 v5, v135
	v_mov_b32_e32 v6, v135
	v_mov_b32_e32 v7, v135
	v_mov_b32_e32 v8, v135
	v_mov_b32_e32 v9, v135
	v_mov_b32_e32 v14, v135
	v_mov_b32_e32 v15, v135
	v_mov_b32_e32 v16, v135
	v_mov_b32_e32 v17, v135
	s_waitcnt vmcnt(0)
	v_mov_b32_e32 v22, v135
	v_mov_b32_e32 v23, v135
	v_mov_b32_e32 v24, v135
	v_mov_b32_e32 v25, v135
	v_mov_b32_e32 v30, v135
	v_mov_b32_e32 v31, v135
	v_mov_b32_e32 v32, v135
	v_mov_b32_e32 v33, v135
	v_mov_b32_e32 v38, v135
	v_mov_b32_e32 v39, v135
	v_mov_b32_e32 v40, v135
	v_mov_b32_e32 v41, v135
	v_mov_b32_e32 v46, v135
	v_mov_b32_e32 v47, v135
	v_mov_b32_e32 v48, v135
	v_mov_b32_e32 v49, v135
	v_mov_b32_e32 v54, v135
	v_mov_b32_e32 v55, v135
	v_mov_b32_e32 v56, v135
	v_mov_b32_e32 v57, v135
	v_mov_b32_e32 v10, v135
	v_mov_b32_e32 v11, v135
	v_mov_b32_e32 v12, v135
	v_mov_b32_e32 v13, v135
	v_mov_b32_e32 v18, v135
	v_mov_b32_e32 v19, v135
	v_mov_b32_e32 v20, v135
	v_mov_b32_e32 v21, v135
	v_mov_b32_e32 v26, v135
	v_mov_b32_e32 v27, v135
	v_mov_b32_e32 v28, v135
	v_mov_b32_e32 v29, v135
	v_mov_b32_e32 v34, v135
	v_mov_b32_e32 v35, v135
	v_mov_b32_e32 v36, v135
	v_mov_b32_e32 v37, v135
	v_mov_b32_e32 v42, v135
	v_mov_b32_e32 v43, v135
	v_mov_b32_e32 v44, v135
	v_mov_b32_e32 v45, v135
	v_mov_b32_e32 v50, v135
	v_mov_b32_e32 v51, v135
	v_mov_b32_e32 v52, v135
	v_mov_b32_e32 v53, v135
	v_mov_b32_e32 v58, v135
	v_mov_b32_e32 v59, v135
	v_mov_b32_e32 v60, v135
	v_mov_b32_e32 v61, v135
	v_mov_b32_e32 v62, v135
	v_mov_b32_e32 v63, v135
	v_mov_b32_e32 v64, v135
	v_mov_b32_e32 v65, v135
	v_mov_b32_e32 v66, v135
	v_mov_b32_e32 v67, v135
	v_mov_b32_e32 v68, v135
	v_mov_b32_e32 v69, v135
	v_mov_b32_e32 v70, v135
	v_mov_b32_e32 v71, v135
	v_mov_b32_e32 v72, v135
	v_mov_b32_e32 v73, v135
	v_mov_b32_e32 v78, v135
	v_mov_b32_e32 v79, v135
	v_mov_b32_e32 v80, v135
	v_mov_b32_e32 v81, v135
	v_mov_b32_e32 v86, v135
	v_mov_b32_e32 v87, v135
	v_mov_b32_e32 v88, v135
	v_mov_b32_e32 v89, v135
	v_mov_b32_e32 v94, v135
	v_mov_b32_e32 v95, v135
	v_mov_b32_e32 v96, v135
	v_mov_b32_e32 v97, v135
	v_mov_b32_e32 v102, v135
	v_mov_b32_e32 v103, v135
	v_mov_b32_e32 v104, v135
	v_mov_b32_e32 v105, v135
	v_mov_b32_e32 v110, v135
	v_mov_b32_e32 v111, v135
	v_mov_b32_e32 v112, v135
	v_mov_b32_e32 v113, v135
	v_mov_b32_e32 v118, v135
	v_mov_b32_e32 v119, v135
	v_mov_b32_e32 v120, v135
	v_mov_b32_e32 v121, v135
	v_mov_b32_e32 v74, v135
	v_mov_b32_e32 v75, v135
	v_mov_b32_e32 v76, v135
	v_mov_b32_e32 v77, v135
	v_mov_b32_e32 v82, v135
	v_mov_b32_e32 v83, v135
	v_mov_b32_e32 v84, v135
	v_mov_b32_e32 v85, v135
	v_mov_b32_e32 v90, v135
	v_mov_b32_e32 v91, v135
	v_mov_b32_e32 v92, v135
	v_mov_b32_e32 v93, v135
	v_mov_b32_e32 v98, v135
	v_mov_b32_e32 v99, v135
	v_mov_b32_e32 v100, v135
	v_mov_b32_e32 v101, v135
	v_mov_b32_e32 v106, v135
	v_mov_b32_e32 v107, v135
	v_mov_b32_e32 v108, v135
	v_mov_b32_e32 v109, v135
	v_mov_b32_e32 v114, v135
	v_mov_b32_e32 v115, v135
	v_mov_b32_e32 v116, v135
	v_mov_b32_e32 v117, v135
	v_mov_b32_e32 v122, v135
	v_mov_b32_e32 v123, v135
	v_mov_b32_e32 v124, v135
	v_mov_b32_e32 v125, v135
	v_mov_b32_e32 v126, v135
	v_mov_b32_e32 v127, v135
	v_mov_b32_e32 v128, v135
	v_mov_b32_e32 v129, v135
	s_barrier
	s_branch .LBB0_646
	.p2align 6

.LBB0_1097:
	s_lshl_b64 s[2:3], s[18:19], 1
	s_add_u32 s24, s90, s2
	s_addc_u32 s25, s91, s3
	s_and_b64 s[2:3], s[22:23], exec
	s_cselect_b32 s15, s25, s31
	s_cselect_b32 s17, s24, s30
	s_lshl_b64 s[2:3], s[20:21], 1
	s_add_u32 s26, s37, s2
	s_addc_u32 s27, s38, s3
	s_and_b64 s[2:3], s[22:23], exec
	s_cselect_b32 s52, s27, s35
	s_cselect_b32 s53, s26, s34
	s_add_u32 s30, s30, 0x40080
	s_addc_u32 s31, s31, 0
	s_add_u32 s54, s34, 0x100
	s_addc_u32 s55, s35, 0
	s_mov_b32 s56, -2
	s_branch .Lpk1098_peel
	.p2align 6
.Lpk1098_peel:
	ds_read_b128 v[152:155], v148
	ds_read_b128 v[156:159], v148 offset:1024
	ds_read_b128 v[160:163], v148 offset:2048
	ds_read_b128 v[164:167], v148 offset:3072
	ds_read_b128 v[168:171], v149
	ds_read_b128 v[172:175], v149 offset:1024
	ds_read_b128 v[178:181], v149 offset:2048
	ds_read_b128 v[182:185], v149 offset:3072
	s_add_u32 s2, s30, 0xfffc0080
	s_addc_u32 s3, s31, -1
	s_cmp_eq_u32 s56, 12
	s_cselect_b32 s3, s15, s3
	s_cselect_b32 s2, s17, s2
	s_cselect_b32 s35, s52, s55
	s_cselect_b32 s34, s53, s54
	v_lshl_add_u64 v[144:145], s[30:31], 0, v[138:139]
	s_add_i32 m0, s40, 0xc000
	ds_read_b128 v[186:189], v150
	ds_read_b128 v[190:193], v150 offset:1024
	ds_read_b128 v[194:197], v150 offset:2048
	ds_read_b128 v[198:201], v150 offset:3072
	ds_read_b128 v[202:205], v150 offset:4096
	ds_read_b128 v[206:209], v150 offset:5120
	ds_read_b128 v[210:213], v150 offset:6144
	ds_read_b128 v[214:217], v150 offset:7168
	global_load_lds_dwordx4 v[144:145], off
	v_lshl_add_u64 v[144:145], s[30:31], 0, v[140:141]
	s_add_i32 m0, s40, 0xe000
	s_nop 0
	global_load_lds_dwordx4 v[144:145], off
	s_waitcnt vmcnt(8)
	s_waitcnt lgkmcnt(0)
	s_barrier
	s_setprio 1
	s_waitcnt lgkmcnt(0)
	v_mfma_f32_16x16x32_bf16 v[126:129], v[152:155], v[186:189], 0
	v_mfma_f32_16x16x32_bf16 v[122:125], v[160:163], v[186:189], 0
	v_mfma_f32_16x16x32_bf16 v[114:117], v[152:155], v[194:197], 0
	v_mfma_f32_16x16x32_bf16 v[106:109], v[160:163], v[194:197], 0
	v_mfma_f32_16x16x32_bf16 v[98:101], v[152:155], v[202:205], 0
	v_mfma_f32_16x16x32_bf16 v[90:93], v[160:163], v[202:205], 0
	v_mfma_f32_16x16x32_bf16 v[82:85], v[152:155], v[210:213], 0
	v_mfma_f32_16x16x32_bf16 v[74:77], v[160:163], v[210:213], 0
	v_mfma_f32_16x16x32_bf16 v[126:129], v[156:159], v[190:193], v[126:129]
	v_mfma_f32_16x16x32_bf16 v[122:125], v[164:167], v[190:193], v[122:125]
	v_mfma_f32_16x16x32_bf16 v[114:117], v[156:159], v[198:201], v[114:117]
	v_mfma_f32_16x16x32_bf16 v[106:109], v[164:167], v[198:201], v[106:109]
	v_mfma_f32_16x16x32_bf16 v[98:101], v[156:159], v[206:209], v[98:101]
	v_mfma_f32_16x16x32_bf16 v[90:93], v[164:167], v[206:209], v[90:93]
	v_mfma_f32_16x16x32_bf16 v[82:85], v[156:159], v[214:217], v[82:85]
	v_mfma_f32_16x16x32_bf16 v[74:77], v[164:167], v[214:217], v[74:77]
	s_setprio 0
	s_setprio 1
	v_mfma_f32_16x16x32_bf16 v[118:121], v[168:171], v[186:189], 0
	v_mfma_f32_16x16x32_bf16 v[110:113], v[178:181], v[186:189], 0
	v_mfma_f32_16x16x32_bf16 v[102:105], v[168:171], v[194:197], 0
	v_mfma_f32_16x16x32_bf16 v[94:97], v[178:181], v[194:197], 0
	v_mfma_f32_16x16x32_bf16 v[86:89], v[168:171], v[202:205], 0
	v_mfma_f32_16x16x32_bf16 v[78:81], v[178:181], v[202:205], 0
	v_mfma_f32_16x16x32_bf16 v[70:73], v[168:171], v[210:213], 0
	v_mfma_f32_16x16x32_bf16 v[66:69], v[178:181], v[210:213], 0
	v_mfma_f32_16x16x32_bf16 v[118:121], v[172:175], v[190:193], v[118:121]
	v_mfma_f32_16x16x32_bf16 v[110:113], v[182:185], v[190:193], v[110:113]
	v_mfma_f32_16x16x32_bf16 v[102:105], v[172:175], v[198:201], v[102:105]
	v_mfma_f32_16x16x32_bf16 v[94:97], v[182:185], v[198:201], v[94:97]
	v_mfma_f32_16x16x32_bf16 v[86:89], v[172:175], v[206:209], v[86:89]
	v_mfma_f32_16x16x32_bf16 v[78:81], v[182:185], v[206:209], v[78:81]
	v_mfma_f32_16x16x32_bf16 v[70:73], v[172:175], v[214:217], v[70:73]
	v_mfma_f32_16x16x32_bf16 v[66:69], v[182:185], v[214:217], v[66:69]
	s_setprio 0
	s_barrier
	s_add_i32 s57, s47, s39
	v_lshl_add_u64 v[144:145], s[34:35], 0, v[132:133]
	s_mov_b32 m0, s57
	ds_read_b128 v[186:189], v150 offset:16384
	ds_read_b128 v[190:193], v150 offset:17408
	ds_read_b128 v[194:197], v150 offset:18432
	ds_read_b128 v[198:201], v150 offset:19456
	ds_read_b128 v[202:205], v150 offset:20480
	ds_read_b128 v[206:209], v150 offset:21504
	ds_read_b128 v[210:213], v150 offset:22528
	ds_read_b128 v[214:217], v150 offset:23552
	global_load_lds_dwordx4 v[144:145], off
	s_add_i32 m0, s57, 0x2000
	s_add_u32 s58, s34, 0x40000
	v_lshl_add_u64 v[218:219], s[34:35], 0, v[136:137]
	s_addc_u32 s59, s35, 0
	s_add_i32 s57, s48, s39
	global_load_lds_dwordx4 v[218:219], off
	v_lshl_add_u64 v[220:221], s[58:59], 0, v[132:133]
	s_mov_b32 m0, s57
	v_lshl_add_u64 v[222:223], s[2:3], 0, v[134:135]
	global_load_lds_dwordx4 v[220:221], off
	v_lshl_add_u64 v[220:221], s[58:59], 0, v[136:137]
	s_add_i32 m0, s57, 0x2000
	s_nop 0
	global_load_lds_dwordx4 v[220:221], off
	v_lshl_add_u64 v[220:221], s[2:3], 0, v[130:131]
	s_mov_b32 m0, s40
	s_nop 0
	global_load_lds_dwordx4 v[220:221], off
	s_mov_b32 m0, s29
	s_nop 0
	global_load_lds_dwordx4 v[222:223], off
	s_waitcnt vmcnt(8)
	s_waitcnt lgkmcnt(0)
	s_barrier
	s_setprio 1
	s_waitcnt lgkmcnt(0)
	v_mfma_f32_16x16x32_bf16 v[62:65], v[152:155], v[186:189], 0
	v_mfma_f32_16x16x32_bf16 v[58:61], v[160:163], v[186:189], 0
	v_mfma_f32_16x16x32_bf16 v[50:53], v[152:155], v[194:197], 0
	v_mfma_f32_16x16x32_bf16 v[42:45], v[160:163], v[194:197], 0
	v_mfma_f32_16x16x32_bf16 v[34:37], v[152:155], v[202:205], 0
	v_mfma_f32_16x16x32_bf16 v[26:29], v[160:163], v[202:205], 0
	v_mfma_f32_16x16x32_bf16 v[18:21], v[152:155], v[210:213], 0
	v_mfma_f32_16x16x32_bf16 v[10:13], v[160:163], v[210:213], 0
	v_mfma_f32_16x16x32_bf16 v[62:65], v[156:159], v[190:193], v[62:65]
	v_mfma_f32_16x16x32_bf16 v[58:61], v[164:167], v[190:193], v[58:61]
	v_mfma_f32_16x16x32_bf16 v[50:53], v[156:159], v[198:201], v[50:53]
	v_mfma_f32_16x16x32_bf16 v[42:45], v[164:167], v[198:201], v[42:45]
	v_mfma_f32_16x16x32_bf16 v[34:37], v[156:159], v[206:209], v[34:37]
	v_mfma_f32_16x16x32_bf16 v[26:29], v[164:167], v[206:209], v[26:29]
	v_mfma_f32_16x16x32_bf16 v[18:21], v[156:159], v[214:217], v[18:21]
	v_mfma_f32_16x16x32_bf16 v[10:13], v[164:167], v[214:217], v[10:13]
	s_setprio 0
	s_setprio 1
	v_mfma_f32_16x16x32_bf16 v[54:57], v[168:171], v[186:189], 0
	v_mfma_f32_16x16x32_bf16 v[46:49], v[178:181], v[186:189], 0
	v_mfma_f32_16x16x32_bf16 v[38:41], v[168:171], v[194:197], 0
	v_mfma_f32_16x16x32_bf16 v[30:33], v[178:181], v[194:197], 0
	v_mfma_f32_16x16x32_bf16 v[22:25], v[168:171], v[202:205], 0
	v_mfma_f32_16x16x32_bf16 v[14:17], v[178:181], v[202:205], 0
	v_mfma_f32_16x16x32_bf16 v[6:9], v[168:171], v[210:213], 0
	v_mfma_f32_16x16x32_bf16 v[2:5], v[178:181], v[210:213], 0
	v_mfma_f32_16x16x32_bf16 v[54:57], v[172:175], v[190:193], v[54:57]
	v_mfma_f32_16x16x32_bf16 v[46:49], v[182:185], v[190:193], v[46:49]
	v_mfma_f32_16x16x32_bf16 v[38:41], v[172:175], v[198:201], v[38:41]
	v_mfma_f32_16x16x32_bf16 v[30:33], v[182:185], v[198:201], v[30:33]
	v_mfma_f32_16x16x32_bf16 v[22:25], v[172:175], v[206:209], v[22:25]
	v_mfma_f32_16x16x32_bf16 v[14:17], v[182:185], v[206:209], v[14:17]
	v_mfma_f32_16x16x32_bf16 v[6:9], v[172:175], v[214:217], v[6:9]
	v_mfma_f32_16x16x32_bf16 v[2:5], v[182:185], v[214:217], v[2:5]
	s_setprio 0
	s_barrier
	s_add_i32 s57, 0, 0x18000
	v_add_u32_e32 v151, s57, v146
	s_add_i32 s58, 0, 0x1c000
	ds_read_b128 v[152:155], v151
	ds_read_b128 v[156:159], v151 offset:1024
	ds_read_b128 v[160:163], v151 offset:2048
	ds_read_b128 v[164:167], v151 offset:3072
	v_add_u32_e32 v151, s58, v146
	ds_read_b128 v[168:171], v151
	ds_read_b128 v[172:175], v151 offset:1024
	ds_read_b128 v[178:181], v151 offset:2048
	ds_read_b128 v[182:185], v151 offset:3072
	s_add_u32 s2, s2, 0x40000
	s_addc_u32 s3, s3, 0
	s_mov_b32 m0, s41
	v_lshl_add_u64 v[224:225], s[2:3], 0, v[130:131]
	ds_read_b128 v[186:189], v150 offset:32768
	ds_read_b128 v[190:193], v150 offset:33792
	ds_read_b128 v[194:197], v150 offset:34816
	ds_read_b128 v[198:201], v150 offset:35840
	ds_read_b128 v[202:205], v150 offset:36864
	ds_read_b128 v[206:209], v150 offset:37888
	ds_read_b128 v[210:213], v150 offset:38912
	ds_read_b128 v[214:217], v150 offset:39936
	global_load_lds_dwordx4 v[224:225], off
	v_lshl_add_u64 v[224:225], s[2:3], 0, v[134:135]
	s_mov_b32 m0, s42
	s_nop 0
	global_load_lds_dwordx4 v[224:225], off
	s_waitcnt vmcnt(8)
	s_waitcnt lgkmcnt(0)
	s_barrier
	s_setprio 1
	s_waitcnt lgkmcnt(0)
	v_mfma_f32_16x16x32_bf16 v[126:129], v[152:155], v[186:189], v[126:129]
	v_mfma_f32_16x16x32_bf16 v[122:125], v[160:163], v[186:189], v[122:125]
	v_mfma_f32_16x16x32_bf16 v[114:117], v[152:155], v[194:197], v[114:117]
	v_mfma_f32_16x16x32_bf16 v[106:109], v[160:163], v[194:197], v[106:109]
	v_mfma_f32_16x16x32_bf16 v[98:101], v[152:155], v[202:205], v[98:101]
	v_mfma_f32_16x16x32_bf16 v[90:93], v[160:163], v[202:205], v[90:93]
	v_mfma_f32_16x16x32_bf16 v[82:85], v[152:155], v[210:213], v[82:85]
	v_mfma_f32_16x16x32_bf16 v[74:77], v[160:163], v[210:213], v[74:77]
	v_mfma_f32_16x16x32_bf16 v[126:129], v[156:159], v[190:193], v[126:129]
	v_mfma_f32_16x16x32_bf16 v[122:125], v[164:167], v[190:193], v[122:125]
	v_mfma_f32_16x16x32_bf16 v[114:117], v[156:159], v[198:201], v[114:117]
	v_mfma_f32_16x16x32_bf16 v[106:109], v[164:167], v[198:201], v[106:109]
	v_mfma_f32_16x16x32_bf16 v[98:101], v[156:159], v[206:209], v[98:101]
	v_mfma_f32_16x16x32_bf16 v[90:93], v[164:167], v[206:209], v[90:93]
	v_mfma_f32_16x16x32_bf16 v[82:85], v[156:159], v[214:217], v[82:85]
	v_mfma_f32_16x16x32_bf16 v[74:77], v[164:167], v[214:217], v[74:77]
	s_setprio 0
	s_setprio 1
	v_mfma_f32_16x16x32_bf16 v[118:121], v[168:171], v[186:189], v[118:121]
	v_mfma_f32_16x16x32_bf16 v[110:113], v[178:181], v[186:189], v[110:113]
	v_mfma_f32_16x16x32_bf16 v[102:105], v[168:171], v[194:197], v[102:105]
	v_mfma_f32_16x16x32_bf16 v[94:97], v[178:181], v[194:197], v[94:97]
	v_mfma_f32_16x16x32_bf16 v[86:89], v[168:171], v[202:205], v[86:89]
	v_mfma_f32_16x16x32_bf16 v[78:81], v[178:181], v[202:205], v[78:81]
	v_mfma_f32_16x16x32_bf16 v[70:73], v[168:171], v[210:213], v[70:73]
	v_mfma_f32_16x16x32_bf16 v[66:69], v[178:181], v[210:213], v[66:69]
	v_mfma_f32_16x16x32_bf16 v[118:121], v[172:175], v[190:193], v[118:121]
	v_mfma_f32_16x16x32_bf16 v[110:113], v[182:185], v[190:193], v[110:113]
	v_mfma_f32_16x16x32_bf16 v[102:105], v[172:175], v[198:201], v[102:105]
	v_mfma_f32_16x16x32_bf16 v[94:97], v[182:185], v[198:201], v[94:97]
	v_mfma_f32_16x16x32_bf16 v[86:89], v[172:175], v[206:209], v[86:89]
	v_mfma_f32_16x16x32_bf16 v[78:81], v[182:185], v[206:209], v[78:81]
	v_mfma_f32_16x16x32_bf16 v[70:73], v[172:175], v[214:217], v[70:73]
	v_mfma_f32_16x16x32_bf16 v[66:69], v[182:185], v[214:217], v[66:69]
	s_setprio 0
	s_barrier
	s_add_i32 s2, s57, s39
	v_lshl_add_u64 v[144:145], v[144:145], 0, s[6:7]
	s_mov_b32 m0, s2
	ds_read_b128 v[186:189], v150 offset:49152
	ds_read_b128 v[190:193], v150 offset:50176
	ds_read_b128 v[194:197], v150 offset:51200
	ds_read_b128 v[198:201], v150 offset:52224
	ds_read_b128 v[202:205], v150 offset:53248
	ds_read_b128 v[206:209], v150 offset:54272
	ds_read_b128 v[210:213], v150 offset:55296
	ds_read_b128 v[214:217], v150 offset:56320
	global_load_lds_dwordx4 v[144:145], off
	s_add_i32 m0, s2, 0x2000
	s_add_u32 s2, s34, 0x40080
	v_lshl_add_u64 v[144:145], v[218:219], 0, s[6:7]
	s_addc_u32 s3, s35, 0
	s_add_i32 s34, s58, s39
	global_load_lds_dwordx4 v[144:145], off
	v_lshl_add_u64 v[144:145], s[2:3], 0, v[132:133]
	s_mov_b32 m0, s34
	s_nop 0
	global_load_lds_dwordx4 v[144:145], off
	v_lshl_add_u64 v[144:145], s[2:3], 0, v[136:137]
	s_add_i32 m0, s34, 0x2000
	s_nop 0
	global_load_lds_dwordx4 v[144:145], off
	v_lshl_add_u64 v[144:145], v[220:221], 0, s[6:7]
	s_mov_b32 m0, s44
	s_nop 0
	global_load_lds_dwordx4 v[144:145], off
	v_lshl_add_u64 v[144:145], v[222:223], 0, s[6:7]
	s_mov_b32 m0, s45
	s_nop 0
	global_load_lds_dwordx4 v[144:145], off
	s_waitcnt vmcnt(8)
	s_waitcnt lgkmcnt(0)
	s_barrier
	s_setprio 1
	s_waitcnt lgkmcnt(0)
	v_mfma_f32_16x16x32_bf16 v[62:65], v[152:155], v[186:189], v[62:65]
	v_mfma_f32_16x16x32_bf16 v[58:61], v[160:163], v[186:189], v[58:61]
	v_mfma_f32_16x16x32_bf16 v[50:53], v[152:155], v[194:197], v[50:53]
	v_mfma_f32_16x16x32_bf16 v[42:45], v[160:163], v[194:197], v[42:45]
	v_mfma_f32_16x16x32_bf16 v[34:37], v[152:155], v[202:205], v[34:37]
	v_mfma_f32_16x16x32_bf16 v[26:29], v[160:163], v[202:205], v[26:29]
	v_mfma_f32_16x16x32_bf16 v[18:21], v[152:155], v[210:213], v[18:21]
	v_mfma_f32_16x16x32_bf16 v[10:13], v[160:163], v[210:213], v[10:13]
	v_mfma_f32_16x16x32_bf16 v[62:65], v[156:159], v[190:193], v[62:65]
	v_mfma_f32_16x16x32_bf16 v[58:61], v[164:167], v[190:193], v[58:61]
	v_mfma_f32_16x16x32_bf16 v[50:53], v[156:159], v[198:201], v[50:53]
	v_mfma_f32_16x16x32_bf16 v[42:45], v[164:167], v[198:201], v[42:45]
	v_mfma_f32_16x16x32_bf16 v[34:37], v[156:159], v[206:209], v[34:37]
	v_mfma_f32_16x16x32_bf16 v[26:29], v[164:167], v[206:209], v[26:29]
	v_mfma_f32_16x16x32_bf16 v[18:21], v[156:159], v[214:217], v[18:21]
	v_mfma_f32_16x16x32_bf16 v[10:13], v[164:167], v[214:217], v[10:13]
	s_setprio 0
	s_setprio 1
	v_mfma_f32_16x16x32_bf16 v[54:57], v[168:171], v[186:189], v[54:57]
	v_mfma_f32_16x16x32_bf16 v[46:49], v[178:181], v[186:189], v[46:49]
	v_mfma_f32_16x16x32_bf16 v[38:41], v[168:171], v[194:197], v[38:41]
	v_mfma_f32_16x16x32_bf16 v[30:33], v[178:181], v[194:197], v[30:33]
	v_mfma_f32_16x16x32_bf16 v[22:25], v[168:171], v[202:205], v[22:25]
	v_mfma_f32_16x16x32_bf16 v[14:17], v[178:181], v[202:205], v[14:17]
	v_mfma_f32_16x16x32_bf16 v[6:9], v[168:171], v[210:213], v[6:9]
	v_mfma_f32_16x16x32_bf16 v[2:5], v[178:181], v[210:213], v[2:5]
	v_mfma_f32_16x16x32_bf16 v[54:57], v[172:175], v[190:193], v[54:57]
	v_mfma_f32_16x16x32_bf16 v[46:49], v[182:185], v[190:193], v[46:49]
	v_mfma_f32_16x16x32_bf16 v[38:41], v[172:175], v[198:201], v[38:41]
	v_mfma_f32_16x16x32_bf16 v[30:33], v[182:185], v[198:201], v[30:33]
	v_mfma_f32_16x16x32_bf16 v[22:25], v[172:175], v[206:209], v[22:25]
	v_mfma_f32_16x16x32_bf16 v[14:17], v[182:185], v[206:209], v[14:17]
	v_mfma_f32_16x16x32_bf16 v[6:9], v[172:175], v[214:217], v[6:9]
	v_mfma_f32_16x16x32_bf16 v[2:5], v[182:185], v[214:217], v[2:5]
	s_setprio 0
	s_barrier
	s_add_i32 s56, s56, 2
	s_add_u32 s30, s30, 0x100
	s_addc_u32 s31, s31, 0
	s_add_u32 s54, s54, 0x100
	s_addc_u32 s55, s55, 0
	s_cmp_gt_u32 s56, 13
	s_cbranch_scc0 .LBB0_1098
	s_branch .Lpk1098_exit
	s_branch .LBB0_1098
	.p2align 6

.LBB0_1178:
	s_lshl_b64 s[2:3], s[22:23], 1
	v_readlane_b32 s28, v253, 52
	v_readlane_b32 s29, v253, 53
	s_add_u32 s28, s28, s2
	s_addc_u32 s29, s29, s3
	s_and_b64 s[2:3], s[26:27], exec
	s_cselect_b32 s19, s29, s37
	s_cselect_b32 s21, s28, s36
	s_lshl_b64 s[2:3], s[24:25], 1
	s_add_u32 s30, s35, s2
	s_addc_u32 s31, s40, s3
	s_and_b64 s[2:3], s[26:27], exec
	s_cselect_b32 s57, s31, s39
	s_cselect_b32 s58, s30, s38
	s_add_u32 s36, s36, 0x40080
	s_addc_u32 s37, s37, 0
	s_add_u32 s59, s38, 0x100
	s_addc_u32 s60, s39, 0
	s_mov_b32 s61, -2
	s_branch .Lpk1179_peel
	.p2align 6
.Lpk1179_peel:
	ds_read_b128 v[144:147], v158
	ds_read_b128 v[164:167], v158 offset:1024
	ds_read_b128 v[168:171], v158 offset:2048
	ds_read_b128 v[172:175], v158 offset:3072
	ds_read_b128 v[178:181], v159
	ds_read_b128 v[182:185], v159 offset:1024
	ds_read_b128 v[186:189], v159 offset:2048
	ds_read_b128 v[190:193], v159 offset:3072
	s_add_u32 s2, s36, 0xfffc0080
	s_addc_u32 s3, s37, -1
	s_cmp_eq_u32 s61, 12
	s_cselect_b32 s3, s19, s3
	s_cselect_b32 s2, s21, s2
	s_cselect_b32 s39, s57, s60
	s_cselect_b32 s38, s58, s59
	v_lshl_add_u64 v[226:227], s[36:37], 0, v[138:139]
	s_add_i32 m0, s42, 0xc000
	ds_read_b128 v[194:197], v160
	ds_read_b128 v[198:201], v160 offset:1024
	ds_read_b128 v[202:205], v160 offset:2048
	ds_read_b128 v[206:209], v160 offset:3072
	ds_read_b128 v[210:213], v160 offset:4096
	ds_read_b128 v[214:217], v160 offset:5120
	ds_read_b128 v[218:221], v160 offset:6144
	ds_read_b128 v[222:225], v160 offset:7168
	global_load_lds_dwordx4 v[226:227], off
	v_lshl_add_u64 v[226:227], s[36:37], 0, v[140:141]
	s_add_i32 m0, s42, 0xe000
	s_nop 0
	global_load_lds_dwordx4 v[226:227], off
	s_waitcnt vmcnt(8)
	s_waitcnt lgkmcnt(0)
	s_barrier
	s_setprio 1
	s_waitcnt lgkmcnt(0)
	v_mfma_f32_16x16x32_bf16 v[126:129], v[144:147], v[194:197], 0
	v_mfma_f32_16x16x32_bf16 v[122:125], v[168:171], v[194:197], 0
	v_mfma_f32_16x16x32_bf16 v[114:117], v[144:147], v[202:205], 0
	v_mfma_f32_16x16x32_bf16 v[106:109], v[168:171], v[202:205], 0
	v_mfma_f32_16x16x32_bf16 v[98:101], v[144:147], v[210:213], 0
	v_mfma_f32_16x16x32_bf16 v[90:93], v[168:171], v[210:213], 0
	v_mfma_f32_16x16x32_bf16 v[82:85], v[144:147], v[218:221], 0
	v_mfma_f32_16x16x32_bf16 v[74:77], v[168:171], v[218:221], 0
	v_mfma_f32_16x16x32_bf16 v[126:129], v[164:167], v[198:201], v[126:129]
	v_mfma_f32_16x16x32_bf16 v[122:125], v[172:175], v[198:201], v[122:125]
	v_mfma_f32_16x16x32_bf16 v[114:117], v[164:167], v[206:209], v[114:117]
	v_mfma_f32_16x16x32_bf16 v[106:109], v[172:175], v[206:209], v[106:109]
	v_mfma_f32_16x16x32_bf16 v[98:101], v[164:167], v[214:217], v[98:101]
	v_mfma_f32_16x16x32_bf16 v[90:93], v[172:175], v[214:217], v[90:93]
	v_mfma_f32_16x16x32_bf16 v[82:85], v[164:167], v[222:225], v[82:85]
	v_mfma_f32_16x16x32_bf16 v[74:77], v[172:175], v[222:225], v[74:77]
	s_setprio 0
	s_setprio 1
	v_mfma_f32_16x16x32_bf16 v[118:121], v[178:181], v[194:197], 0
	v_mfma_f32_16x16x32_bf16 v[110:113], v[186:189], v[194:197], 0
	v_mfma_f32_16x16x32_bf16 v[102:105], v[178:181], v[202:205], 0
	v_mfma_f32_16x16x32_bf16 v[94:97], v[186:189], v[202:205], 0
	v_mfma_f32_16x16x32_bf16 v[86:89], v[178:181], v[210:213], 0
	v_mfma_f32_16x16x32_bf16 v[78:81], v[186:189], v[210:213], 0
	v_mfma_f32_16x16x32_bf16 v[70:73], v[178:181], v[218:221], 0
	v_mfma_f32_16x16x32_bf16 v[66:69], v[186:189], v[218:221], 0
	v_mfma_f32_16x16x32_bf16 v[118:121], v[182:185], v[198:201], v[118:121]
	v_mfma_f32_16x16x32_bf16 v[110:113], v[190:193], v[198:201], v[110:113]
	v_mfma_f32_16x16x32_bf16 v[102:105], v[182:185], v[206:209], v[102:105]
	v_mfma_f32_16x16x32_bf16 v[94:97], v[190:193], v[206:209], v[94:97]
	v_mfma_f32_16x16x32_bf16 v[86:89], v[182:185], v[214:217], v[86:89]
	v_mfma_f32_16x16x32_bf16 v[78:81], v[190:193], v[214:217], v[78:81]
	v_mfma_f32_16x16x32_bf16 v[70:73], v[182:185], v[222:225], v[70:73]
	v_mfma_f32_16x16x32_bf16 v[66:69], v[190:193], v[222:225], v[66:69]
	s_setprio 0
	s_barrier
	s_add_i32 s62, s51, s41
	v_lshl_add_u64 v[226:227], s[38:39], 0, v[132:133]
	s_mov_b32 m0, s62
	ds_read_b128 v[194:197], v160 offset:16384
	ds_read_b128 v[198:201], v160 offset:17408
	ds_read_b128 v[202:205], v160 offset:18432
	ds_read_b128 v[206:209], v160 offset:19456
	ds_read_b128 v[210:213], v160 offset:20480
	ds_read_b128 v[214:217], v160 offset:21504
	ds_read_b128 v[218:221], v160 offset:22528
	ds_read_b128 v[222:225], v160 offset:23552
	global_load_lds_dwordx4 v[226:227], off
	s_add_i32 m0, s62, 0x2000
	s_add_u32 s62, s38, 0x40000
	v_lshl_add_u64 v[228:229], s[38:39], 0, v[136:137]
	s_addc_u32 s63, s39, 0
	s_add_i32 s64, s52, s41
	global_load_lds_dwordx4 v[228:229], off
	v_lshl_add_u64 v[230:231], s[62:63], 0, v[132:133]
	s_mov_b32 m0, s64
	v_lshl_add_u64 v[232:233], s[2:3], 0, v[134:135]
	global_load_lds_dwordx4 v[230:231], off
	v_lshl_add_u64 v[230:231], s[62:63], 0, v[136:137]
	s_add_i32 m0, s64, 0x2000
	s_nop 0
	global_load_lds_dwordx4 v[230:231], off
	v_lshl_add_u64 v[230:231], s[2:3], 0, v[130:131]
	s_mov_b32 m0, s42
	s_nop 0
	global_load_lds_dwordx4 v[230:231], off
	s_mov_b32 m0, s43
	s_nop 0
	global_load_lds_dwordx4 v[232:233], off
	s_waitcnt vmcnt(8)
	s_waitcnt lgkmcnt(0)
	s_barrier
	s_setprio 1
	s_waitcnt lgkmcnt(0)
	v_mfma_f32_16x16x32_bf16 v[62:65], v[144:147], v[194:197], 0
	v_mfma_f32_16x16x32_bf16 v[58:61], v[168:171], v[194:197], 0
	v_mfma_f32_16x16x32_bf16 v[50:53], v[144:147], v[202:205], 0
	v_mfma_f32_16x16x32_bf16 v[42:45], v[168:171], v[202:205], 0
	v_mfma_f32_16x16x32_bf16 v[34:37], v[144:147], v[210:213], 0
	v_mfma_f32_16x16x32_bf16 v[26:29], v[168:171], v[210:213], 0
	v_mfma_f32_16x16x32_bf16 v[18:21], v[144:147], v[218:221], 0
	v_mfma_f32_16x16x32_bf16 v[10:13], v[168:171], v[218:221], 0
	v_mfma_f32_16x16x32_bf16 v[62:65], v[164:167], v[198:201], v[62:65]
	v_mfma_f32_16x16x32_bf16 v[58:61], v[172:175], v[198:201], v[58:61]
	v_mfma_f32_16x16x32_bf16 v[50:53], v[164:167], v[206:209], v[50:53]
	v_mfma_f32_16x16x32_bf16 v[42:45], v[172:175], v[206:209], v[42:45]
	v_mfma_f32_16x16x32_bf16 v[34:37], v[164:167], v[214:217], v[34:37]
	v_mfma_f32_16x16x32_bf16 v[26:29], v[172:175], v[214:217], v[26:29]
	v_mfma_f32_16x16x32_bf16 v[18:21], v[164:167], v[222:225], v[18:21]
	v_mfma_f32_16x16x32_bf16 v[10:13], v[172:175], v[222:225], v[10:13]
	s_setprio 0
	s_setprio 1
	v_mfma_f32_16x16x32_bf16 v[54:57], v[178:181], v[194:197], 0
	v_mfma_f32_16x16x32_bf16 v[46:49], v[186:189], v[194:197], 0
	v_mfma_f32_16x16x32_bf16 v[38:41], v[178:181], v[202:205], 0
	v_mfma_f32_16x16x32_bf16 v[30:33], v[186:189], v[202:205], 0
	v_mfma_f32_16x16x32_bf16 v[22:25], v[178:181], v[210:213], 0
	v_mfma_f32_16x16x32_bf16 v[14:17], v[186:189], v[210:213], 0
	v_mfma_f32_16x16x32_bf16 v[6:9], v[178:181], v[218:221], 0
	v_mfma_f32_16x16x32_bf16 v[2:5], v[186:189], v[218:221], 0
	v_mfma_f32_16x16x32_bf16 v[54:57], v[182:185], v[198:201], v[54:57]
	v_mfma_f32_16x16x32_bf16 v[46:49], v[190:193], v[198:201], v[46:49]
	v_mfma_f32_16x16x32_bf16 v[38:41], v[182:185], v[206:209], v[38:41]
	v_mfma_f32_16x16x32_bf16 v[30:33], v[190:193], v[206:209], v[30:33]
	v_mfma_f32_16x16x32_bf16 v[22:25], v[182:185], v[214:217], v[22:25]
	v_mfma_f32_16x16x32_bf16 v[14:17], v[190:193], v[214:217], v[14:17]
	v_mfma_f32_16x16x32_bf16 v[6:9], v[182:185], v[222:225], v[6:9]
	v_mfma_f32_16x16x32_bf16 v[2:5], v[190:193], v[222:225], v[2:5]
	s_setprio 0
	s_barrier
	s_add_i32 s62, 0, 0x18000
	v_add_u32_e32 v163, s62, v148
	s_add_i32 s63, 0, 0x1c000
	ds_read_b128 v[144:147], v163
	ds_read_b128 v[164:167], v163 offset:1024
	ds_read_b128 v[168:171], v163 offset:2048
	ds_read_b128 v[172:175], v163 offset:3072
	v_add_u32_e32 v163, s63, v148
	ds_read_b128 v[178:181], v163
	ds_read_b128 v[182:185], v163 offset:1024
	ds_read_b128 v[186:189], v163 offset:2048
	ds_read_b128 v[190:193], v163 offset:3072
	s_add_u32 s2, s2, 0x40000
	s_addc_u32 s3, s3, 0
	s_mov_b32 m0, s44
	v_lshl_add_u64 v[234:235], s[2:3], 0, v[130:131]
	ds_read_b128 v[194:197], v160 offset:32768
	ds_read_b128 v[198:201], v160 offset:33792
	ds_read_b128 v[202:205], v160 offset:34816
	ds_read_b128 v[206:209], v160 offset:35840
	ds_read_b128 v[210:213], v160 offset:36864
	ds_read_b128 v[214:217], v160 offset:37888
	ds_read_b128 v[218:221], v160 offset:38912
	ds_read_b128 v[222:225], v160 offset:39936
	global_load_lds_dwordx4 v[234:235], off
	v_lshl_add_u64 v[234:235], s[2:3], 0, v[134:135]
	s_mov_b32 m0, s45
	s_nop 0
	global_load_lds_dwordx4 v[234:235], off
	s_waitcnt vmcnt(8)
	s_waitcnt lgkmcnt(0)
	s_barrier
	s_setprio 1
	s_waitcnt lgkmcnt(0)
	v_mfma_f32_16x16x32_bf16 v[126:129], v[144:147], v[194:197], v[126:129]
	v_mfma_f32_16x16x32_bf16 v[122:125], v[168:171], v[194:197], v[122:125]
	v_mfma_f32_16x16x32_bf16 v[114:117], v[144:147], v[202:205], v[114:117]
	v_mfma_f32_16x16x32_bf16 v[106:109], v[168:171], v[202:205], v[106:109]
	v_mfma_f32_16x16x32_bf16 v[98:101], v[144:147], v[210:213], v[98:101]
	v_mfma_f32_16x16x32_bf16 v[90:93], v[168:171], v[210:213], v[90:93]
	v_mfma_f32_16x16x32_bf16 v[82:85], v[144:147], v[218:221], v[82:85]
	v_mfma_f32_16x16x32_bf16 v[74:77], v[168:171], v[218:221], v[74:77]
	v_mfma_f32_16x16x32_bf16 v[126:129], v[164:167], v[198:201], v[126:129]
	v_mfma_f32_16x16x32_bf16 v[122:125], v[172:175], v[198:201], v[122:125]
	v_mfma_f32_16x16x32_bf16 v[114:117], v[164:167], v[206:209], v[114:117]
	v_mfma_f32_16x16x32_bf16 v[106:109], v[172:175], v[206:209], v[106:109]
	v_mfma_f32_16x16x32_bf16 v[98:101], v[164:167], v[214:217], v[98:101]
	v_mfma_f32_16x16x32_bf16 v[90:93], v[172:175], v[214:217], v[90:93]
	v_mfma_f32_16x16x32_bf16 v[82:85], v[164:167], v[222:225], v[82:85]
	v_mfma_f32_16x16x32_bf16 v[74:77], v[172:175], v[222:225], v[74:77]
	s_setprio 0
	s_setprio 1
	v_mfma_f32_16x16x32_bf16 v[118:121], v[178:181], v[194:197], v[118:121]
	v_mfma_f32_16x16x32_bf16 v[110:113], v[186:189], v[194:197], v[110:113]
	v_mfma_f32_16x16x32_bf16 v[102:105], v[178:181], v[202:205], v[102:105]
	v_mfma_f32_16x16x32_bf16 v[94:97], v[186:189], v[202:205], v[94:97]
	v_mfma_f32_16x16x32_bf16 v[86:89], v[178:181], v[210:213], v[86:89]
	v_mfma_f32_16x16x32_bf16 v[78:81], v[186:189], v[210:213], v[78:81]
	v_mfma_f32_16x16x32_bf16 v[70:73], v[178:181], v[218:221], v[70:73]
	v_mfma_f32_16x16x32_bf16 v[66:69], v[186:189], v[218:221], v[66:69]
	v_mfma_f32_16x16x32_bf16 v[118:121], v[182:185], v[198:201], v[118:121]
	v_mfma_f32_16x16x32_bf16 v[110:113], v[190:193], v[198:201], v[110:113]
	v_mfma_f32_16x16x32_bf16 v[102:105], v[182:185], v[206:209], v[102:105]
	v_mfma_f32_16x16x32_bf16 v[94:97], v[190:193], v[206:209], v[94:97]
	v_mfma_f32_16x16x32_bf16 v[86:89], v[182:185], v[214:217], v[86:89]
	v_mfma_f32_16x16x32_bf16 v[78:81], v[190:193], v[214:217], v[78:81]
	v_mfma_f32_16x16x32_bf16 v[70:73], v[182:185], v[222:225], v[70:73]
	v_mfma_f32_16x16x32_bf16 v[66:69], v[190:193], v[222:225], v[66:69]
	s_setprio 0
	s_barrier
	s_add_i32 s2, s62, s41
	v_lshl_add_u64 v[226:227], v[226:227], 0, s[10:11]
	s_mov_b32 m0, s2
	ds_read_b128 v[194:197], v160 offset:49152
	ds_read_b128 v[198:201], v160 offset:50176
	ds_read_b128 v[202:205], v160 offset:51200
	ds_read_b128 v[206:209], v160 offset:52224
	ds_read_b128 v[210:213], v160 offset:53248
	ds_read_b128 v[214:217], v160 offset:54272
	ds_read_b128 v[218:221], v160 offset:55296
	ds_read_b128 v[222:225], v160 offset:56320
	global_load_lds_dwordx4 v[226:227], off
	s_add_i32 m0, s2, 0x2000
	s_add_u32 s2, s38, 0x40080
	v_lshl_add_u64 v[226:227], v[228:229], 0, s[10:11]
	s_addc_u32 s3, s39, 0
	s_add_i32 s38, s63, s41
	global_load_lds_dwordx4 v[226:227], off
	v_lshl_add_u64 v[226:227], s[2:3], 0, v[132:133]
	s_mov_b32 m0, s38
	s_nop 0
	global_load_lds_dwordx4 v[226:227], off
	v_lshl_add_u64 v[226:227], s[2:3], 0, v[136:137]
	s_add_i32 m0, s38, 0x2000
	s_nop 0
	global_load_lds_dwordx4 v[226:227], off
	v_lshl_add_u64 v[226:227], v[230:231], 0, s[10:11]
	s_mov_b32 m0, s47
	s_nop 0
	global_load_lds_dwordx4 v[226:227], off
	v_lshl_add_u64 v[226:227], v[232:233], 0, s[10:11]
	s_mov_b32 m0, s48
	s_nop 0
	global_load_lds_dwordx4 v[226:227], off
	s_waitcnt vmcnt(8)
	s_waitcnt lgkmcnt(0)
	s_barrier
	s_setprio 1
	s_waitcnt lgkmcnt(0)
	v_mfma_f32_16x16x32_bf16 v[62:65], v[144:147], v[194:197], v[62:65]
	v_mfma_f32_16x16x32_bf16 v[58:61], v[168:171], v[194:197], v[58:61]
	v_mfma_f32_16x16x32_bf16 v[50:53], v[144:147], v[202:205], v[50:53]
	v_mfma_f32_16x16x32_bf16 v[42:45], v[168:171], v[202:205], v[42:45]
	v_mfma_f32_16x16x32_bf16 v[34:37], v[144:147], v[210:213], v[34:37]
	v_mfma_f32_16x16x32_bf16 v[26:29], v[168:171], v[210:213], v[26:29]
	v_mfma_f32_16x16x32_bf16 v[18:21], v[144:147], v[218:221], v[18:21]
	v_mfma_f32_16x16x32_bf16 v[10:13], v[168:171], v[218:221], v[10:13]
	v_mfma_f32_16x16x32_bf16 v[62:65], v[164:167], v[198:201], v[62:65]
	v_mfma_f32_16x16x32_bf16 v[58:61], v[172:175], v[198:201], v[58:61]
	v_mfma_f32_16x16x32_bf16 v[50:53], v[164:167], v[206:209], v[50:53]
	v_mfma_f32_16x16x32_bf16 v[42:45], v[172:175], v[206:209], v[42:45]
	v_mfma_f32_16x16x32_bf16 v[34:37], v[164:167], v[214:217], v[34:37]
	v_mfma_f32_16x16x32_bf16 v[26:29], v[172:175], v[214:217], v[26:29]
	v_mfma_f32_16x16x32_bf16 v[18:21], v[164:167], v[222:225], v[18:21]
	v_mfma_f32_16x16x32_bf16 v[10:13], v[172:175], v[222:225], v[10:13]
	s_setprio 0
	s_setprio 1
	v_mfma_f32_16x16x32_bf16 v[54:57], v[178:181], v[194:197], v[54:57]
	v_mfma_f32_16x16x32_bf16 v[46:49], v[186:189], v[194:197], v[46:49]
	v_mfma_f32_16x16x32_bf16 v[38:41], v[178:181], v[202:205], v[38:41]
	v_mfma_f32_16x16x32_bf16 v[30:33], v[186:189], v[202:205], v[30:33]
	v_mfma_f32_16x16x32_bf16 v[22:25], v[178:181], v[210:213], v[22:25]
	v_mfma_f32_16x16x32_bf16 v[14:17], v[186:189], v[210:213], v[14:17]
	v_mfma_f32_16x16x32_bf16 v[6:9], v[178:181], v[218:221], v[6:9]
	v_mfma_f32_16x16x32_bf16 v[2:5], v[186:189], v[218:221], v[2:5]
	v_mfma_f32_16x16x32_bf16 v[54:57], v[182:185], v[198:201], v[54:57]
	v_mfma_f32_16x16x32_bf16 v[46:49], v[190:193], v[198:201], v[46:49]
	v_mfma_f32_16x16x32_bf16 v[38:41], v[182:185], v[206:209], v[38:41]
	v_mfma_f32_16x16x32_bf16 v[30:33], v[190:193], v[206:209], v[30:33]
	v_mfma_f32_16x16x32_bf16 v[22:25], v[182:185], v[214:217], v[22:25]
	v_mfma_f32_16x16x32_bf16 v[14:17], v[190:193], v[214:217], v[14:17]
	v_mfma_f32_16x16x32_bf16 v[6:9], v[182:185], v[222:225], v[6:9]
	v_mfma_f32_16x16x32_bf16 v[2:5], v[190:193], v[222:225], v[2:5]
	s_setprio 0
	s_barrier
	s_add_i32 s61, s61, 2
	s_add_u32 s36, s36, 0x100
	s_addc_u32 s37, s37, 0
	s_add_u32 s59, s59, 0x100
	s_addc_u32 s60, s60, 0
	s_cmp_gt_u32 s61, 13
	s_cbranch_scc0 .LBB0_1179
	s_branch .Lpk1179_exit
	s_branch .LBB0_1179
	.p2align 6

.LBB0_1238:
	s_lshl_b64 s[2:3], s[22:23], 1
	s_add_u32 s28, s4, s2
	s_addc_u32 s29, s5, s3
	s_and_b64 s[2:3], s[26:27], exec
	s_cselect_b32 s19, s29, s37
	s_cselect_b32 s21, s28, s36
	s_lshl_b64 s[2:3], s[24:25], 1
	s_add_u32 s30, s41, s2
	s_addc_u32 s31, s42, s3
	s_and_b64 s[2:3], s[26:27], exec
	s_cselect_b32 s58, s31, s39
	s_cselect_b32 s59, s30, s38
	s_add_u32 s36, s36, 0x40080
	s_addc_u32 s37, s37, 0
	s_add_u32 s60, s38, 0x100
	s_addc_u32 s61, s39, 0
	s_mov_b32 s62, -2
	s_branch .Lpk1239_peel
	.p2align 6
.Lpk1239_peel:
	ds_read_b128 v[152:155], v148
	ds_read_b128 v[156:159], v148 offset:1024
	ds_read_b128 v[160:163], v148 offset:2048
	ds_read_b128 v[164:167], v148 offset:3072
	ds_read_b128 v[168:171], v149
	ds_read_b128 v[172:175], v149 offset:1024
	ds_read_b128 v[178:181], v149 offset:2048
	ds_read_b128 v[182:185], v149 offset:3072
	s_add_u32 s2, s36, 0xfffc0080
	s_addc_u32 s3, s37, -1
	s_cmp_eq_u32 s62, 12
	s_cselect_b32 s3, s19, s3
	s_cselect_b32 s2, s21, s2
	s_cselect_b32 s39, s58, s61
	s_cselect_b32 s38, s59, s60
	v_lshl_add_u64 v[144:145], s[36:37], 0, v[138:139]
	s_add_i32 m0, s44, 0xc000
	ds_read_b128 v[186:189], v150
	ds_read_b128 v[190:193], v150 offset:1024
	ds_read_b128 v[194:197], v150 offset:2048
	ds_read_b128 v[198:201], v150 offset:3072
	ds_read_b128 v[202:205], v150 offset:4096
	ds_read_b128 v[206:209], v150 offset:5120
	ds_read_b128 v[210:213], v150 offset:6144
	ds_read_b128 v[214:217], v150 offset:7168
	global_load_lds_dwordx4 v[144:145], off
	v_lshl_add_u64 v[144:145], s[36:37], 0, v[140:141]
	s_add_i32 m0, s44, 0xe000
	s_nop 0
	global_load_lds_dwordx4 v[144:145], off
	s_waitcnt vmcnt(8)
	s_waitcnt lgkmcnt(0)
	s_barrier
	s_setprio 1
	s_waitcnt lgkmcnt(0)
	v_mfma_f32_16x16x32_bf16 v[126:129], v[152:155], v[186:189], 0
	v_mfma_f32_16x16x32_bf16 v[122:125], v[160:163], v[186:189], 0
	v_mfma_f32_16x16x32_bf16 v[114:117], v[152:155], v[194:197], 0
	v_mfma_f32_16x16x32_bf16 v[106:109], v[160:163], v[194:197], 0
	v_mfma_f32_16x16x32_bf16 v[98:101], v[152:155], v[202:205], 0
	v_mfma_f32_16x16x32_bf16 v[90:93], v[160:163], v[202:205], 0
	v_mfma_f32_16x16x32_bf16 v[82:85], v[152:155], v[210:213], 0
	v_mfma_f32_16x16x32_bf16 v[74:77], v[160:163], v[210:213], 0
	v_mfma_f32_16x16x32_bf16 v[126:129], v[156:159], v[190:193], v[126:129]
	v_mfma_f32_16x16x32_bf16 v[122:125], v[164:167], v[190:193], v[122:125]
	v_mfma_f32_16x16x32_bf16 v[114:117], v[156:159], v[198:201], v[114:117]
	v_mfma_f32_16x16x32_bf16 v[106:109], v[164:167], v[198:201], v[106:109]
	v_mfma_f32_16x16x32_bf16 v[98:101], v[156:159], v[206:209], v[98:101]
	v_mfma_f32_16x16x32_bf16 v[90:93], v[164:167], v[206:209], v[90:93]
	v_mfma_f32_16x16x32_bf16 v[82:85], v[156:159], v[214:217], v[82:85]
	v_mfma_f32_16x16x32_bf16 v[74:77], v[164:167], v[214:217], v[74:77]
	s_setprio 0
	s_setprio 1
	v_mfma_f32_16x16x32_bf16 v[118:121], v[168:171], v[186:189], 0
	v_mfma_f32_16x16x32_bf16 v[110:113], v[178:181], v[186:189], 0
	v_mfma_f32_16x16x32_bf16 v[102:105], v[168:171], v[194:197], 0
	v_mfma_f32_16x16x32_bf16 v[94:97], v[178:181], v[194:197], 0
	v_mfma_f32_16x16x32_bf16 v[86:89], v[168:171], v[202:205], 0
	v_mfma_f32_16x16x32_bf16 v[78:81], v[178:181], v[202:205], 0
	v_mfma_f32_16x16x32_bf16 v[70:73], v[168:171], v[210:213], 0
	v_mfma_f32_16x16x32_bf16 v[66:69], v[178:181], v[210:213], 0
	v_mfma_f32_16x16x32_bf16 v[118:121], v[172:175], v[190:193], v[118:121]
	v_mfma_f32_16x16x32_bf16 v[110:113], v[182:185], v[190:193], v[110:113]
	v_mfma_f32_16x16x32_bf16 v[102:105], v[172:175], v[198:201], v[102:105]
	v_mfma_f32_16x16x32_bf16 v[94:97], v[182:185], v[198:201], v[94:97]
	v_mfma_f32_16x16x32_bf16 v[86:89], v[172:175], v[206:209], v[86:89]
	v_mfma_f32_16x16x32_bf16 v[78:81], v[182:185], v[206:209], v[78:81]
	v_mfma_f32_16x16x32_bf16 v[70:73], v[172:175], v[214:217], v[70:73]
	v_mfma_f32_16x16x32_bf16 v[66:69], v[182:185], v[214:217], v[66:69]
	s_setprio 0
	s_barrier
	s_add_i32 s63, s51, s43
	v_lshl_add_u64 v[144:145], s[38:39], 0, v[132:133]
	s_mov_b32 m0, s63
	ds_read_b128 v[186:189], v150 offset:16384
	ds_read_b128 v[190:193], v150 offset:17408
	ds_read_b128 v[194:197], v150 offset:18432
	ds_read_b128 v[198:201], v150 offset:19456
	ds_read_b128 v[202:205], v150 offset:20480
	ds_read_b128 v[206:209], v150 offset:21504
	ds_read_b128 v[210:213], v150 offset:22528
	ds_read_b128 v[214:217], v150 offset:23552
	global_load_lds_dwordx4 v[144:145], off
	s_add_i32 m0, s63, 0x2000
	s_add_u32 s64, s38, 0x40000
	v_lshl_add_u64 v[218:219], s[38:39], 0, v[136:137]
	s_addc_u32 s65, s39, 0
	s_add_i32 s63, s52, s43
	global_load_lds_dwordx4 v[218:219], off
	v_lshl_add_u64 v[220:221], s[64:65], 0, v[132:133]
	s_mov_b32 m0, s63
	v_lshl_add_u64 v[222:223], s[2:3], 0, v[134:135]
	global_load_lds_dwordx4 v[220:221], off
	v_lshl_add_u64 v[220:221], s[64:65], 0, v[136:137]
	s_add_i32 m0, s63, 0x2000
	s_nop 0
	global_load_lds_dwordx4 v[220:221], off
	v_lshl_add_u64 v[220:221], s[2:3], 0, v[130:131]
	s_mov_b32 m0, s44
	s_nop 0
	global_load_lds_dwordx4 v[220:221], off
	s_mov_b32 m0, s35
	s_nop 0
	global_load_lds_dwordx4 v[222:223], off
	s_waitcnt vmcnt(8)
	s_waitcnt lgkmcnt(0)
	s_barrier
	s_setprio 1
	s_waitcnt lgkmcnt(0)
	v_mfma_f32_16x16x32_bf16 v[62:65], v[152:155], v[186:189], 0
	v_mfma_f32_16x16x32_bf16 v[58:61], v[160:163], v[186:189], 0
	v_mfma_f32_16x16x32_bf16 v[50:53], v[152:155], v[194:197], 0
	v_mfma_f32_16x16x32_bf16 v[42:45], v[160:163], v[194:197], 0
	v_mfma_f32_16x16x32_bf16 v[34:37], v[152:155], v[202:205], 0
	v_mfma_f32_16x16x32_bf16 v[26:29], v[160:163], v[202:205], 0
	v_mfma_f32_16x16x32_bf16 v[18:21], v[152:155], v[210:213], 0
	v_mfma_f32_16x16x32_bf16 v[10:13], v[160:163], v[210:213], 0
	v_mfma_f32_16x16x32_bf16 v[62:65], v[156:159], v[190:193], v[62:65]
	v_mfma_f32_16x16x32_bf16 v[58:61], v[164:167], v[190:193], v[58:61]
	v_mfma_f32_16x16x32_bf16 v[50:53], v[156:159], v[198:201], v[50:53]
	v_mfma_f32_16x16x32_bf16 v[42:45], v[164:167], v[198:201], v[42:45]
	v_mfma_f32_16x16x32_bf16 v[34:37], v[156:159], v[206:209], v[34:37]
	v_mfma_f32_16x16x32_bf16 v[26:29], v[164:167], v[206:209], v[26:29]
	v_mfma_f32_16x16x32_bf16 v[18:21], v[156:159], v[214:217], v[18:21]
	v_mfma_f32_16x16x32_bf16 v[10:13], v[164:167], v[214:217], v[10:13]
	s_setprio 0
	s_setprio 1
	v_mfma_f32_16x16x32_bf16 v[54:57], v[168:171], v[186:189], 0
	v_mfma_f32_16x16x32_bf16 v[46:49], v[178:181], v[186:189], 0
	v_mfma_f32_16x16x32_bf16 v[38:41], v[168:171], v[194:197], 0
	v_mfma_f32_16x16x32_bf16 v[30:33], v[178:181], v[194:197], 0
	v_mfma_f32_16x16x32_bf16 v[22:25], v[168:171], v[202:205], 0
	v_mfma_f32_16x16x32_bf16 v[14:17], v[178:181], v[202:205], 0
	v_mfma_f32_16x16x32_bf16 v[6:9], v[168:171], v[210:213], 0
	v_mfma_f32_16x16x32_bf16 v[2:5], v[178:181], v[210:213], 0
	v_mfma_f32_16x16x32_bf16 v[54:57], v[172:175], v[190:193], v[54:57]
	v_mfma_f32_16x16x32_bf16 v[46:49], v[182:185], v[190:193], v[46:49]
	v_mfma_f32_16x16x32_bf16 v[38:41], v[172:175], v[198:201], v[38:41]
	v_mfma_f32_16x16x32_bf16 v[30:33], v[182:185], v[198:201], v[30:33]
	v_mfma_f32_16x16x32_bf16 v[22:25], v[172:175], v[206:209], v[22:25]
	v_mfma_f32_16x16x32_bf16 v[14:17], v[182:185], v[206:209], v[14:17]
	v_mfma_f32_16x16x32_bf16 v[6:9], v[172:175], v[214:217], v[6:9]
	v_mfma_f32_16x16x32_bf16 v[2:5], v[182:185], v[214:217], v[2:5]
	s_setprio 0
	s_barrier
	s_add_i32 s63, 0, 0x18000
	v_add_u32_e32 v151, s63, v146
	s_add_i32 s64, 0, 0x1c000
	ds_read_b128 v[152:155], v151
	ds_read_b128 v[156:159], v151 offset:1024
	ds_read_b128 v[160:163], v151 offset:2048
	ds_read_b128 v[164:167], v151 offset:3072
	v_add_u32_e32 v151, s64, v146
	ds_read_b128 v[168:171], v151
	ds_read_b128 v[172:175], v151 offset:1024
	ds_read_b128 v[178:181], v151 offset:2048
	ds_read_b128 v[182:185], v151 offset:3072
	s_add_u32 s2, s2, 0x40000
	s_addc_u32 s3, s3, 0
	s_mov_b32 m0, s45
	v_lshl_add_u64 v[224:225], s[2:3], 0, v[130:131]
	ds_read_b128 v[186:189], v150 offset:32768
	ds_read_b128 v[190:193], v150 offset:33792
	ds_read_b128 v[194:197], v150 offset:34816
	ds_read_b128 v[198:201], v150 offset:35840
	ds_read_b128 v[202:205], v150 offset:36864
	ds_read_b128 v[206:209], v150 offset:37888
	ds_read_b128 v[210:213], v150 offset:38912
	ds_read_b128 v[214:217], v150 offset:39936
	global_load_lds_dwordx4 v[224:225], off
	v_lshl_add_u64 v[224:225], s[2:3], 0, v[134:135]
	s_mov_b32 m0, s46
	s_nop 0
	global_load_lds_dwordx4 v[224:225], off
	s_waitcnt vmcnt(8)
	s_waitcnt lgkmcnt(0)
	s_barrier
	s_setprio 1
	s_waitcnt lgkmcnt(0)
	v_mfma_f32_16x16x32_bf16 v[126:129], v[152:155], v[186:189], v[126:129]
	v_mfma_f32_16x16x32_bf16 v[122:125], v[160:163], v[186:189], v[122:125]
	v_mfma_f32_16x16x32_bf16 v[114:117], v[152:155], v[194:197], v[114:117]
	v_mfma_f32_16x16x32_bf16 v[106:109], v[160:163], v[194:197], v[106:109]
	v_mfma_f32_16x16x32_bf16 v[98:101], v[152:155], v[202:205], v[98:101]
	v_mfma_f32_16x16x32_bf16 v[90:93], v[160:163], v[202:205], v[90:93]
	v_mfma_f32_16x16x32_bf16 v[82:85], v[152:155], v[210:213], v[82:85]
	v_mfma_f32_16x16x32_bf16 v[74:77], v[160:163], v[210:213], v[74:77]
	v_mfma_f32_16x16x32_bf16 v[126:129], v[156:159], v[190:193], v[126:129]
	v_mfma_f32_16x16x32_bf16 v[122:125], v[164:167], v[190:193], v[122:125]
	v_mfma_f32_16x16x32_bf16 v[114:117], v[156:159], v[198:201], v[114:117]
	v_mfma_f32_16x16x32_bf16 v[106:109], v[164:167], v[198:201], v[106:109]
	v_mfma_f32_16x16x32_bf16 v[98:101], v[156:159], v[206:209], v[98:101]
	v_mfma_f32_16x16x32_bf16 v[90:93], v[164:167], v[206:209], v[90:93]
	v_mfma_f32_16x16x32_bf16 v[82:85], v[156:159], v[214:217], v[82:85]
	v_mfma_f32_16x16x32_bf16 v[74:77], v[164:167], v[214:217], v[74:77]
	s_setprio 0
	s_setprio 1
	v_mfma_f32_16x16x32_bf16 v[118:121], v[168:171], v[186:189], v[118:121]
	v_mfma_f32_16x16x32_bf16 v[110:113], v[178:181], v[186:189], v[110:113]
	v_mfma_f32_16x16x32_bf16 v[102:105], v[168:171], v[194:197], v[102:105]
	v_mfma_f32_16x16x32_bf16 v[94:97], v[178:181], v[194:197], v[94:97]
	v_mfma_f32_16x16x32_bf16 v[86:89], v[168:171], v[202:205], v[86:89]
	v_mfma_f32_16x16x32_bf16 v[78:81], v[178:181], v[202:205], v[78:81]
	v_mfma_f32_16x16x32_bf16 v[70:73], v[168:171], v[210:213], v[70:73]
	v_mfma_f32_16x16x32_bf16 v[66:69], v[178:181], v[210:213], v[66:69]
	v_mfma_f32_16x16x32_bf16 v[118:121], v[172:175], v[190:193], v[118:121]
	v_mfma_f32_16x16x32_bf16 v[110:113], v[182:185], v[190:193], v[110:113]
	v_mfma_f32_16x16x32_bf16 v[102:105], v[172:175], v[198:201], v[102:105]
	v_mfma_f32_16x16x32_bf16 v[94:97], v[182:185], v[198:201], v[94:97]
	v_mfma_f32_16x16x32_bf16 v[86:89], v[172:175], v[206:209], v[86:89]
	v_mfma_f32_16x16x32_bf16 v[78:81], v[182:185], v[206:209], v[78:81]
	v_mfma_f32_16x16x32_bf16 v[70:73], v[172:175], v[214:217], v[70:73]
	v_mfma_f32_16x16x32_bf16 v[66:69], v[182:185], v[214:217], v[66:69]
	s_setprio 0
	s_barrier
	s_add_i32 s2, s63, s43
	v_lshl_add_u64 v[144:145], v[144:145], 0, s[8:9]
	s_mov_b32 m0, s2
	ds_read_b128 v[186:189], v150 offset:49152
	ds_read_b128 v[190:193], v150 offset:50176
	ds_read_b128 v[194:197], v150 offset:51200
	ds_read_b128 v[198:201], v150 offset:52224
	ds_read_b128 v[202:205], v150 offset:53248
	ds_read_b128 v[206:209], v150 offset:54272
	ds_read_b128 v[210:213], v150 offset:55296
	ds_read_b128 v[214:217], v150 offset:56320
	global_load_lds_dwordx4 v[144:145], off
	s_add_i32 m0, s2, 0x2000
	s_add_u32 s2, s38, 0x40080
	v_lshl_add_u64 v[144:145], v[218:219], 0, s[8:9]
	s_addc_u32 s3, s39, 0
	s_add_i32 s38, s64, s43
	global_load_lds_dwordx4 v[144:145], off
	v_lshl_add_u64 v[144:145], s[2:3], 0, v[132:133]
	s_mov_b32 m0, s38
	s_nop 0
	global_load_lds_dwordx4 v[144:145], off
	v_lshl_add_u64 v[144:145], s[2:3], 0, v[136:137]
	s_add_i32 m0, s38, 0x2000
	s_nop 0
	global_load_lds_dwordx4 v[144:145], off
	v_lshl_add_u64 v[144:145], v[220:221], 0, s[8:9]
	s_mov_b32 m0, s48
	s_nop 0
	global_load_lds_dwordx4 v[144:145], off
	v_lshl_add_u64 v[144:145], v[222:223], 0, s[8:9]
	s_mov_b32 m0, s49
	s_nop 0
	global_load_lds_dwordx4 v[144:145], off
	s_waitcnt vmcnt(8)
	s_waitcnt lgkmcnt(0)
	s_barrier
	s_setprio 1
	s_waitcnt lgkmcnt(0)
	v_mfma_f32_16x16x32_bf16 v[62:65], v[152:155], v[186:189], v[62:65]
	v_mfma_f32_16x16x32_bf16 v[58:61], v[160:163], v[186:189], v[58:61]
	v_mfma_f32_16x16x32_bf16 v[50:53], v[152:155], v[194:197], v[50:53]
	v_mfma_f32_16x16x32_bf16 v[42:45], v[160:163], v[194:197], v[42:45]
	v_mfma_f32_16x16x32_bf16 v[34:37], v[152:155], v[202:205], v[34:37]
	v_mfma_f32_16x16x32_bf16 v[26:29], v[160:163], v[202:205], v[26:29]
	v_mfma_f32_16x16x32_bf16 v[18:21], v[152:155], v[210:213], v[18:21]
	v_mfma_f32_16x16x32_bf16 v[10:13], v[160:163], v[210:213], v[10:13]
	v_mfma_f32_16x16x32_bf16 v[62:65], v[156:159], v[190:193], v[62:65]
	v_mfma_f32_16x16x32_bf16 v[58:61], v[164:167], v[190:193], v[58:61]
	v_mfma_f32_16x16x32_bf16 v[50:53], v[156:159], v[198:201], v[50:53]
	v_mfma_f32_16x16x32_bf16 v[42:45], v[164:167], v[198:201], v[42:45]
	v_mfma_f32_16x16x32_bf16 v[34:37], v[156:159], v[206:209], v[34:37]
	v_mfma_f32_16x16x32_bf16 v[26:29], v[164:167], v[206:209], v[26:29]
	v_mfma_f32_16x16x32_bf16 v[18:21], v[156:159], v[214:217], v[18:21]
	v_mfma_f32_16x16x32_bf16 v[10:13], v[164:167], v[214:217], v[10:13]
	s_setprio 0
	s_setprio 1
	v_mfma_f32_16x16x32_bf16 v[54:57], v[168:171], v[186:189], v[54:57]
	v_mfma_f32_16x16x32_bf16 v[46:49], v[178:181], v[186:189], v[46:49]
	v_mfma_f32_16x16x32_bf16 v[38:41], v[168:171], v[194:197], v[38:41]
	v_mfma_f32_16x16x32_bf16 v[30:33], v[178:181], v[194:197], v[30:33]
	v_mfma_f32_16x16x32_bf16 v[22:25], v[168:171], v[202:205], v[22:25]
	v_mfma_f32_16x16x32_bf16 v[14:17], v[178:181], v[202:205], v[14:17]
	v_mfma_f32_16x16x32_bf16 v[6:9], v[168:171], v[210:213], v[6:9]
	v_mfma_f32_16x16x32_bf16 v[2:5], v[178:181], v[210:213], v[2:5]
	v_mfma_f32_16x16x32_bf16 v[54:57], v[172:175], v[190:193], v[54:57]
	v_mfma_f32_16x16x32_bf16 v[46:49], v[182:185], v[190:193], v[46:49]
	v_mfma_f32_16x16x32_bf16 v[38:41], v[172:175], v[198:201], v[38:41]
	v_mfma_f32_16x16x32_bf16 v[30:33], v[182:185], v[198:201], v[30:33]
	v_mfma_f32_16x16x32_bf16 v[22:25], v[172:175], v[206:209], v[22:25]
	v_mfma_f32_16x16x32_bf16 v[14:17], v[182:185], v[206:209], v[14:17]
	v_mfma_f32_16x16x32_bf16 v[6:9], v[172:175], v[214:217], v[6:9]
	v_mfma_f32_16x16x32_bf16 v[2:5], v[182:185], v[214:217], v[2:5]
	s_setprio 0
	s_barrier
	s_add_i32 s62, s62, 2
	s_add_u32 s36, s36, 0x100
	s_addc_u32 s37, s37, 0
	s_add_u32 s60, s60, 0x100
	s_addc_u32 s61, s61, 0
	s_cmp_gt_u32 s62, 13
	s_cbranch_scc0 .LBB0_1239
	s_branch .Lpk1239_exit
	s_branch .LBB0_1239
	.p2align 6

.LBB0_1302:
	s_lshl_b64 s[2:3], s[14:15], 1
	v_readlane_b32 s20, v253, 52
	v_readlane_b32 s21, v253, 53
	s_add_u32 s20, s20, s2
	s_addc_u32 s21, s21, s3
	s_and_b64 s[2:3], s[18:19], exec
	s_cselect_b32 s11, s21, s27
	s_cselect_b32 s13, s20, s26
	s_lshl_b64 s[2:3], s[16:17], 1
	s_add_u32 s22, s48, s2
	s_addc_u32 s23, s49, s3
	s_and_b64 s[2:3], s[18:19], exec
	s_cselect_b32 s47, s23, s29
	s_cselect_b32 s52, s22, s28
	s_add_u32 s26, s26, 0x40080
	s_addc_u32 s27, s27, 0
	s_add_u32 s53, s28, 0x100
	s_addc_u32 s54, s29, 0
	s_mov_b32 s55, -2
	s_branch .Lpk1303_peel
	.p2align 6
.Lpk1303_peel:
	ds_read_b128 v[166:169], v139
	ds_read_b128 v[170:173], v139 offset:1024
	ds_read_b128 v[178:181], v139 offset:2048
	ds_read_b128 v[182:185], v139 offset:3072
	ds_read_b128 v[186:189], v163
	ds_read_b128 v[190:193], v163 offset:1024
	ds_read_b128 v[194:197], v163 offset:2048
	ds_read_b128 v[198:201], v163 offset:3072
	s_add_u32 s2, s26, 0xfffc0080
	s_addc_u32 s3, s27, -1
	s_cmp_eq_u32 s55, 12
	s_cselect_b32 s3, s11, s3
	s_cselect_b32 s2, s13, s2
	s_cselect_b32 s29, s47, s54
	s_cselect_b32 s28, s52, s53
	v_lshl_add_u64 v[148:149], s[26:27], 0, v[142:143]
	s_add_i32 m0, s34, 0xc000
	ds_read_b128 v[202:205], v164
	ds_read_b128 v[206:209], v164 offset:1024
	ds_read_b128 v[210:213], v164 offset:2048
	ds_read_b128 v[214:217], v164 offset:3072
	ds_read_b128 v[218:221], v164 offset:4096
	ds_read_b128 v[222:225], v164 offset:5120
	ds_read_b128 v[226:229], v164 offset:6144
	ds_read_b128 v[230:233], v164 offset:7168
	global_load_lds_dwordx4 v[148:149], off
	v_lshl_add_u64 v[148:149], s[26:27], 0, v[144:145]
	s_add_i32 m0, s34, 0xe000
	s_nop 0
	global_load_lds_dwordx4 v[148:149], off
	s_waitcnt vmcnt(8)
	s_waitcnt lgkmcnt(0)
	s_barrier
	s_setprio 1
	s_waitcnt lgkmcnt(0)
	v_mfma_f32_16x16x32_bf16 v[126:129], v[166:169], v[202:205], 0
	v_mfma_f32_16x16x32_bf16 v[122:125], v[178:181], v[202:205], 0
	v_mfma_f32_16x16x32_bf16 v[110:113], v[166:169], v[210:213], 0
	v_mfma_f32_16x16x32_bf16 v[106:109], v[178:181], v[210:213], 0
	v_mfma_f32_16x16x32_bf16 v[94:97], v[166:169], v[218:221], 0
	v_mfma_f32_16x16x32_bf16 v[90:93], v[178:181], v[218:221], 0
	v_mfma_f32_16x16x32_bf16 v[78:81], v[166:169], v[226:229], 0
	v_mfma_f32_16x16x32_bf16 v[74:77], v[178:181], v[226:229], 0
	v_mfma_f32_16x16x32_bf16 v[126:129], v[170:173], v[206:209], v[126:129]
	v_mfma_f32_16x16x32_bf16 v[122:125], v[182:185], v[206:209], v[122:125]
	v_mfma_f32_16x16x32_bf16 v[110:113], v[170:173], v[214:217], v[110:113]
	v_mfma_f32_16x16x32_bf16 v[106:109], v[182:185], v[214:217], v[106:109]
	v_mfma_f32_16x16x32_bf16 v[94:97], v[170:173], v[222:225], v[94:97]
	v_mfma_f32_16x16x32_bf16 v[90:93], v[182:185], v[222:225], v[90:93]
	v_mfma_f32_16x16x32_bf16 v[78:81], v[170:173], v[230:233], v[78:81]
	v_mfma_f32_16x16x32_bf16 v[74:77], v[182:185], v[230:233], v[74:77]
	s_setprio 0
	s_setprio 1
	v_mfma_f32_16x16x32_bf16 v[118:121], v[186:189], v[202:205], 0
	v_mfma_f32_16x16x32_bf16 v[114:117], v[194:197], v[202:205], 0
	v_mfma_f32_16x16x32_bf16 v[102:105], v[186:189], v[210:213], 0
	v_mfma_f32_16x16x32_bf16 v[98:101], v[194:197], v[210:213], 0
	v_mfma_f32_16x16x32_bf16 v[86:89], v[186:189], v[218:221], 0
	v_mfma_f32_16x16x32_bf16 v[82:85], v[194:197], v[218:221], 0
	v_mfma_f32_16x16x32_bf16 v[70:73], v[186:189], v[226:229], 0
	v_mfma_f32_16x16x32_bf16 v[66:69], v[194:197], v[226:229], 0
	v_mfma_f32_16x16x32_bf16 v[118:121], v[190:193], v[206:209], v[118:121]
	v_mfma_f32_16x16x32_bf16 v[114:117], v[198:201], v[206:209], v[114:117]
	v_mfma_f32_16x16x32_bf16 v[102:105], v[190:193], v[214:217], v[102:105]
	v_mfma_f32_16x16x32_bf16 v[98:101], v[198:201], v[214:217], v[98:101]
	v_mfma_f32_16x16x32_bf16 v[86:89], v[190:193], v[222:225], v[86:89]
	v_mfma_f32_16x16x32_bf16 v[82:85], v[198:201], v[222:225], v[82:85]
	v_mfma_f32_16x16x32_bf16 v[70:73], v[190:193], v[230:233], v[70:73]
	v_mfma_f32_16x16x32_bf16 v[66:69], v[198:201], v[230:233], v[66:69]
	s_setprio 0
	s_barrier
	s_add_i32 s56, s42, s30
	v_lshl_add_u64 v[148:149], s[28:29], 0, v[132:133]
	s_mov_b32 m0, s56
	ds_read_b128 v[202:205], v164 offset:16384
	ds_read_b128 v[206:209], v164 offset:17408
	ds_read_b128 v[210:213], v164 offset:18432
	ds_read_b128 v[214:217], v164 offset:19456
	ds_read_b128 v[218:221], v164 offset:20480
	ds_read_b128 v[222:225], v164 offset:21504
	ds_read_b128 v[226:229], v164 offset:22528
	ds_read_b128 v[230:233], v164 offset:23552
	global_load_lds_dwordx4 v[148:149], off
	s_add_i32 m0, s56, 0x2000
	s_add_u32 s56, s28, 0x40000
	v_lshl_add_u64 v[174:175], s[28:29], 0, v[136:137]
	s_addc_u32 s57, s29, 0
	s_add_i32 s58, s43, s30
	global_load_lds_dwordx4 v[174:175], off
	v_lshl_add_u64 v[234:235], s[56:57], 0, v[132:133]
	s_mov_b32 m0, s58
	v_lshl_add_u64 v[236:237], s[2:3], 0, v[134:135]
	global_load_lds_dwordx4 v[234:235], off
	v_lshl_add_u64 v[234:235], s[56:57], 0, v[136:137]
	s_add_i32 m0, s58, 0x2000
	s_nop 0
	global_load_lds_dwordx4 v[234:235], off
	v_lshl_add_u64 v[234:235], s[2:3], 0, v[130:131]
	s_mov_b32 m0, s34
	s_nop 0
	global_load_lds_dwordx4 v[234:235], off
	s_mov_b32 m0, s25
	s_nop 0
	global_load_lds_dwordx4 v[236:237], off
	s_waitcnt vmcnt(8)
	s_waitcnt lgkmcnt(0)
	s_barrier
	s_setprio 1
	s_waitcnt lgkmcnt(0)
	v_mfma_f32_16x16x32_bf16 v[62:65], v[166:169], v[202:205], 0
	v_mfma_f32_16x16x32_bf16 v[58:61], v[178:181], v[202:205], 0
	v_mfma_f32_16x16x32_bf16 v[46:49], v[166:169], v[210:213], 0
	v_mfma_f32_16x16x32_bf16 v[42:45], v[178:181], v[210:213], 0
	v_mfma_f32_16x16x32_bf16 v[30:33], v[166:169], v[218:221], 0
	v_mfma_f32_16x16x32_bf16 v[26:29], v[178:181], v[218:221], 0
	v_mfma_f32_16x16x32_bf16 v[14:17], v[166:169], v[226:229], 0
	v_mfma_f32_16x16x32_bf16 v[10:13], v[178:181], v[226:229], 0
	v_mfma_f32_16x16x32_bf16 v[62:65], v[170:173], v[206:209], v[62:65]
	v_mfma_f32_16x16x32_bf16 v[58:61], v[182:185], v[206:209], v[58:61]
	v_mfma_f32_16x16x32_bf16 v[46:49], v[170:173], v[214:217], v[46:49]
	v_mfma_f32_16x16x32_bf16 v[42:45], v[182:185], v[214:217], v[42:45]
	v_mfma_f32_16x16x32_bf16 v[30:33], v[170:173], v[222:225], v[30:33]
	v_mfma_f32_16x16x32_bf16 v[26:29], v[182:185], v[222:225], v[26:29]
	v_mfma_f32_16x16x32_bf16 v[14:17], v[170:173], v[230:233], v[14:17]
	v_mfma_f32_16x16x32_bf16 v[10:13], v[182:185], v[230:233], v[10:13]
	s_setprio 0
	s_setprio 1
	v_mfma_f32_16x16x32_bf16 v[54:57], v[186:189], v[202:205], 0
	v_mfma_f32_16x16x32_bf16 v[50:53], v[194:197], v[202:205], 0
	v_mfma_f32_16x16x32_bf16 v[38:41], v[186:189], v[210:213], 0
	v_mfma_f32_16x16x32_bf16 v[34:37], v[194:197], v[210:213], 0
	v_mfma_f32_16x16x32_bf16 v[22:25], v[186:189], v[218:221], 0
	v_mfma_f32_16x16x32_bf16 v[18:21], v[194:197], v[218:221], 0
	v_mfma_f32_16x16x32_bf16 v[6:9], v[186:189], v[226:229], 0
	v_mfma_f32_16x16x32_bf16 v[2:5], v[194:197], v[226:229], 0
	v_mfma_f32_16x16x32_bf16 v[54:57], v[190:193], v[206:209], v[54:57]
	v_mfma_f32_16x16x32_bf16 v[50:53], v[198:201], v[206:209], v[50:53]
	v_mfma_f32_16x16x32_bf16 v[38:41], v[190:193], v[214:217], v[38:41]
	v_mfma_f32_16x16x32_bf16 v[34:37], v[198:201], v[214:217], v[34:37]
	v_mfma_f32_16x16x32_bf16 v[22:25], v[190:193], v[222:225], v[22:25]
	v_mfma_f32_16x16x32_bf16 v[18:21], v[198:201], v[222:225], v[18:21]
	v_mfma_f32_16x16x32_bf16 v[6:9], v[190:193], v[230:233], v[6:9]
	v_mfma_f32_16x16x32_bf16 v[2:5], v[198:201], v[230:233], v[2:5]
	s_setprio 0
	s_barrier
	s_add_i32 s56, 0, 0x18000
	v_add_u32_e32 v165, s56, v162
	s_add_i32 s57, 0, 0x1c000
	ds_read_b128 v[166:169], v165
	ds_read_b128 v[170:173], v165 offset:1024
	ds_read_b128 v[178:181], v165 offset:2048
	ds_read_b128 v[182:185], v165 offset:3072
	v_add_u32_e32 v165, s57, v162
	ds_read_b128 v[186:189], v165
	ds_read_b128 v[190:193], v165 offset:1024
	ds_read_b128 v[194:197], v165 offset:2048
	ds_read_b128 v[198:201], v165 offset:3072
	s_add_u32 s2, s2, 0x40000
	s_addc_u32 s3, s3, 0
	s_mov_b32 m0, s35
	v_lshl_add_u64 v[238:239], s[2:3], 0, v[130:131]
	ds_read_b128 v[202:205], v164 offset:32768
	ds_read_b128 v[206:209], v164 offset:33792
	ds_read_b128 v[210:213], v164 offset:34816
	ds_read_b128 v[214:217], v164 offset:35840
	ds_read_b128 v[218:221], v164 offset:36864
	ds_read_b128 v[222:225], v164 offset:37888
	ds_read_b128 v[226:229], v164 offset:38912
	ds_read_b128 v[230:233], v164 offset:39936
	global_load_lds_dwordx4 v[238:239], off
	v_lshl_add_u64 v[238:239], s[2:3], 0, v[134:135]
	s_mov_b32 m0, s36
	s_nop 0
	global_load_lds_dwordx4 v[238:239], off
	s_waitcnt vmcnt(8)
	s_waitcnt lgkmcnt(0)
	s_barrier
	s_setprio 1
	s_waitcnt lgkmcnt(0)
	v_mfma_f32_16x16x32_bf16 v[126:129], v[166:169], v[202:205], v[126:129]
	v_mfma_f32_16x16x32_bf16 v[122:125], v[178:181], v[202:205], v[122:125]
	v_mfma_f32_16x16x32_bf16 v[110:113], v[166:169], v[210:213], v[110:113]
	v_mfma_f32_16x16x32_bf16 v[106:109], v[178:181], v[210:213], v[106:109]
	v_mfma_f32_16x16x32_bf16 v[94:97], v[166:169], v[218:221], v[94:97]
	v_mfma_f32_16x16x32_bf16 v[90:93], v[178:181], v[218:221], v[90:93]
	v_mfma_f32_16x16x32_bf16 v[78:81], v[166:169], v[226:229], v[78:81]
	v_mfma_f32_16x16x32_bf16 v[74:77], v[178:181], v[226:229], v[74:77]
	v_mfma_f32_16x16x32_bf16 v[126:129], v[170:173], v[206:209], v[126:129]
	v_mfma_f32_16x16x32_bf16 v[122:125], v[182:185], v[206:209], v[122:125]
	v_mfma_f32_16x16x32_bf16 v[110:113], v[170:173], v[214:217], v[110:113]
	v_mfma_f32_16x16x32_bf16 v[106:109], v[182:185], v[214:217], v[106:109]
	v_mfma_f32_16x16x32_bf16 v[94:97], v[170:173], v[222:225], v[94:97]
	v_mfma_f32_16x16x32_bf16 v[90:93], v[182:185], v[222:225], v[90:93]
	v_mfma_f32_16x16x32_bf16 v[78:81], v[170:173], v[230:233], v[78:81]
	v_mfma_f32_16x16x32_bf16 v[74:77], v[182:185], v[230:233], v[74:77]
	s_setprio 0
	s_setprio 1
	v_mfma_f32_16x16x32_bf16 v[118:121], v[186:189], v[202:205], v[118:121]
	v_mfma_f32_16x16x32_bf16 v[114:117], v[194:197], v[202:205], v[114:117]
	v_mfma_f32_16x16x32_bf16 v[102:105], v[186:189], v[210:213], v[102:105]
	v_mfma_f32_16x16x32_bf16 v[98:101], v[194:197], v[210:213], v[98:101]
	v_mfma_f32_16x16x32_bf16 v[86:89], v[186:189], v[218:221], v[86:89]
	v_mfma_f32_16x16x32_bf16 v[82:85], v[194:197], v[218:221], v[82:85]
	v_mfma_f32_16x16x32_bf16 v[70:73], v[186:189], v[226:229], v[70:73]
	v_mfma_f32_16x16x32_bf16 v[66:69], v[194:197], v[226:229], v[66:69]
	v_mfma_f32_16x16x32_bf16 v[118:121], v[190:193], v[206:209], v[118:121]
	v_mfma_f32_16x16x32_bf16 v[114:117], v[198:201], v[206:209], v[114:117]
	v_mfma_f32_16x16x32_bf16 v[102:105], v[190:193], v[214:217], v[102:105]
	v_mfma_f32_16x16x32_bf16 v[98:101], v[198:201], v[214:217], v[98:101]
	v_mfma_f32_16x16x32_bf16 v[86:89], v[190:193], v[222:225], v[86:89]
	v_mfma_f32_16x16x32_bf16 v[82:85], v[198:201], v[222:225], v[82:85]
	v_mfma_f32_16x16x32_bf16 v[70:73], v[190:193], v[230:233], v[70:73]
	v_mfma_f32_16x16x32_bf16 v[66:69], v[198:201], v[230:233], v[66:69]
	s_setprio 0
	s_barrier
	s_add_i32 s2, s56, s30
	v_lshl_add_u64 v[148:149], v[148:149], 0, s[6:7]
	s_mov_b32 m0, s2
	ds_read_b128 v[202:205], v164 offset:49152
	ds_read_b128 v[206:209], v164 offset:50176
	ds_read_b128 v[210:213], v164 offset:51200
	ds_read_b128 v[214:217], v164 offset:52224
	ds_read_b128 v[218:221], v164 offset:53248
	ds_read_b128 v[222:225], v164 offset:54272
	ds_read_b128 v[226:229], v164 offset:55296
	ds_read_b128 v[230:233], v164 offset:56320
	global_load_lds_dwordx4 v[148:149], off
	s_add_i32 m0, s2, 0x2000
	s_add_u32 s2, s28, 0x40080
	v_lshl_add_u64 v[148:149], v[174:175], 0, s[6:7]
	s_addc_u32 s3, s29, 0
	s_add_i32 s28, s57, s30
	global_load_lds_dwordx4 v[148:149], off
	v_lshl_add_u64 v[148:149], s[2:3], 0, v[132:133]
	s_mov_b32 m0, s28
	s_nop 0
	global_load_lds_dwordx4 v[148:149], off
	v_lshl_add_u64 v[148:149], s[2:3], 0, v[136:137]
	s_add_i32 m0, s28, 0x2000
	s_nop 0
	global_load_lds_dwordx4 v[148:149], off
	v_lshl_add_u64 v[148:149], v[234:235], 0, s[6:7]
	s_mov_b32 m0, s39
	s_nop 0
	global_load_lds_dwordx4 v[148:149], off
	v_lshl_add_u64 v[148:149], v[236:237], 0, s[6:7]
	s_mov_b32 m0, s40
	s_nop 0
	global_load_lds_dwordx4 v[148:149], off
	s_waitcnt vmcnt(8)
	s_waitcnt lgkmcnt(0)
	s_barrier
	s_setprio 1
	s_waitcnt lgkmcnt(0)
	v_mfma_f32_16x16x32_bf16 v[62:65], v[166:169], v[202:205], v[62:65]
	v_mfma_f32_16x16x32_bf16 v[58:61], v[178:181], v[202:205], v[58:61]
	v_mfma_f32_16x16x32_bf16 v[46:49], v[166:169], v[210:213], v[46:49]
	v_mfma_f32_16x16x32_bf16 v[42:45], v[178:181], v[210:213], v[42:45]
	v_mfma_f32_16x16x32_bf16 v[30:33], v[166:169], v[218:221], v[30:33]
	v_mfma_f32_16x16x32_bf16 v[26:29], v[178:181], v[218:221], v[26:29]
	v_mfma_f32_16x16x32_bf16 v[14:17], v[166:169], v[226:229], v[14:17]
	v_mfma_f32_16x16x32_bf16 v[10:13], v[178:181], v[226:229], v[10:13]
	v_mfma_f32_16x16x32_bf16 v[62:65], v[170:173], v[206:209], v[62:65]
	v_mfma_f32_16x16x32_bf16 v[58:61], v[182:185], v[206:209], v[58:61]
	v_mfma_f32_16x16x32_bf16 v[46:49], v[170:173], v[214:217], v[46:49]
	v_mfma_f32_16x16x32_bf16 v[42:45], v[182:185], v[214:217], v[42:45]
	v_mfma_f32_16x16x32_bf16 v[30:33], v[170:173], v[222:225], v[30:33]
	v_mfma_f32_16x16x32_bf16 v[26:29], v[182:185], v[222:225], v[26:29]
	v_mfma_f32_16x16x32_bf16 v[14:17], v[170:173], v[230:233], v[14:17]
	v_mfma_f32_16x16x32_bf16 v[10:13], v[182:185], v[230:233], v[10:13]
	s_setprio 0
	s_setprio 1
	v_mfma_f32_16x16x32_bf16 v[54:57], v[186:189], v[202:205], v[54:57]
	v_mfma_f32_16x16x32_bf16 v[50:53], v[194:197], v[202:205], v[50:53]
	v_mfma_f32_16x16x32_bf16 v[38:41], v[186:189], v[210:213], v[38:41]
	v_mfma_f32_16x16x32_bf16 v[34:37], v[194:197], v[210:213], v[34:37]
	v_mfma_f32_16x16x32_bf16 v[22:25], v[186:189], v[218:221], v[22:25]
	v_mfma_f32_16x16x32_bf16 v[18:21], v[194:197], v[218:221], v[18:21]
	v_mfma_f32_16x16x32_bf16 v[6:9], v[186:189], v[226:229], v[6:9]
	v_mfma_f32_16x16x32_bf16 v[2:5], v[194:197], v[226:229], v[2:5]
	v_mfma_f32_16x16x32_bf16 v[54:57], v[190:193], v[206:209], v[54:57]
	v_mfma_f32_16x16x32_bf16 v[50:53], v[198:201], v[206:209], v[50:53]
	v_mfma_f32_16x16x32_bf16 v[38:41], v[190:193], v[214:217], v[38:41]
	v_mfma_f32_16x16x32_bf16 v[34:37], v[198:201], v[214:217], v[34:37]
	v_mfma_f32_16x16x32_bf16 v[22:25], v[190:193], v[222:225], v[22:25]
	v_mfma_f32_16x16x32_bf16 v[18:21], v[198:201], v[222:225], v[18:21]
	v_mfma_f32_16x16x32_bf16 v[6:9], v[190:193], v[230:233], v[6:9]
	v_mfma_f32_16x16x32_bf16 v[2:5], v[198:201], v[230:233], v[2:5]
	s_setprio 0
	s_barrier
	s_add_i32 s55, s55, 2
	s_add_u32 s26, s26, 0x100
	s_addc_u32 s27, s27, 0
	s_add_u32 s53, s53, 0x100
	s_addc_u32 s54, s54, 0
	s_cmp_gt_u32 s55, 13
	s_cbranch_scc0 .LBB0_1303
	s_branch .Lpk1303_exit
	s_branch .LBB0_1303
	.p2align 6

.LBB0_1385:
	s_lshl_b32 s3, s3, 5
	v_lshl_or_b32 v131, s8, 6, v155
	s_lshl_b32 s8, s8, 13
	s_and_b32 s23, s3, 0x60
	v_lshlrev_b32_e32 v3, 2, v155
	s_add_u32 s12, s0, 0x8000
	v_lshl_or_b32 v2, v155, 6, v138
	v_and_b32_e32 v3, 32, v3
	s_addc_u32 s13, s1, 0
	v_bitop3_b32 v4, v2, s8, v3 bitop3:0xde
	s_add_i32 m0, s19, 0x18000
	v_lshl_add_u64 v[2:3], s[12:13], 0, v[142:143]
	s_waitcnt vmcnt(2)
	s_barrier
	global_load_lds_dwordx4 v[2:3], off
	s_add_i32 m0, s19, 0x1a000
	v_lshl_add_u64 v[2:3], s[12:13], 0, v[146:147]
	s_add_u32 s12, s6, 0x8000
	s_addc_u32 s13, s7, 0
	s_add_i32 s24, s19, 0x8000
	global_load_lds_dwordx4 v[2:3], off
	v_lshl_add_u64 v[2:3], s[12:13], 0, v[140:141]
	s_mov_b32 m0, s24
	s_add_i32 s25, s19, 0xa000
	global_load_lds_dwordx4 v[2:3], off
	v_lshl_add_u64 v[2:3], s[12:13], 0, v[144:145]
	s_add_u32 s12, s0, 0xc000
	s_mov_b32 m0, s25
	s_addc_u32 s13, s1, 0
	global_load_lds_dwordx4 v[2:3], off
	s_add_i32 m0, s19, 0x1c000
	v_lshl_add_u64 v[2:3], s[12:13], 0, v[142:143]
	global_load_lds_dwordx4 v[2:3], off
	v_lshl_add_u64 v[2:3], s[12:13], 0, v[146:147]
	s_add_i32 m0, s19, 0x1e000
	v_readlane_b32 s3, v252, 7
	global_load_lds_dwordx4 v[2:3], off
	v_and_b32_e32 v2, 0x1800, v150
	v_lshlrev_b32_e32 v6, 7, v153
	s_add_u32 s8, s3, s10
	v_readlane_b32 s3, v252, 8
	v_or3_b32 v2, v1, v2, v6
	s_addc_u32 s9, s3, s9
	v_add_u32_e32 v2, v2, v152
	v_mov_b32_e32 v3, v143
	v_readlane_b32 s10, v252, 9
	v_lshl_add_u64 v[2:3], s[8:9], 0, v[2:3]
	s_mul_hi_i32 s3, s10, 0x160000
	s_mul_i32 s10, s10, 0x160000
	v_mov_b32_e32 v7, s3
	v_subrev_co_u32_e32 v2, vcc, s10, v2
	v_lshl_or_b32 v5, s23, 7, v156
	s_nop 0
	v_subb_co_u32_e32 v3, vcc, v3, v7, vcc
	v_lshl_add_u64 v[148:149], s[78:79], 0, v[2:3]
	v_and_b32_e32 v2, 0x3800, v154
	v_or3_b32 v2, v1, v2, v6
	v_add_u32_e32 v2, v2, v152
	v_mov_b32_e32 v3, v143
	v_lshl_add_u64 v[2:3], s[8:9], 0, v[2:3]
	s_waitcnt vmcnt(6)
	v_mov_b32_e32 v6, s3
	v_subrev_co_u32_e32 v2, vcc, s10, v2
	s_add_i32 s29, 0, 0x10000
	s_add_i32 s31, 0, 0x14000
	s_add_i32 s35, 0, 0x18000
	s_add_i32 s37, 0, 0x1c000
	v_subb_co_u32_e32 v3, vcc, v3, v6, vcc
	v_add_u32_e32 v133, s29, v5
	v_add_u32_e32 v135, s31, v5
	s_add_i32 s29, s29, s2
	s_add_i32 s31, s31, s2
	v_add_u32_e32 v139, s35, v5
	v_add_u32_e32 v158, s37, v5
	s_add_i32 s35, s35, s2
	s_add_i32 s37, s37, s2
	v_lshl_add_u64 v[150:151], s[78:79], 0, v[2:3]
	s_mov_b32 s26, -2
	s_mov_b64 s[8:9], 0x10000
	v_add_u32_e32 v137, 0, v4
	s_mov_b64 s[10:11], 0x87fc000
	s_add_i32 s27, s19, 0xc000
	s_add_i32 s28, s19, 0xe000
	s_add_i32 s30, s29, 0x2000
	s_add_i32 s34, s31, 0x2000
	s_add_i32 s36, s35, 0x2000
	s_add_i32 s38, s37, 0x2000
	v_mov_b32_e32 v2, v143
	v_mov_b32_e32 v3, v143
	v_mov_b32_e32 v4, v143
	v_mov_b32_e32 v5, v143
	v_mov_b32_e32 v6, v143
	v_mov_b32_e32 v7, v143
	v_mov_b32_e32 v8, v143
	v_mov_b32_e32 v9, v143
	v_mov_b32_e32 v14, v143
	v_mov_b32_e32 v15, v143
	v_mov_b32_e32 v16, v143
	v_mov_b32_e32 v17, v143
	s_waitcnt vmcnt(0)
	v_mov_b32_e32 v22, v143
	v_mov_b32_e32 v23, v143
	v_mov_b32_e32 v24, v143
	v_mov_b32_e32 v25, v143
	v_mov_b32_e32 v30, v143
	v_mov_b32_e32 v31, v143
	v_mov_b32_e32 v32, v143
	v_mov_b32_e32 v33, v143
	v_mov_b32_e32 v38, v143
	v_mov_b32_e32 v39, v143
	v_mov_b32_e32 v40, v143
	v_mov_b32_e32 v41, v143
	v_mov_b32_e32 v46, v143
	v_mov_b32_e32 v47, v143
	v_mov_b32_e32 v48, v143
	v_mov_b32_e32 v49, v143
	v_mov_b32_e32 v54, v143
	v_mov_b32_e32 v55, v143
	v_mov_b32_e32 v56, v143
	v_mov_b32_e32 v57, v143
	v_mov_b32_e32 v10, v143
	v_mov_b32_e32 v11, v143
	v_mov_b32_e32 v12, v143
	v_mov_b32_e32 v13, v143
	v_mov_b32_e32 v18, v143
	v_mov_b32_e32 v19, v143
	v_mov_b32_e32 v20, v143
	v_mov_b32_e32 v21, v143
	v_mov_b32_e32 v26, v143
	v_mov_b32_e32 v27, v143
	v_mov_b32_e32 v28, v143
	v_mov_b32_e32 v29, v143
	v_mov_b32_e32 v34, v143
	v_mov_b32_e32 v35, v143
	v_mov_b32_e32 v36, v143
	v_mov_b32_e32 v37, v143
	v_mov_b32_e32 v42, v143
	v_mov_b32_e32 v43, v143
	v_mov_b32_e32 v44, v143
	v_mov_b32_e32 v45, v143
	v_mov_b32_e32 v50, v143
	v_mov_b32_e32 v51, v143
	v_mov_b32_e32 v52, v143
	v_mov_b32_e32 v53, v143
	v_mov_b32_e32 v58, v143
	v_mov_b32_e32 v59, v143
	v_mov_b32_e32 v60, v143
	v_mov_b32_e32 v61, v143
	v_mov_b32_e32 v62, v143
	v_mov_b32_e32 v63, v143
	v_mov_b32_e32 v64, v143
	v_mov_b32_e32 v65, v143
	v_mov_b32_e32 v66, v143
	v_mov_b32_e32 v67, v143
	v_mov_b32_e32 v68, v143
	v_mov_b32_e32 v69, v143
	v_mov_b32_e32 v70, v143
	v_mov_b32_e32 v71, v143
	v_mov_b32_e32 v72, v143
	v_mov_b32_e32 v73, v143
	v_mov_b32_e32 v78, v143
	v_mov_b32_e32 v79, v143
	v_mov_b32_e32 v80, v143
	v_mov_b32_e32 v81, v143
	v_mov_b32_e32 v86, v143
	v_mov_b32_e32 v87, v143
	v_mov_b32_e32 v88, v143
	v_mov_b32_e32 v89, v143
	v_mov_b32_e32 v94, v143
	v_mov_b32_e32 v95, v143
	v_mov_b32_e32 v96, v143
	v_mov_b32_e32 v97, v143
	v_mov_b32_e32 v102, v143
	v_mov_b32_e32 v103, v143
	v_mov_b32_e32 v104, v143
	v_mov_b32_e32 v105, v143
	v_mov_b32_e32 v110, v143
	v_mov_b32_e32 v111, v143
	v_mov_b32_e32 v112, v143
	v_mov_b32_e32 v113, v143
	v_mov_b32_e32 v118, v143
	v_mov_b32_e32 v119, v143
	v_mov_b32_e32 v120, v143
	v_mov_b32_e32 v121, v143
	v_mov_b32_e32 v74, v143
	v_mov_b32_e32 v75, v143
	v_mov_b32_e32 v76, v143
	v_mov_b32_e32 v77, v143
	v_mov_b32_e32 v82, v143
	v_mov_b32_e32 v83, v143
	v_mov_b32_e32 v84, v143
	v_mov_b32_e32 v85, v143
	v_mov_b32_e32 v90, v143
	v_mov_b32_e32 v91, v143
	v_mov_b32_e32 v92, v143
	v_mov_b32_e32 v93, v143
	v_mov_b32_e32 v98, v143
	v_mov_b32_e32 v99, v143
	v_mov_b32_e32 v100, v143
	v_mov_b32_e32 v101, v143
	v_mov_b32_e32 v106, v143
	v_mov_b32_e32 v107, v143
	v_mov_b32_e32 v108, v143
	v_mov_b32_e32 v109, v143
	v_mov_b32_e32 v114, v143
	v_mov_b32_e32 v115, v143
	v_mov_b32_e32 v116, v143
	v_mov_b32_e32 v117, v143
	v_mov_b32_e32 v122, v143
	v_mov_b32_e32 v123, v143
	v_mov_b32_e32 v124, v143
	v_mov_b32_e32 v125, v143
	v_mov_b32_e32 v126, v143
	v_mov_b32_e32 v127, v143
	v_mov_b32_e32 v128, v143
	v_mov_b32_e32 v129, v143
	s_barrier
	s_branch .LBB0_1386
	.p2align 6

.LBB0_1399:
	s_lshl_b64 s[2:3], s[14:15], 1
	v_readlane_b32 s20, v253, 52
	v_readlane_b32 s21, v253, 53
	s_add_u32 s20, s20, s2
	s_addc_u32 s21, s21, s3
	s_and_b64 s[2:3], s[18:19], exec
	s_cselect_b32 s11, s21, s29
	s_cselect_b32 s13, s20, s28
	s_lshl_b64 s[2:3], s[16:17], 1
	s_add_u32 s22, s48, s2
	s_addc_u32 s23, s49, s3
	s_and_b64 s[2:3], s[18:19], exec
	s_cselect_b32 s47, s23, s31
	s_cselect_b32 s52, s22, s30
	s_add_u32 s28, s28, 0x40080
	s_addc_u32 s29, s29, 0
	s_add_u32 s53, s30, 0x100
	s_addc_u32 s54, s31, 0
	s_mov_b32 s55, -2
	s_branch .Lpk1400_peel
	.p2align 6
.Lpk1400_peel:
	ds_read_b128 v[152:155], v1
	ds_read_b128 v[156:159], v1 offset:1024
	ds_read_b128 v[160:163], v1 offset:2048
	ds_read_b128 v[164:167], v1 offset:3072
	ds_read_b128 v[168:171], v149
	ds_read_b128 v[172:175], v149 offset:1024
	ds_read_b128 v[178:181], v149 offset:2048
	ds_read_b128 v[182:185], v149 offset:3072
	s_add_u32 s2, s28, 0xfffc0080
	s_addc_u32 s3, s29, -1
	s_cmp_eq_u32 s55, 12
	s_cselect_b32 s3, s11, s3
	s_cselect_b32 s2, s13, s2
	s_cselect_b32 s31, s47, s54
	s_cselect_b32 s30, s52, s53
	v_lshl_add_u64 v[146:147], s[28:29], 0, v[140:141]
	s_add_i32 m0, s25, 0xc000
	ds_read_b128 v[186:189], v150
	ds_read_b128 v[190:193], v150 offset:1024
	ds_read_b128 v[194:197], v150 offset:2048
	ds_read_b128 v[198:201], v150 offset:3072
	ds_read_b128 v[202:205], v150 offset:4096
	ds_read_b128 v[206:209], v150 offset:5120
	ds_read_b128 v[210:213], v150 offset:6144
	ds_read_b128 v[214:217], v150 offset:7168
	global_load_lds_dwordx4 v[146:147], off
	v_lshl_add_u64 v[146:147], s[28:29], 0, v[142:143]
	s_add_i32 m0, s25, 0xe000
	s_nop 0
	global_load_lds_dwordx4 v[146:147], off
	s_waitcnt vmcnt(8)
	s_waitcnt lgkmcnt(0)
	s_barrier
	s_setprio 1
	s_waitcnt lgkmcnt(0)
	v_mfma_f32_16x16x32_bf16 v[126:129], v[152:155], v[186:189], 0
	v_mfma_f32_16x16x32_bf16 v[122:125], v[160:163], v[186:189], 0
	v_mfma_f32_16x16x32_bf16 v[110:113], v[152:155], v[194:197], 0
	v_mfma_f32_16x16x32_bf16 v[106:109], v[160:163], v[194:197], 0
	v_mfma_f32_16x16x32_bf16 v[94:97], v[152:155], v[202:205], 0
	v_mfma_f32_16x16x32_bf16 v[90:93], v[160:163], v[202:205], 0
	v_mfma_f32_16x16x32_bf16 v[78:81], v[152:155], v[210:213], 0
	v_mfma_f32_16x16x32_bf16 v[74:77], v[160:163], v[210:213], 0
	v_mfma_f32_16x16x32_bf16 v[126:129], v[156:159], v[190:193], v[126:129]
	v_mfma_f32_16x16x32_bf16 v[122:125], v[164:167], v[190:193], v[122:125]
	v_mfma_f32_16x16x32_bf16 v[110:113], v[156:159], v[198:201], v[110:113]
	v_mfma_f32_16x16x32_bf16 v[106:109], v[164:167], v[198:201], v[106:109]
	v_mfma_f32_16x16x32_bf16 v[94:97], v[156:159], v[206:209], v[94:97]
	v_mfma_f32_16x16x32_bf16 v[90:93], v[164:167], v[206:209], v[90:93]
	v_mfma_f32_16x16x32_bf16 v[78:81], v[156:159], v[214:217], v[78:81]
	v_mfma_f32_16x16x32_bf16 v[74:77], v[164:167], v[214:217], v[74:77]
	s_setprio 0
	s_setprio 1
	v_mfma_f32_16x16x32_bf16 v[118:121], v[168:171], v[186:189], 0
	v_mfma_f32_16x16x32_bf16 v[114:117], v[178:181], v[186:189], 0
	v_mfma_f32_16x16x32_bf16 v[102:105], v[168:171], v[194:197], 0
	v_mfma_f32_16x16x32_bf16 v[98:101], v[178:181], v[194:197], 0
	v_mfma_f32_16x16x32_bf16 v[86:89], v[168:171], v[202:205], 0
	v_mfma_f32_16x16x32_bf16 v[82:85], v[178:181], v[202:205], 0
	v_mfma_f32_16x16x32_bf16 v[70:73], v[168:171], v[210:213], 0
	v_mfma_f32_16x16x32_bf16 v[66:69], v[178:181], v[210:213], 0
	v_mfma_f32_16x16x32_bf16 v[118:121], v[172:175], v[190:193], v[118:121]
	v_mfma_f32_16x16x32_bf16 v[114:117], v[182:185], v[190:193], v[114:117]
	v_mfma_f32_16x16x32_bf16 v[102:105], v[172:175], v[198:201], v[102:105]
	v_mfma_f32_16x16x32_bf16 v[98:101], v[182:185], v[198:201], v[98:101]
	v_mfma_f32_16x16x32_bf16 v[86:89], v[172:175], v[206:209], v[86:89]
	v_mfma_f32_16x16x32_bf16 v[82:85], v[182:185], v[206:209], v[82:85]
	v_mfma_f32_16x16x32_bf16 v[70:73], v[172:175], v[214:217], v[70:73]
	v_mfma_f32_16x16x32_bf16 v[66:69], v[182:185], v[214:217], v[66:69]
	s_setprio 0
	s_barrier
	s_add_i32 s56, s43, s34
	v_lshl_add_u64 v[146:147], s[30:31], 0, v[132:133]
	s_mov_b32 m0, s56
	ds_read_b128 v[186:189], v150 offset:16384
	ds_read_b128 v[190:193], v150 offset:17408
	ds_read_b128 v[194:197], v150 offset:18432
	ds_read_b128 v[198:201], v150 offset:19456
	ds_read_b128 v[202:205], v150 offset:20480
	ds_read_b128 v[206:209], v150 offset:21504
	ds_read_b128 v[210:213], v150 offset:22528
	ds_read_b128 v[214:217], v150 offset:23552
	global_load_lds_dwordx4 v[146:147], off
	s_add_i32 m0, s56, 0x2000
	s_add_u32 s56, s30, 0x40000
	v_lshl_add_u64 v[218:219], s[30:31], 0, v[136:137]
	s_addc_u32 s57, s31, 0
	s_add_i32 s58, s44, s34
	global_load_lds_dwordx4 v[218:219], off
	v_lshl_add_u64 v[220:221], s[56:57], 0, v[132:133]
	s_mov_b32 m0, s58
	v_lshl_add_u64 v[222:223], s[2:3], 0, v[134:135]
	global_load_lds_dwordx4 v[220:221], off
	v_lshl_add_u64 v[220:221], s[56:57], 0, v[136:137]
	s_add_i32 m0, s58, 0x2000
	s_nop 0
	global_load_lds_dwordx4 v[220:221], off
	v_lshl_add_u64 v[220:221], s[2:3], 0, v[130:131]
	s_mov_b32 m0, s25
	s_nop 0
	global_load_lds_dwordx4 v[220:221], off
	s_mov_b32 m0, s27
	s_nop 0
	global_load_lds_dwordx4 v[222:223], off
	s_waitcnt vmcnt(8)
	s_waitcnt lgkmcnt(0)
	s_barrier
	s_setprio 1
	s_waitcnt lgkmcnt(0)
	v_mfma_f32_16x16x32_bf16 v[62:65], v[152:155], v[186:189], 0
	v_mfma_f32_16x16x32_bf16 v[58:61], v[160:163], v[186:189], 0
	v_mfma_f32_16x16x32_bf16 v[46:49], v[152:155], v[194:197], 0
	v_mfma_f32_16x16x32_bf16 v[42:45], v[160:163], v[194:197], 0
	v_mfma_f32_16x16x32_bf16 v[30:33], v[152:155], v[202:205], 0
	v_mfma_f32_16x16x32_bf16 v[26:29], v[160:163], v[202:205], 0
	v_mfma_f32_16x16x32_bf16 v[14:17], v[152:155], v[210:213], 0
	v_mfma_f32_16x16x32_bf16 v[10:13], v[160:163], v[210:213], 0
	v_mfma_f32_16x16x32_bf16 v[62:65], v[156:159], v[190:193], v[62:65]
	v_mfma_f32_16x16x32_bf16 v[58:61], v[164:167], v[190:193], v[58:61]
	v_mfma_f32_16x16x32_bf16 v[46:49], v[156:159], v[198:201], v[46:49]
	v_mfma_f32_16x16x32_bf16 v[42:45], v[164:167], v[198:201], v[42:45]
	v_mfma_f32_16x16x32_bf16 v[30:33], v[156:159], v[206:209], v[30:33]
	v_mfma_f32_16x16x32_bf16 v[26:29], v[164:167], v[206:209], v[26:29]
	v_mfma_f32_16x16x32_bf16 v[14:17], v[156:159], v[214:217], v[14:17]
	v_mfma_f32_16x16x32_bf16 v[10:13], v[164:167], v[214:217], v[10:13]
	s_setprio 0
	s_setprio 1
	v_mfma_f32_16x16x32_bf16 v[54:57], v[168:171], v[186:189], 0
	v_mfma_f32_16x16x32_bf16 v[50:53], v[178:181], v[186:189], 0
	v_mfma_f32_16x16x32_bf16 v[38:41], v[168:171], v[194:197], 0
	v_mfma_f32_16x16x32_bf16 v[34:37], v[178:181], v[194:197], 0
	v_mfma_f32_16x16x32_bf16 v[22:25], v[168:171], v[202:205], 0
	v_mfma_f32_16x16x32_bf16 v[18:21], v[178:181], v[202:205], 0
	v_mfma_f32_16x16x32_bf16 v[6:9], v[168:171], v[210:213], 0
	v_mfma_f32_16x16x32_bf16 v[2:5], v[178:181], v[210:213], 0
	v_mfma_f32_16x16x32_bf16 v[54:57], v[172:175], v[190:193], v[54:57]
	v_mfma_f32_16x16x32_bf16 v[50:53], v[182:185], v[190:193], v[50:53]
	v_mfma_f32_16x16x32_bf16 v[38:41], v[172:175], v[198:201], v[38:41]
	v_mfma_f32_16x16x32_bf16 v[34:37], v[182:185], v[198:201], v[34:37]
	v_mfma_f32_16x16x32_bf16 v[22:25], v[172:175], v[206:209], v[22:25]
	v_mfma_f32_16x16x32_bf16 v[18:21], v[182:185], v[206:209], v[18:21]
	v_mfma_f32_16x16x32_bf16 v[6:9], v[172:175], v[214:217], v[6:9]
	v_mfma_f32_16x16x32_bf16 v[2:5], v[182:185], v[214:217], v[2:5]
	s_setprio 0
	s_barrier
	s_add_i32 s56, 0, 0x18000
	v_add_u32_e32 v151, s56, v148
	s_add_i32 s57, 0, 0x1c000
	ds_read_b128 v[152:155], v151
	ds_read_b128 v[156:159], v151 offset:1024
	ds_read_b128 v[160:163], v151 offset:2048
	ds_read_b128 v[164:167], v151 offset:3072
	v_add_u32_e32 v151, s57, v148
	ds_read_b128 v[168:171], v151
	ds_read_b128 v[172:175], v151 offset:1024
	ds_read_b128 v[178:181], v151 offset:2048
	ds_read_b128 v[182:185], v151 offset:3072
	s_add_u32 s2, s2, 0x40000
	s_addc_u32 s3, s3, 0
	s_mov_b32 m0, s36
	v_lshl_add_u64 v[224:225], s[2:3], 0, v[130:131]
	ds_read_b128 v[186:189], v150 offset:32768
	ds_read_b128 v[190:193], v150 offset:33792
	ds_read_b128 v[194:197], v150 offset:34816
	ds_read_b128 v[198:201], v150 offset:35840
	ds_read_b128 v[202:205], v150 offset:36864
	ds_read_b128 v[206:209], v150 offset:37888
	ds_read_b128 v[210:213], v150 offset:38912
	ds_read_b128 v[214:217], v150 offset:39936
	global_load_lds_dwordx4 v[224:225], off
	v_lshl_add_u64 v[224:225], s[2:3], 0, v[134:135]
	s_mov_b32 m0, s37
	s_nop 0
	global_load_lds_dwordx4 v[224:225], off
	s_waitcnt vmcnt(8)
	s_waitcnt lgkmcnt(0)
	s_barrier
	s_setprio 1
	s_waitcnt lgkmcnt(0)
	v_mfma_f32_16x16x32_bf16 v[126:129], v[152:155], v[186:189], v[126:129]
	v_mfma_f32_16x16x32_bf16 v[122:125], v[160:163], v[186:189], v[122:125]
	v_mfma_f32_16x16x32_bf16 v[110:113], v[152:155], v[194:197], v[110:113]
	v_mfma_f32_16x16x32_bf16 v[106:109], v[160:163], v[194:197], v[106:109]
	v_mfma_f32_16x16x32_bf16 v[94:97], v[152:155], v[202:205], v[94:97]
	v_mfma_f32_16x16x32_bf16 v[90:93], v[160:163], v[202:205], v[90:93]
	v_mfma_f32_16x16x32_bf16 v[78:81], v[152:155], v[210:213], v[78:81]
	v_mfma_f32_16x16x32_bf16 v[74:77], v[160:163], v[210:213], v[74:77]
	v_mfma_f32_16x16x32_bf16 v[126:129], v[156:159], v[190:193], v[126:129]
	v_mfma_f32_16x16x32_bf16 v[122:125], v[164:167], v[190:193], v[122:125]
	v_mfma_f32_16x16x32_bf16 v[110:113], v[156:159], v[198:201], v[110:113]
	v_mfma_f32_16x16x32_bf16 v[106:109], v[164:167], v[198:201], v[106:109]
	v_mfma_f32_16x16x32_bf16 v[94:97], v[156:159], v[206:209], v[94:97]
	v_mfma_f32_16x16x32_bf16 v[90:93], v[164:167], v[206:209], v[90:93]
	v_mfma_f32_16x16x32_bf16 v[78:81], v[156:159], v[214:217], v[78:81]
	v_mfma_f32_16x16x32_bf16 v[74:77], v[164:167], v[214:217], v[74:77]
	s_setprio 0
	s_setprio 1
	v_mfma_f32_16x16x32_bf16 v[118:121], v[168:171], v[186:189], v[118:121]
	v_mfma_f32_16x16x32_bf16 v[114:117], v[178:181], v[186:189], v[114:117]
	v_mfma_f32_16x16x32_bf16 v[102:105], v[168:171], v[194:197], v[102:105]
	v_mfma_f32_16x16x32_bf16 v[98:101], v[178:181], v[194:197], v[98:101]
	v_mfma_f32_16x16x32_bf16 v[86:89], v[168:171], v[202:205], v[86:89]
	v_mfma_f32_16x16x32_bf16 v[82:85], v[178:181], v[202:205], v[82:85]
	v_mfma_f32_16x16x32_bf16 v[70:73], v[168:171], v[210:213], v[70:73]
	v_mfma_f32_16x16x32_bf16 v[66:69], v[178:181], v[210:213], v[66:69]
	v_mfma_f32_16x16x32_bf16 v[118:121], v[172:175], v[190:193], v[118:121]
	v_mfma_f32_16x16x32_bf16 v[114:117], v[182:185], v[190:193], v[114:117]
	v_mfma_f32_16x16x32_bf16 v[102:105], v[172:175], v[198:201], v[102:105]
	v_mfma_f32_16x16x32_bf16 v[98:101], v[182:185], v[198:201], v[98:101]
	v_mfma_f32_16x16x32_bf16 v[86:89], v[172:175], v[206:209], v[86:89]
	v_mfma_f32_16x16x32_bf16 v[82:85], v[182:185], v[206:209], v[82:85]
	v_mfma_f32_16x16x32_bf16 v[70:73], v[172:175], v[214:217], v[70:73]
	v_mfma_f32_16x16x32_bf16 v[66:69], v[182:185], v[214:217], v[66:69]
	s_setprio 0
	s_barrier
	s_add_i32 s2, s56, s34
	v_lshl_add_u64 v[146:147], v[146:147], 0, s[6:7]
	s_mov_b32 m0, s2
	ds_read_b128 v[186:189], v150 offset:49152
	ds_read_b128 v[190:193], v150 offset:50176
	ds_read_b128 v[194:197], v150 offset:51200
	ds_read_b128 v[198:201], v150 offset:52224
	ds_read_b128 v[202:205], v150 offset:53248
	ds_read_b128 v[206:209], v150 offset:54272
	ds_read_b128 v[210:213], v150 offset:55296
	ds_read_b128 v[214:217], v150 offset:56320
	global_load_lds_dwordx4 v[146:147], off
	s_add_i32 m0, s2, 0x2000
	s_add_u32 s2, s30, 0x40080
	v_lshl_add_u64 v[146:147], v[218:219], 0, s[6:7]
	s_addc_u32 s3, s31, 0
	s_add_i32 s30, s57, s34
	global_load_lds_dwordx4 v[146:147], off
	v_lshl_add_u64 v[146:147], s[2:3], 0, v[132:133]
	s_mov_b32 m0, s30
	s_nop 0
	global_load_lds_dwordx4 v[146:147], off
	v_lshl_add_u64 v[146:147], s[2:3], 0, v[136:137]
	s_add_i32 m0, s30, 0x2000
	s_nop 0
	global_load_lds_dwordx4 v[146:147], off
	v_lshl_add_u64 v[146:147], v[220:221], 0, s[6:7]
	s_mov_b32 m0, s40
	s_nop 0
	global_load_lds_dwordx4 v[146:147], off
	v_lshl_add_u64 v[146:147], v[222:223], 0, s[6:7]
	s_mov_b32 m0, s41
	s_nop 0
	global_load_lds_dwordx4 v[146:147], off
	s_waitcnt vmcnt(8)
	s_waitcnt lgkmcnt(0)
	s_barrier
	s_setprio 1
	s_waitcnt lgkmcnt(0)
	v_mfma_f32_16x16x32_bf16 v[62:65], v[152:155], v[186:189], v[62:65]
	v_mfma_f32_16x16x32_bf16 v[58:61], v[160:163], v[186:189], v[58:61]
	v_mfma_f32_16x16x32_bf16 v[46:49], v[152:155], v[194:197], v[46:49]
	v_mfma_f32_16x16x32_bf16 v[42:45], v[160:163], v[194:197], v[42:45]
	v_mfma_f32_16x16x32_bf16 v[30:33], v[152:155], v[202:205], v[30:33]
	v_mfma_f32_16x16x32_bf16 v[26:29], v[160:163], v[202:205], v[26:29]
	v_mfma_f32_16x16x32_bf16 v[14:17], v[152:155], v[210:213], v[14:17]
	v_mfma_f32_16x16x32_bf16 v[10:13], v[160:163], v[210:213], v[10:13]
	v_mfma_f32_16x16x32_bf16 v[62:65], v[156:159], v[190:193], v[62:65]
	v_mfma_f32_16x16x32_bf16 v[58:61], v[164:167], v[190:193], v[58:61]
	v_mfma_f32_16x16x32_bf16 v[46:49], v[156:159], v[198:201], v[46:49]
	v_mfma_f32_16x16x32_bf16 v[42:45], v[164:167], v[198:201], v[42:45]
	v_mfma_f32_16x16x32_bf16 v[30:33], v[156:159], v[206:209], v[30:33]
	v_mfma_f32_16x16x32_bf16 v[26:29], v[164:167], v[206:209], v[26:29]
	v_mfma_f32_16x16x32_bf16 v[14:17], v[156:159], v[214:217], v[14:17]
	v_mfma_f32_16x16x32_bf16 v[10:13], v[164:167], v[214:217], v[10:13]
	s_setprio 0
	s_setprio 1
	v_mfma_f32_16x16x32_bf16 v[54:57], v[168:171], v[186:189], v[54:57]
	v_mfma_f32_16x16x32_bf16 v[50:53], v[178:181], v[186:189], v[50:53]
	v_mfma_f32_16x16x32_bf16 v[38:41], v[168:171], v[194:197], v[38:41]
	v_mfma_f32_16x16x32_bf16 v[34:37], v[178:181], v[194:197], v[34:37]
	v_mfma_f32_16x16x32_bf16 v[22:25], v[168:171], v[202:205], v[22:25]
	v_mfma_f32_16x16x32_bf16 v[18:21], v[178:181], v[202:205], v[18:21]
	v_mfma_f32_16x16x32_bf16 v[6:9], v[168:171], v[210:213], v[6:9]
	v_mfma_f32_16x16x32_bf16 v[2:5], v[178:181], v[210:213], v[2:5]
	v_mfma_f32_16x16x32_bf16 v[54:57], v[172:175], v[190:193], v[54:57]
	v_mfma_f32_16x16x32_bf16 v[50:53], v[182:185], v[190:193], v[50:53]
	v_mfma_f32_16x16x32_bf16 v[38:41], v[172:175], v[198:201], v[38:41]
	v_mfma_f32_16x16x32_bf16 v[34:37], v[182:185], v[198:201], v[34:37]
	v_mfma_f32_16x16x32_bf16 v[22:25], v[172:175], v[206:209], v[22:25]
	v_mfma_f32_16x16x32_bf16 v[18:21], v[182:185], v[206:209], v[18:21]
	v_mfma_f32_16x16x32_bf16 v[6:9], v[172:175], v[214:217], v[6:9]
	v_mfma_f32_16x16x32_bf16 v[2:5], v[182:185], v[214:217], v[2:5]
	s_setprio 0
	s_barrier
	s_add_i32 s55, s55, 2
	s_add_u32 s28, s28, 0x100
	s_addc_u32 s29, s29, 0
	s_add_u32 s53, s53, 0x100
	s_addc_u32 s54, s54, 0
	s_cmp_gt_u32 s55, 13
	s_cbranch_scc0 .LBB0_1400
	s_branch .Lpk1400_exit
	s_branch .LBB0_1400
	.p2align 6

.LBB0_1443:
	s_lshl_b64 s[2:3], s[16:17], 1
	v_readlane_b32 s22, v253, 54
	s_add_u32 s22, s22, s2
	v_readlane_b32 s2, v253, 7
	s_addc_u32 s23, s2, s3
	s_and_b64 s[2:3], s[20:21], exec
	s_cselect_b32 s56, s23, s27
	s_cselect_b32 s57, s22, s26
	s_lshl_b64 s[2:3], s[18:19], 1
	s_add_u32 s24, s36, s2
	s_addc_u32 s25, s37, s3
	s_and_b64 s[2:3], s[20:21], exec
	s_cselect_b32 s58, s25, s29
	s_cselect_b32 s59, s24, s28
	s_add_u32 s26, s26, 0xc000
	s_addc_u32 s27, s27, 0
	s_add_u32 s60, s28, 0x10000
	s_addc_u32 s61, s29, 0
	s_mov_b32 s62, -2
	s_branch .Lpk1444_peel
	.p2align 6
.Lpk1444_peel:
	ds_read_b128 v[152:155], v148
	ds_read_b128 v[156:159], v148 offset:1024
	ds_read_b128 v[160:163], v148 offset:2048
	ds_read_b128 v[164:167], v148 offset:3072
	ds_read_b128 v[168:171], v149
	ds_read_b128 v[172:175], v149 offset:1024
	ds_read_b128 v[178:181], v149 offset:2048
	ds_read_b128 v[182:185], v149 offset:3072
	s_add_u32 s2, s26, 0x4000
	s_addc_u32 s3, s27, 0
	s_cmp_eq_u32 s62, 40
	s_cselect_b32 s2, s57, s2
	s_cselect_b32 s3, s56, s3
	s_cselect_b32 s31, s58, s61
	s_cselect_b32 s30, s59, s60
	s_add_u32 s28, s2, 0x8000
	s_addc_u32 s29, s3, 0
	v_lshl_add_u64 v[144:145], s[26:27], 0, v[138:139]
	s_add_i32 m0, s39, 0xc000
	ds_read_b128 v[186:189], v150
	ds_read_b128 v[190:193], v150 offset:1024
	ds_read_b128 v[194:197], v150 offset:2048
	ds_read_b128 v[198:201], v150 offset:3072
	ds_read_b128 v[202:205], v150 offset:4096
	ds_read_b128 v[206:209], v150 offset:5120
	ds_read_b128 v[210:213], v150 offset:6144
	ds_read_b128 v[214:217], v150 offset:7168
	global_load_lds_dwordx4 v[144:145], off
	v_lshl_add_u64 v[144:145], s[26:27], 0, v[140:141]
	s_add_i32 m0, s39, 0xe000
	s_nop 0
	global_load_lds_dwordx4 v[144:145], off
	s_waitcnt vmcnt(8)
	s_waitcnt lgkmcnt(0)
	s_barrier
	s_setprio 1
	s_waitcnt lgkmcnt(0)
	v_mfma_f32_16x16x32_bf16 v[126:129], v[152:155], v[186:189], 0
	v_mfma_f32_16x16x32_bf16 v[122:125], v[160:163], v[186:189], 0
	v_mfma_f32_16x16x32_bf16 v[114:117], v[152:155], v[194:197], 0
	v_mfma_f32_16x16x32_bf16 v[106:109], v[160:163], v[194:197], 0
	v_mfma_f32_16x16x32_bf16 v[98:101], v[152:155], v[202:205], 0
	v_mfma_f32_16x16x32_bf16 v[90:93], v[160:163], v[202:205], 0
	v_mfma_f32_16x16x32_bf16 v[82:85], v[152:155], v[210:213], 0
	v_mfma_f32_16x16x32_bf16 v[74:77], v[160:163], v[210:213], 0
	v_mfma_f32_16x16x32_bf16 v[126:129], v[156:159], v[190:193], v[126:129]
	v_mfma_f32_16x16x32_bf16 v[122:125], v[164:167], v[190:193], v[122:125]
	v_mfma_f32_16x16x32_bf16 v[114:117], v[156:159], v[198:201], v[114:117]
	v_mfma_f32_16x16x32_bf16 v[106:109], v[164:167], v[198:201], v[106:109]
	v_mfma_f32_16x16x32_bf16 v[98:101], v[156:159], v[206:209], v[98:101]
	v_mfma_f32_16x16x32_bf16 v[90:93], v[164:167], v[206:209], v[90:93]
	v_mfma_f32_16x16x32_bf16 v[82:85], v[156:159], v[214:217], v[82:85]
	v_mfma_f32_16x16x32_bf16 v[74:77], v[164:167], v[214:217], v[74:77]
	s_setprio 0
	s_setprio 1
	v_mfma_f32_16x16x32_bf16 v[118:121], v[168:171], v[186:189], 0
	v_mfma_f32_16x16x32_bf16 v[110:113], v[178:181], v[186:189], 0
	v_mfma_f32_16x16x32_bf16 v[102:105], v[168:171], v[194:197], 0
	v_mfma_f32_16x16x32_bf16 v[94:97], v[178:181], v[194:197], 0
	v_mfma_f32_16x16x32_bf16 v[86:89], v[168:171], v[202:205], 0
	v_mfma_f32_16x16x32_bf16 v[78:81], v[178:181], v[202:205], 0
	v_mfma_f32_16x16x32_bf16 v[70:73], v[168:171], v[210:213], 0
	v_mfma_f32_16x16x32_bf16 v[66:69], v[178:181], v[210:213], 0
	v_mfma_f32_16x16x32_bf16 v[118:121], v[172:175], v[190:193], v[118:121]
	v_mfma_f32_16x16x32_bf16 v[110:113], v[182:185], v[190:193], v[110:113]
	v_mfma_f32_16x16x32_bf16 v[102:105], v[172:175], v[198:201], v[102:105]
	v_mfma_f32_16x16x32_bf16 v[94:97], v[182:185], v[198:201], v[94:97]
	v_mfma_f32_16x16x32_bf16 v[86:89], v[172:175], v[206:209], v[86:89]
	v_mfma_f32_16x16x32_bf16 v[78:81], v[182:185], v[206:209], v[78:81]
	v_mfma_f32_16x16x32_bf16 v[70:73], v[172:175], v[214:217], v[70:73]
	v_mfma_f32_16x16x32_bf16 v[66:69], v[182:185], v[214:217], v[66:69]
	s_setprio 0
	s_barrier
	s_add_i32 s63, s46, s38
	v_lshl_add_u64 v[144:145], s[30:31], 0, v[132:133]
	s_mov_b32 m0, s63
	ds_read_b128 v[186:189], v150 offset:16384
	ds_read_b128 v[190:193], v150 offset:17408
	ds_read_b128 v[194:197], v150 offset:18432
	ds_read_b128 v[198:201], v150 offset:19456
	ds_read_b128 v[202:205], v150 offset:20480
	ds_read_b128 v[206:209], v150 offset:21504
	ds_read_b128 v[210:213], v150 offset:22528
	ds_read_b128 v[214:217], v150 offset:23552
	global_load_lds_dwordx4 v[144:145], off
	s_add_i32 m0, s63, 0x2000
	s_add_u32 s64, s30, 0x4000
	v_lshl_add_u64 v[144:145], s[30:31], 0, v[136:137]
	s_addc_u32 s65, s31, 0
	s_add_i32 s63, s47, s38
	global_load_lds_dwordx4 v[144:145], off
	v_lshl_add_u64 v[144:145], s[64:65], 0, v[132:133]
	s_mov_b32 m0, s63
	s_nop 0
	global_load_lds_dwordx4 v[144:145], off
	v_lshl_add_u64 v[144:145], s[64:65], 0, v[136:137]
	s_add_i32 m0, s63, 0x2000
	s_nop 0
	global_load_lds_dwordx4 v[144:145], off
	v_lshl_add_u64 v[144:145], s[2:3], 0, v[130:131]
	s_mov_b32 m0, s39
	s_nop 0
	global_load_lds_dwordx4 v[144:145], off
	v_lshl_add_u64 v[144:145], s[2:3], 0, v[134:135]
	s_mov_b32 m0, s40
	s_nop 0
	global_load_lds_dwordx4 v[144:145], off
	s_waitcnt vmcnt(8)
	s_waitcnt lgkmcnt(0)
	s_barrier
	s_setprio 1
	s_waitcnt lgkmcnt(0)
	v_mfma_f32_16x16x32_bf16 v[62:65], v[152:155], v[186:189], 0
	v_mfma_f32_16x16x32_bf16 v[58:61], v[160:163], v[186:189], 0
	v_mfma_f32_16x16x32_bf16 v[50:53], v[152:155], v[194:197], 0
	v_mfma_f32_16x16x32_bf16 v[42:45], v[160:163], v[194:197], 0
	v_mfma_f32_16x16x32_bf16 v[34:37], v[152:155], v[202:205], 0
	v_mfma_f32_16x16x32_bf16 v[26:29], v[160:163], v[202:205], 0
	v_mfma_f32_16x16x32_bf16 v[18:21], v[152:155], v[210:213], 0
	v_mfma_f32_16x16x32_bf16 v[10:13], v[160:163], v[210:213], 0
	v_mfma_f32_16x16x32_bf16 v[62:65], v[156:159], v[190:193], v[62:65]
	v_mfma_f32_16x16x32_bf16 v[58:61], v[164:167], v[190:193], v[58:61]
	v_mfma_f32_16x16x32_bf16 v[50:53], v[156:159], v[198:201], v[50:53]
	v_mfma_f32_16x16x32_bf16 v[42:45], v[164:167], v[198:201], v[42:45]
	v_mfma_f32_16x16x32_bf16 v[34:37], v[156:159], v[206:209], v[34:37]
	v_mfma_f32_16x16x32_bf16 v[26:29], v[164:167], v[206:209], v[26:29]
	v_mfma_f32_16x16x32_bf16 v[18:21], v[156:159], v[214:217], v[18:21]
	v_mfma_f32_16x16x32_bf16 v[10:13], v[164:167], v[214:217], v[10:13]
	s_setprio 0
	s_setprio 1
	v_mfma_f32_16x16x32_bf16 v[54:57], v[168:171], v[186:189], 0
	v_mfma_f32_16x16x32_bf16 v[46:49], v[178:181], v[186:189], 0
	v_mfma_f32_16x16x32_bf16 v[38:41], v[168:171], v[194:197], 0
	v_mfma_f32_16x16x32_bf16 v[30:33], v[178:181], v[194:197], 0
	v_mfma_f32_16x16x32_bf16 v[22:25], v[168:171], v[202:205], 0
	v_mfma_f32_16x16x32_bf16 v[14:17], v[178:181], v[202:205], 0
	v_mfma_f32_16x16x32_bf16 v[6:9], v[168:171], v[210:213], 0
	v_mfma_f32_16x16x32_bf16 v[2:5], v[178:181], v[210:213], 0
	v_mfma_f32_16x16x32_bf16 v[54:57], v[172:175], v[190:193], v[54:57]
	v_mfma_f32_16x16x32_bf16 v[46:49], v[182:185], v[190:193], v[46:49]
	v_mfma_f32_16x16x32_bf16 v[38:41], v[172:175], v[198:201], v[38:41]
	v_mfma_f32_16x16x32_bf16 v[30:33], v[182:185], v[198:201], v[30:33]
	v_mfma_f32_16x16x32_bf16 v[22:25], v[172:175], v[206:209], v[22:25]
	v_mfma_f32_16x16x32_bf16 v[14:17], v[182:185], v[206:209], v[14:17]
	v_mfma_f32_16x16x32_bf16 v[6:9], v[172:175], v[214:217], v[6:9]
	v_mfma_f32_16x16x32_bf16 v[2:5], v[182:185], v[214:217], v[2:5]
	s_setprio 0
	s_barrier
	s_add_i32 s63, 0, 0x18000
	v_add_u32_e32 v144, s63, v146
	s_add_i32 s64, 0, 0x1c000
	ds_read_b128 v[152:155], v144
	ds_read_b128 v[156:159], v144 offset:1024
	ds_read_b128 v[160:163], v144 offset:2048
	ds_read_b128 v[164:167], v144 offset:3072
	v_add_u32_e32 v144, s64, v146
	ds_read_b128 v[168:171], v144
	ds_read_b128 v[172:175], v144 offset:1024
	ds_read_b128 v[178:181], v144 offset:2048
	ds_read_b128 v[182:185], v144 offset:3072
	s_add_u32 s2, s2, 0x4000
	s_addc_u32 s3, s3, 0
	s_mov_b32 m0, s41
	v_lshl_add_u64 v[144:145], s[2:3], 0, v[130:131]
	ds_read_b128 v[186:189], v150 offset:32768
	ds_read_b128 v[190:193], v150 offset:33792
	ds_read_b128 v[194:197], v150 offset:34816
	ds_read_b128 v[198:201], v150 offset:35840
	ds_read_b128 v[202:205], v150 offset:36864
	ds_read_b128 v[206:209], v150 offset:37888
	ds_read_b128 v[210:213], v150 offset:38912
	ds_read_b128 v[214:217], v150 offset:39936
	global_load_lds_dwordx4 v[144:145], off
	v_lshl_add_u64 v[144:145], s[2:3], 0, v[134:135]
	s_mov_b32 m0, s42
	s_nop 0
	global_load_lds_dwordx4 v[144:145], off
	s_waitcnt vmcnt(8)
	s_waitcnt lgkmcnt(0)
	s_barrier
	s_setprio 1
	s_waitcnt lgkmcnt(0)
	v_mfma_f32_16x16x32_bf16 v[126:129], v[152:155], v[186:189], v[126:129]
	v_mfma_f32_16x16x32_bf16 v[122:125], v[160:163], v[186:189], v[122:125]
	v_mfma_f32_16x16x32_bf16 v[114:117], v[152:155], v[194:197], v[114:117]
	v_mfma_f32_16x16x32_bf16 v[106:109], v[160:163], v[194:197], v[106:109]
	v_mfma_f32_16x16x32_bf16 v[98:101], v[152:155], v[202:205], v[98:101]
	v_mfma_f32_16x16x32_bf16 v[90:93], v[160:163], v[202:205], v[90:93]
	v_mfma_f32_16x16x32_bf16 v[82:85], v[152:155], v[210:213], v[82:85]
	v_mfma_f32_16x16x32_bf16 v[74:77], v[160:163], v[210:213], v[74:77]
	v_mfma_f32_16x16x32_bf16 v[126:129], v[156:159], v[190:193], v[126:129]
	v_mfma_f32_16x16x32_bf16 v[122:125], v[164:167], v[190:193], v[122:125]
	v_mfma_f32_16x16x32_bf16 v[114:117], v[156:159], v[198:201], v[114:117]
	v_mfma_f32_16x16x32_bf16 v[106:109], v[164:167], v[198:201], v[106:109]
	v_mfma_f32_16x16x32_bf16 v[98:101], v[156:159], v[206:209], v[98:101]
	v_mfma_f32_16x16x32_bf16 v[90:93], v[164:167], v[206:209], v[90:93]
	v_mfma_f32_16x16x32_bf16 v[82:85], v[156:159], v[214:217], v[82:85]
	v_mfma_f32_16x16x32_bf16 v[74:77], v[164:167], v[214:217], v[74:77]
	s_setprio 0
	s_setprio 1
	v_mfma_f32_16x16x32_bf16 v[118:121], v[168:171], v[186:189], v[118:121]
	v_mfma_f32_16x16x32_bf16 v[110:113], v[178:181], v[186:189], v[110:113]
	v_mfma_f32_16x16x32_bf16 v[102:105], v[168:171], v[194:197], v[102:105]
	v_mfma_f32_16x16x32_bf16 v[94:97], v[178:181], v[194:197], v[94:97]
	v_mfma_f32_16x16x32_bf16 v[86:89], v[168:171], v[202:205], v[86:89]
	v_mfma_f32_16x16x32_bf16 v[78:81], v[178:181], v[202:205], v[78:81]
	v_mfma_f32_16x16x32_bf16 v[70:73], v[168:171], v[210:213], v[70:73]
	v_mfma_f32_16x16x32_bf16 v[66:69], v[178:181], v[210:213], v[66:69]
	v_mfma_f32_16x16x32_bf16 v[118:121], v[172:175], v[190:193], v[118:121]
	v_mfma_f32_16x16x32_bf16 v[110:113], v[182:185], v[190:193], v[110:113]
	v_mfma_f32_16x16x32_bf16 v[102:105], v[172:175], v[198:201], v[102:105]
	v_mfma_f32_16x16x32_bf16 v[94:97], v[182:185], v[198:201], v[94:97]
	v_mfma_f32_16x16x32_bf16 v[86:89], v[172:175], v[206:209], v[86:89]
	v_mfma_f32_16x16x32_bf16 v[78:81], v[182:185], v[206:209], v[78:81]
	v_mfma_f32_16x16x32_bf16 v[70:73], v[172:175], v[214:217], v[70:73]
	v_mfma_f32_16x16x32_bf16 v[66:69], v[182:185], v[214:217], v[66:69]
	s_setprio 0
	s_barrier
	s_add_u32 s2, s30, 0x8000
	s_addc_u32 s3, s31, 0
	s_add_i32 s63, s63, s38
	v_lshl_add_u64 v[144:145], s[2:3], 0, v[132:133]
	s_mov_b32 m0, s63
	ds_read_b128 v[186:189], v150 offset:49152
	ds_read_b128 v[190:193], v150 offset:50176
	ds_read_b128 v[194:197], v150 offset:51200
	ds_read_b128 v[198:201], v150 offset:52224
	ds_read_b128 v[202:205], v150 offset:53248
	ds_read_b128 v[206:209], v150 offset:54272
	ds_read_b128 v[210:213], v150 offset:55296
	ds_read_b128 v[214:217], v150 offset:56320
	global_load_lds_dwordx4 v[144:145], off
	s_add_i32 m0, s63, 0x2000
	v_lshl_add_u64 v[144:145], s[2:3], 0, v[136:137]
	s_add_u32 s2, s30, 0xc000
	s_addc_u32 s3, s31, 0
	s_add_i32 s30, s64, s38
	global_load_lds_dwordx4 v[144:145], off
	v_lshl_add_u64 v[144:145], s[2:3], 0, v[132:133]
	s_mov_b32 m0, s30
	s_nop 0
	global_load_lds_dwordx4 v[144:145], off
	v_lshl_add_u64 v[144:145], s[2:3], 0, v[136:137]
	s_add_i32 m0, s30, 0x2000
	s_nop 0
	global_load_lds_dwordx4 v[144:145], off
	v_lshl_add_u64 v[144:145], s[28:29], 0, v[130:131]
	s_mov_b32 m0, s44
	s_nop 0
	global_load_lds_dwordx4 v[144:145], off
	v_lshl_add_u64 v[144:145], s[28:29], 0, v[134:135]
	s_mov_b32 m0, s45
	s_nop 0
	global_load_lds_dwordx4 v[144:145], off
	s_waitcnt vmcnt(8)
	s_waitcnt lgkmcnt(0)
	s_barrier
	s_setprio 1
	s_waitcnt lgkmcnt(0)
	v_mfma_f32_16x16x32_bf16 v[62:65], v[152:155], v[186:189], v[62:65]
	v_mfma_f32_16x16x32_bf16 v[58:61], v[160:163], v[186:189], v[58:61]
	v_mfma_f32_16x16x32_bf16 v[50:53], v[152:155], v[194:197], v[50:53]
	v_mfma_f32_16x16x32_bf16 v[42:45], v[160:163], v[194:197], v[42:45]
	v_mfma_f32_16x16x32_bf16 v[34:37], v[152:155], v[202:205], v[34:37]
	v_mfma_f32_16x16x32_bf16 v[26:29], v[160:163], v[202:205], v[26:29]
	v_mfma_f32_16x16x32_bf16 v[18:21], v[152:155], v[210:213], v[18:21]
	v_mfma_f32_16x16x32_bf16 v[10:13], v[160:163], v[210:213], v[10:13]
	v_mfma_f32_16x16x32_bf16 v[62:65], v[156:159], v[190:193], v[62:65]
	v_mfma_f32_16x16x32_bf16 v[58:61], v[164:167], v[190:193], v[58:61]
	v_mfma_f32_16x16x32_bf16 v[50:53], v[156:159], v[198:201], v[50:53]
	v_mfma_f32_16x16x32_bf16 v[42:45], v[164:167], v[198:201], v[42:45]
	v_mfma_f32_16x16x32_bf16 v[34:37], v[156:159], v[206:209], v[34:37]
	v_mfma_f32_16x16x32_bf16 v[26:29], v[164:167], v[206:209], v[26:29]
	v_mfma_f32_16x16x32_bf16 v[18:21], v[156:159], v[214:217], v[18:21]
	v_mfma_f32_16x16x32_bf16 v[10:13], v[164:167], v[214:217], v[10:13]
	s_setprio 0
	s_setprio 1
	v_mfma_f32_16x16x32_bf16 v[54:57], v[168:171], v[186:189], v[54:57]
	v_mfma_f32_16x16x32_bf16 v[46:49], v[178:181], v[186:189], v[46:49]
	v_mfma_f32_16x16x32_bf16 v[38:41], v[168:171], v[194:197], v[38:41]
	v_mfma_f32_16x16x32_bf16 v[30:33], v[178:181], v[194:197], v[30:33]
	v_mfma_f32_16x16x32_bf16 v[22:25], v[168:171], v[202:205], v[22:25]
	v_mfma_f32_16x16x32_bf16 v[14:17], v[178:181], v[202:205], v[14:17]
	v_mfma_f32_16x16x32_bf16 v[6:9], v[168:171], v[210:213], v[6:9]
	v_mfma_f32_16x16x32_bf16 v[2:5], v[178:181], v[210:213], v[2:5]
	v_mfma_f32_16x16x32_bf16 v[54:57], v[172:175], v[190:193], v[54:57]
	v_mfma_f32_16x16x32_bf16 v[46:49], v[182:185], v[190:193], v[46:49]
	v_mfma_f32_16x16x32_bf16 v[38:41], v[172:175], v[198:201], v[38:41]
	v_mfma_f32_16x16x32_bf16 v[30:33], v[182:185], v[198:201], v[30:33]
	v_mfma_f32_16x16x32_bf16 v[22:25], v[172:175], v[206:209], v[22:25]
	v_mfma_f32_16x16x32_bf16 v[14:17], v[182:185], v[206:209], v[14:17]
	v_mfma_f32_16x16x32_bf16 v[6:9], v[172:175], v[214:217], v[6:9]
	v_mfma_f32_16x16x32_bf16 v[2:5], v[182:185], v[214:217], v[2:5]
	s_setprio 0
	s_barrier
	s_add_i32 s62, s62, 2
	s_add_u32 s26, s26, 0x10000
	s_addc_u32 s27, s27, 0
	s_add_u32 s60, s60, 0x10000
	s_addc_u32 s61, s61, 0
	s_cmp_gt_u32 s62, 41
	s_cbranch_scc0 .LBB0_1444
	s_branch .Lpk1444_exit
	s_branch .LBB0_1444
	.p2align 6
